# GEMM k-loop: DMA pieces between MFMA groups, LDS xor-swizzle, k-blocked h2 for PEER-query GEMM; hand-written adaLN rows; sorted PEER gather ring
# speedup vs baseline: 1.0606x; 1.0236x over previous
; DEV int ltid() { int t = threadIdx.x; asm volatile("" : "+v"(t)); return t; }
; DEV void ph_adaln_row(const float* xin, const float* g, const float* mod, int sh_off, int sc_off, u16* hout, int row) {
;   const int lane = ltid() & 63, b = row >> 11;
;   const float* xr = xin + (size_t)row * 2048;
;   float4 v[8];
;   float ss = 0.f;
; #pragma unroll
;   for (int i = 0; i < 8; ++i) {
;     v[i] = *(const float4*)(xr + i * 256 + lane * 4);
;     ss += v[i].x * v[i].x + v[i].y * v[i].y + v[i].z * v[i].z + v[i].w * v[i].w;
;   }
;   ss = wave_sum(ss);
;   const float rstd = rsqrtf(ss * (1.f / 2048.f) + 1e-6f);
;   const float* mb = mod + (size_t)b * 12288;
; #pragma unroll
;   for (int i = 0; i < 8; ++i) {
;     int col = i * 256 + lane * 4;
;     float4 g4 = *(const float4*)(g + col);
;     float4 sc = *(const float4*)(mb + sc_off + col);
;     float4 sh = *(const float4*)(mb + sh_off + col);
; __global__ void __launch_bounds__(256, 2) fwd_megakernel(Params p) {
;     ...
;   for (int row = bid * 4 + wid; row < T_; row += nb * 4) ph_adaln_row(p.x, p.norm_mix_g, p.mod, 0, 2048, p.h, row);
.LBB0_189:
	s_or_b64 exec, exec, s[0:1]
	v_readlane_b32 s0, v254, 0
	s_lshl_b32 s2, s0, 2
	v_mov_b32_e32 v1, v0
	v_readlane_b32 s1, v254, 1
	s_mov_b32 s0, s2
	s_waitcnt lgkmcnt(0)
	s_barrier
	v_writelane_b32 v255, s0, 41
	v_ashrrev_i32_e32 v2, 6, v1
	v_add_u32_e32 v1, s2, v2
	v_writelane_b32 v255, s1, 42
	s_movk_i32 s0, 0x4000
	v_cmp_gt_i32_e32 vcc, s0, v1
	s_and_saveexec_b64 s[0:1], vcc
	v_readlane_b32 s8, v254, 25
	v_readlane_b32 s9, v254, 26
	v_readlane_b32 s16, v254, 33
	v_readlane_b32 s17, v254, 34
	v_readlane_b32 s10, v254, 27
	v_readlane_b32 s11, v254, 28
	v_readlane_b32 s12, v254, 29
	v_readlane_b32 s13, v254, 30
	v_readlane_b32 s14, v254, 31
	v_readlane_b32 s15, v254, 32
	v_readlane_b32 s18, v254, 35
	v_readlane_b32 s19, v254, 36
	v_readlane_b32 s20, v254, 37
	v_readlane_b32 s21, v254, 38
	v_readlane_b32 s22, v254, 39
	v_readlane_b32 s23, v254, 40
	s_cbranch_execz .LBB0_192
	v_and_b32_e32 v2, 63, v0
	v_lshrrev_b32_e32 v3, 6, v0
	v_lshlrev_b32_e32 v235, 4, v2
	v_lshlrev_b32_e32 v237, 3, v2
	v_readfirstlane_b32 s13, v3
	v_readlane_b32 s10, v254, 0
	v_add_u32_e32 v236, 0x1000, v235
	v_add_u32_e32 v238, 0x2000, v235
	v_add_u32_e32 v239, 0x3000, v235
	v_add_u32_e32 v240, 0x0, v235
	v_add_u32_e32 v241, 0x1000, v235
	v_mov_b32_e32 v233, 0x358637bd
	v_mov_b32_e32 v234, 0x800000
	s_lshl_b32 s10, s10, 2
	s_add_i32 s10, s10, s13
	s_lshl_b32 s11, s92, 2
	s_cmpk_lt_u32 s10, 0x4000
	s_cbranch_scc0 .Lad_end_p1
	v_readlane_b32 s2, v254, 33
	v_readlane_b32 s3, v254, 34
	s_nop 4
	global_load_dwordx4 v[194:197], v235, s[2:3]
	global_load_dwordx4 v[198:201], v235, s[2:3] offset:1024
	global_load_dwordx4 v[202:205], v235, s[2:3] offset:2048
	global_load_dwordx4 v[206:209], v235, s[2:3] offset:3072
	global_load_dwordx4 v[210:213], v236, s[2:3]
	global_load_dwordx4 v[214:217], v236, s[2:3] offset:1024
	global_load_dwordx4 v[218:221], v236, s[2:3] offset:2048
	global_load_dwordx4 v[222:225], v236, s[2:3] offset:3072
	v_readlane_b32 s2, v254, 25
	v_readlane_b32 s3, v254, 26
	s_lshl_b32 s13, s10, 13
	s_add_u32 s2, s2, s13
	s_addc_u32 s3, s3, 0
	s_lshr_b32 s13, s10, 11
	s_mul_i32 s13, s13, 0xc000
	s_add_u32 s4, s78, s13
	s_addc_u32 s5, s79, 0
	global_load_dwordx4 v[2:5], v235, s[2:3]
	global_load_dwordx4 v[6:9], v235, s[2:3] offset:1024
	global_load_dwordx4 v[10:13], v235, s[2:3] offset:2048
	global_load_dwordx4 v[14:17], v235, s[2:3] offset:3072
	global_load_dwordx4 v[18:21], v236, s[2:3]
	global_load_dwordx4 v[22:25], v236, s[2:3] offset:1024
	global_load_dwordx4 v[26:29], v236, s[2:3] offset:2048
	global_load_dwordx4 v[30:33], v236, s[2:3] offset:3072
	global_load_dwordx4 v[34:37], v238, s[4:5]
	global_load_dwordx4 v[38:41], v238, s[4:5] offset:1024
	global_load_dwordx4 v[42:45], v238, s[4:5] offset:2048
	global_load_dwordx4 v[46:49], v238, s[4:5] offset:3072
	global_load_dwordx4 v[50:53], v239, s[4:5]
	global_load_dwordx4 v[54:57], v239, s[4:5] offset:1024
	global_load_dwordx4 v[58:61], v239, s[4:5] offset:2048
	global_load_dwordx4 v[62:65], v239, s[4:5] offset:3072
	global_load_dwordx4 v[66:69], v240, s[4:5]
	global_load_dwordx4 v[70:73], v240, s[4:5] offset:1024
	global_load_dwordx4 v[74:77], v240, s[4:5] offset:2048
	global_load_dwordx4 v[78:81], v240, s[4:5] offset:3072
	global_load_dwordx4 v[82:85], v241, s[4:5]
	global_load_dwordx4 v[86:89], v241, s[4:5] offset:1024
	global_load_dwordx4 v[90:93], v241, s[4:5] offset:2048
	global_load_dwordx4 v[94:97], v241, s[4:5] offset:3072
.Lad_loop_p1:
	s_add_i32 s12, s10, s11
	s_cmpk_lt_u32 s12, 0x4000
	s_cbranch_scc0 .Lad_last_p1_0
	v_readlane_b32 s2, v254, 25
	v_readlane_b32 s3, v254, 26
	s_lshl_b32 s13, s12, 13
	s_add_u32 s2, s2, s13
	s_addc_u32 s3, s3, 0
	s_lshr_b32 s13, s12, 11
	s_mul_i32 s13, s13, 0xc000
	s_add_u32 s4, s78, s13
	s_addc_u32 s5, s79, 0
	global_load_dwordx4 v[98:101], v235, s[2:3]
	global_load_dwordx4 v[102:105], v235, s[2:3] offset:1024
	global_load_dwordx4 v[106:109], v235, s[2:3] offset:2048
	global_load_dwordx4 v[110:113], v235, s[2:3] offset:3072
	global_load_dwordx4 v[114:117], v236, s[2:3]
	global_load_dwordx4 v[118:121], v236, s[2:3] offset:1024
	global_load_dwordx4 v[122:125], v236, s[2:3] offset:2048
	global_load_dwordx4 v[126:129], v236, s[2:3] offset:3072
	global_load_dwordx4 v[130:133], v238, s[4:5]
	global_load_dwordx4 v[134:137], v238, s[4:5] offset:1024
	global_load_dwordx4 v[138:141], v238, s[4:5] offset:2048
	global_load_dwordx4 v[142:145], v238, s[4:5] offset:3072
	global_load_dwordx4 v[146:149], v239, s[4:5]
	global_load_dwordx4 v[150:153], v239, s[4:5] offset:1024
	global_load_dwordx4 v[154:157], v239, s[4:5] offset:2048
	global_load_dwordx4 v[158:161], v239, s[4:5] offset:3072
	global_load_dwordx4 v[162:165], v240, s[4:5]
	global_load_dwordx4 v[166:169], v240, s[4:5] offset:1024
	global_load_dwordx4 v[170:173], v240, s[4:5] offset:2048
	global_load_dwordx4 v[174:177], v240, s[4:5] offset:3072
	global_load_dwordx4 v[178:181], v241, s[4:5]
	global_load_dwordx4 v[182:185], v241, s[4:5] offset:1024
	global_load_dwordx4 v[186:189], v241, s[4:5] offset:2048
	global_load_dwordx4 v[190:193], v241, s[4:5] offset:3072
	s_waitcnt vmcnt(24)
; DEV unsigned pack2(float a, float b) { float2v v = {a, b}; return __builtin_bit_cast(unsigned, __builtin_convertvector(v, bf16x2v)); }
; DEV void ph_adaln_row(const float* xin, const float* g, const float* mod, int sh_off, int sc_off, u16* hout, int row) {
;     ...
;     ss += v[i].x * v[i].x + v[i].y * v[i].y + v[i].z * v[i].z + v[i].w * v[i].w;
;   }
;   ss = wave_sum(ss);
;   const float rstd = rsqrtf(ss * (1.f / 2048.f) + 1e-6f);
;   const float* mb = mod + (size_t)b * 12288;
; #pragma unroll
;   for (int i = 0; i < 8; ++i) {
;     int col = i * 256 + lane * 4;
;     float4 g4 = *(const float4*)(g + col);
;     float4 sc = *(const float4*)(mb + sc_off + col);
;     float4 sh = *(const float4*)(mb + sh_off + col);
;     float y0 = v[i].x * rstd * g4.x * (1.f + sc.x) + sh.x;
;     float y1 = v[i].y * rstd * g4.y * (1.f + sc.y) + sh.y;
;     float y2 = v[i].z * rstd * g4.z * (1.f + sc.z) + sh.z;
;     float y3 = v[i].w * rstd * g4.w * (1.f + sc.w) + sh.w;
;     u32x2 pk; pk[0] = pack2(y0, y1); pk[1] = pack2(y2, y3);
;     *(u32x2*)(hout + (size_t)row * 2048 + col) = pk;
;   }
	v_mul_f32_e32 v226, v2, v2
	v_mul_f32_e32 v227, v3, v3
	v_mul_f32_e32 v228, v4, v4
	v_mul_f32_e32 v229, v5, v5
	v_fmac_f32_e32 v226, v6, v6
	v_fmac_f32_e32 v227, v7, v7
	v_fmac_f32_e32 v228, v8, v8
	v_fmac_f32_e32 v229, v9, v9
	v_fmac_f32_e32 v226, v10, v10
	v_fmac_f32_e32 v227, v11, v11
	v_fmac_f32_e32 v228, v12, v12
	v_fmac_f32_e32 v229, v13, v13
	v_fmac_f32_e32 v226, v14, v14
	v_fmac_f32_e32 v227, v15, v15
	v_fmac_f32_e32 v228, v16, v16
	v_fmac_f32_e32 v229, v17, v17
	v_fmac_f32_e32 v226, v18, v18
	v_fmac_f32_e32 v227, v19, v19
	v_fmac_f32_e32 v228, v20, v20
	v_fmac_f32_e32 v229, v21, v21
	v_fmac_f32_e32 v226, v22, v22
	v_fmac_f32_e32 v227, v23, v23
	v_fmac_f32_e32 v228, v24, v24
	v_fmac_f32_e32 v229, v25, v25
	v_fmac_f32_e32 v226, v26, v26
	v_fmac_f32_e32 v227, v27, v27
	v_fmac_f32_e32 v228, v28, v28
	v_fmac_f32_e32 v229, v29, v29
	v_fmac_f32_e32 v226, v30, v30
	v_fmac_f32_e32 v227, v31, v31
	v_fmac_f32_e32 v228, v32, v32
	v_fmac_f32_e32 v229, v33, v33
	v_add_f32_e32 v226, v227, v226
	v_add_f32_e32 v228, v229, v228
	v_add_f32_e32 v226, v228, v226
	s_nop 1
	v_add_f32_dpp v226, v226, v226 quad_perm:[1,0,3,2] row_mask:0xf bank_mask:0xf bound_ctrl:1
	s_nop 1
	v_add_f32_dpp v226, v226, v226 quad_perm:[2,3,0,1] row_mask:0xf bank_mask:0xf bound_ctrl:1
	s_nop 1
	v_add_f32_dpp v226, v226, v226 row_half_mirror row_mask:0xf bank_mask:0xf bound_ctrl:1
	s_nop 1
	v_add_f32_dpp v226, v226, v226 row_mirror row_mask:0xf bank_mask:0xf bound_ctrl:1
	s_nop 1
	v_add_f32_dpp v226, v226, v226 row_bcast:15 row_mask:0xa bank_mask:0xf
	s_nop 1
	v_add_f32_dpp v226, v226, v226 row_bcast:31 row_mask:0xc bank_mask:0xf
	s_nop 0
	v_readlane_b32 s12, v226, 63
	s_nop 1
	v_mov_b32_e32 v230, s12
	v_fmamk_f32 v230, v230, 0x3a000000, v233
	v_mul_f32_e32 v231, 0x4b800000, v230
	v_cmp_lt_f32_e32 vcc, v230, v234
	s_nop 1
	v_cndmask_b32_e32 v230, v230, v231, vcc
	v_rsq_f32_e32 v230, v230
	s_nop 0
	v_mul_f32_e32 v231, 0x45800000, v230
	v_cndmask_b32_e32 v232, v230, v231, vcc
	v_mul_f32_e32 v2, v2, v232
	v_mul_f32_e32 v2, v194, v2
	v_add_f32_e32 v34, 1.0, v34
	v_fma_f32 v2, v34, v2, v66
	v_mul_f32_e32 v3, v3, v232
	v_mul_f32_e32 v3, v195, v3
	v_add_f32_e32 v35, 1.0, v35
	v_fma_f32 v3, v35, v3, v67
	v_mul_f32_e32 v4, v4, v232
	v_mul_f32_e32 v4, v196, v4
	v_add_f32_e32 v36, 1.0, v36
	v_fma_f32 v4, v36, v4, v68
	v_mul_f32_e32 v5, v5, v232
	v_mul_f32_e32 v5, v197, v5
	v_add_f32_e32 v37, 1.0, v37
	v_fma_f32 v5, v37, v5, v69
	v_mul_f32_e32 v6, v6, v232
	v_mul_f32_e32 v6, v198, v6
	v_add_f32_e32 v38, 1.0, v38
	v_fma_f32 v6, v38, v6, v70
	v_mul_f32_e32 v7, v7, v232
	v_mul_f32_e32 v7, v199, v7
	v_add_f32_e32 v39, 1.0, v39
	v_fma_f32 v7, v39, v7, v71
	v_mul_f32_e32 v8, v8, v232
	v_mul_f32_e32 v8, v200, v8
	v_add_f32_e32 v40, 1.0, v40
	v_fma_f32 v8, v40, v8, v72
	v_mul_f32_e32 v9, v9, v232
	v_mul_f32_e32 v9, v201, v9
	v_add_f32_e32 v41, 1.0, v41
	v_fma_f32 v9, v41, v9, v73
	v_mul_f32_e32 v10, v10, v232
	v_mul_f32_e32 v10, v202, v10
	v_add_f32_e32 v42, 1.0, v42
	v_fma_f32 v10, v42, v10, v74
	v_mul_f32_e32 v11, v11, v232
	v_mul_f32_e32 v11, v203, v11
	v_add_f32_e32 v43, 1.0, v43
	v_fma_f32 v11, v43, v11, v75
	v_mul_f32_e32 v12, v12, v232
	v_mul_f32_e32 v12, v204, v12
	v_add_f32_e32 v44, 1.0, v44
	v_fma_f32 v12, v44, v12, v76
	v_mul_f32_e32 v13, v13, v232
	v_mul_f32_e32 v13, v205, v13
	v_add_f32_e32 v45, 1.0, v45
	v_fma_f32 v13, v45, v13, v77
	v_mul_f32_e32 v14, v14, v232
	v_mul_f32_e32 v14, v206, v14
	v_add_f32_e32 v46, 1.0, v46
	v_fma_f32 v14, v46, v14, v78
	v_mul_f32_e32 v15, v15, v232
	v_mul_f32_e32 v15, v207, v15
	v_add_f32_e32 v47, 1.0, v47
	v_fma_f32 v15, v47, v15, v79
	v_mul_f32_e32 v16, v16, v232
	v_mul_f32_e32 v16, v208, v16
	v_add_f32_e32 v48, 1.0, v48
	v_fma_f32 v16, v48, v16, v80
	v_mul_f32_e32 v17, v17, v232
	v_mul_f32_e32 v17, v209, v17
	v_add_f32_e32 v49, 1.0, v49
	v_fma_f32 v17, v49, v17, v81
	v_mul_f32_e32 v18, v18, v232
	v_mul_f32_e32 v18, v210, v18
	v_add_f32_e32 v50, 1.0, v50
	v_fma_f32 v18, v50, v18, v82
	v_mul_f32_e32 v19, v19, v232
	v_mul_f32_e32 v19, v211, v19
	v_add_f32_e32 v51, 1.0, v51
	v_fma_f32 v19, v51, v19, v83
	v_mul_f32_e32 v20, v20, v232
	v_mul_f32_e32 v20, v212, v20
	v_add_f32_e32 v52, 1.0, v52
	v_fma_f32 v20, v52, v20, v84
	v_mul_f32_e32 v21, v21, v232
	v_mul_f32_e32 v21, v213, v21
	v_add_f32_e32 v53, 1.0, v53
	v_fma_f32 v21, v53, v21, v85
	v_mul_f32_e32 v22, v22, v232
	v_mul_f32_e32 v22, v214, v22
	v_add_f32_e32 v54, 1.0, v54
	v_fma_f32 v22, v54, v22, v86
	v_mul_f32_e32 v23, v23, v232
	v_mul_f32_e32 v23, v215, v23
	v_add_f32_e32 v55, 1.0, v55
	v_fma_f32 v23, v55, v23, v87
	v_mul_f32_e32 v24, v24, v232
	v_mul_f32_e32 v24, v216, v24
	v_add_f32_e32 v56, 1.0, v56
	v_fma_f32 v24, v56, v24, v88
	v_mul_f32_e32 v25, v25, v232
	v_mul_f32_e32 v25, v217, v25
	v_add_f32_e32 v57, 1.0, v57
	v_fma_f32 v25, v57, v25, v89
	v_mul_f32_e32 v26, v26, v232
	v_mul_f32_e32 v26, v218, v26
	v_add_f32_e32 v58, 1.0, v58
	v_fma_f32 v26, v58, v26, v90
	v_mul_f32_e32 v27, v27, v232
	v_mul_f32_e32 v27, v219, v27
	v_add_f32_e32 v59, 1.0, v59
	v_fma_f32 v27, v59, v27, v91
	v_mul_f32_e32 v28, v28, v232
	v_mul_f32_e32 v28, v220, v28
	v_add_f32_e32 v60, 1.0, v60
	v_fma_f32 v28, v60, v28, v92
	v_mul_f32_e32 v29, v29, v232
	v_mul_f32_e32 v29, v221, v29
	v_add_f32_e32 v61, 1.0, v61
	v_fma_f32 v29, v61, v29, v93
	v_mul_f32_e32 v30, v30, v232
	v_mul_f32_e32 v30, v222, v30
	v_add_f32_e32 v62, 1.0, v62
	v_fma_f32 v30, v62, v30, v94
	v_mul_f32_e32 v31, v31, v232
	v_mul_f32_e32 v31, v223, v31
	v_add_f32_e32 v63, 1.0, v63
	v_fma_f32 v31, v63, v31, v95
	v_mul_f32_e32 v32, v32, v232
	v_mul_f32_e32 v32, v224, v32
	v_add_f32_e32 v64, 1.0, v64
	v_fma_f32 v32, v64, v32, v96
	v_mul_f32_e32 v33, v33, v232
	v_mul_f32_e32 v33, v225, v33
	v_add_f32_e32 v65, 1.0, v65
	v_fma_f32 v33, v65, v33, v97
	v_cvt_pk_bf16_f32 v2, v2, v3
	v_cvt_pk_bf16_f32 v3, v4, v5
	v_cvt_pk_bf16_f32 v4, v6, v7
	v_cvt_pk_bf16_f32 v5, v8, v9
	v_cvt_pk_bf16_f32 v6, v10, v11
	v_cvt_pk_bf16_f32 v7, v12, v13
	v_cvt_pk_bf16_f32 v8, v14, v15
	v_cvt_pk_bf16_f32 v9, v16, v17
	v_cvt_pk_bf16_f32 v10, v18, v19
	v_cvt_pk_bf16_f32 v11, v20, v21
	v_cvt_pk_bf16_f32 v12, v22, v23
	v_cvt_pk_bf16_f32 v13, v24, v25
	v_cvt_pk_bf16_f32 v14, v26, v27
	v_cvt_pk_bf16_f32 v15, v28, v29
	v_cvt_pk_bf16_f32 v16, v30, v31
	v_cvt_pk_bf16_f32 v17, v32, v33
	s_lshl_b32 s13, s10, 12
	s_add_u32 s8, s80, s13
	s_addc_u32 s9, s81, 0
	global_store_dwordx2 v237, v[2:3], s[8:9]
	global_store_dwordx2 v237, v[4:5], s[8:9] offset:512
	global_store_dwordx2 v237, v[6:7], s[8:9] offset:1024
	global_store_dwordx2 v237, v[8:9], s[8:9] offset:1536
	global_store_dwordx2 v237, v[10:11], s[8:9] offset:2048
	global_store_dwordx2 v237, v[12:13], s[8:9] offset:2560
	global_store_dwordx2 v237, v[14:15], s[8:9] offset:3072
	global_store_dwordx2 v237, v[16:17], s[8:9] offset:3584
	s_add_i32 s10, s10, s11
	s_add_i32 s12, s10, s11
	s_cmpk_lt_u32 s12, 0x4000
	s_cbranch_scc0 .Lad_last_p1_1
; DEV void ph_adaln_row(const float* xin, const float* g, const float* mod, int sh_off, int sc_off, u16* hout, int row) {
;     ...
; #pragma unroll
;   for (int i = 0; i < 8; ++i) {
;     v[i] = *(const float4*)(xr + i * 256 + lane * 4);
;     ss += v[i].x * v[i].x + v[i].y * v[i].y + v[i].z * v[i].z + v[i].w * v[i].w;
;   }
;   ss = wave_sum(ss);
;   const float rstd = rsqrtf(ss * (1.f / 2048.f) + 1e-6f);
;   const float* mb = mod + (size_t)b * 12288;
; #pragma unroll
;   for (int i = 0; i < 8; ++i) {
;     int col = i * 256 + lane * 4;
;     float4 g4 = *(const float4*)(g + col);
;     float4 sc = *(const float4*)(mb + sc_off + col);
;     float4 sh = *(const float4*)(mb + sh_off + col);
;     float y0 = v[i].x * rstd * g4.x * (1.f + sc.x) + sh.x;
;     float y1 = v[i].y * rstd * g4.y * (1.f + sc.y) + sh.y;
;     float y2 = v[i].z * rstd * g4.z * (1.f + sc.z) + sh.z;
;     float y3 = v[i].w * rstd * g4.w * (1.f + sc.w) + sh.w;
	v_readlane_b32 s2, v254, 25
	v_readlane_b32 s3, v254, 26
	s_lshl_b32 s13, s12, 13
	s_add_u32 s2, s2, s13
	s_addc_u32 s3, s3, 0
	s_lshr_b32 s13, s12, 11
	s_mul_i32 s13, s13, 0xc000
	s_add_u32 s4, s78, s13
	s_addc_u32 s5, s79, 0
	global_load_dwordx4 v[2:5], v235, s[2:3]
	global_load_dwordx4 v[6:9], v235, s[2:3] offset:1024
	global_load_dwordx4 v[10:13], v235, s[2:3] offset:2048
	global_load_dwordx4 v[14:17], v235, s[2:3] offset:3072
	global_load_dwordx4 v[18:21], v236, s[2:3]
	global_load_dwordx4 v[22:25], v236, s[2:3] offset:1024
	global_load_dwordx4 v[26:29], v236, s[2:3] offset:2048
	global_load_dwordx4 v[30:33], v236, s[2:3] offset:3072
	global_load_dwordx4 v[34:37], v238, s[4:5]
	global_load_dwordx4 v[38:41], v238, s[4:5] offset:1024
	global_load_dwordx4 v[42:45], v238, s[4:5] offset:2048
	global_load_dwordx4 v[46:49], v238, s[4:5] offset:3072
	global_load_dwordx4 v[50:53], v239, s[4:5]
	global_load_dwordx4 v[54:57], v239, s[4:5] offset:1024
	global_load_dwordx4 v[58:61], v239, s[4:5] offset:2048
	global_load_dwordx4 v[62:65], v239, s[4:5] offset:3072
	global_load_dwordx4 v[66:69], v240, s[4:5]
	global_load_dwordx4 v[70:73], v240, s[4:5] offset:1024
	global_load_dwordx4 v[74:77], v240, s[4:5] offset:2048
	global_load_dwordx4 v[78:81], v240, s[4:5] offset:3072
	global_load_dwordx4 v[82:85], v241, s[4:5]
	global_load_dwordx4 v[86:89], v241, s[4:5] offset:1024
	global_load_dwordx4 v[90:93], v241, s[4:5] offset:2048
	global_load_dwordx4 v[94:97], v241, s[4:5] offset:3072
	s_waitcnt vmcnt(24)
	v_mul_f32_e32 v226, v98, v98
	v_mul_f32_e32 v227, v99, v99
	v_mul_f32_e32 v228, v100, v100
	v_mul_f32_e32 v229, v101, v101
	v_fmac_f32_e32 v226, v102, v102
	v_fmac_f32_e32 v227, v103, v103
	v_fmac_f32_e32 v228, v104, v104
	v_fmac_f32_e32 v229, v105, v105
	v_fmac_f32_e32 v226, v106, v106
	v_fmac_f32_e32 v227, v107, v107
	v_fmac_f32_e32 v228, v108, v108
	v_fmac_f32_e32 v229, v109, v109
	v_fmac_f32_e32 v226, v110, v110
	v_fmac_f32_e32 v227, v111, v111
	v_fmac_f32_e32 v228, v112, v112
	v_fmac_f32_e32 v229, v113, v113
	v_fmac_f32_e32 v226, v114, v114
	v_fmac_f32_e32 v227, v115, v115
	v_fmac_f32_e32 v228, v116, v116
	v_fmac_f32_e32 v229, v117, v117
	v_fmac_f32_e32 v226, v118, v118
	v_fmac_f32_e32 v227, v119, v119
	v_fmac_f32_e32 v228, v120, v120
	v_fmac_f32_e32 v229, v121, v121
	v_fmac_f32_e32 v226, v122, v122
	v_fmac_f32_e32 v227, v123, v123
	v_fmac_f32_e32 v228, v124, v124
	v_fmac_f32_e32 v229, v125, v125
	v_fmac_f32_e32 v226, v126, v126
	v_fmac_f32_e32 v227, v127, v127
	v_fmac_f32_e32 v228, v128, v128
	v_fmac_f32_e32 v229, v129, v129
	v_add_f32_e32 v226, v227, v226
	v_add_f32_e32 v228, v229, v228
	v_add_f32_e32 v226, v228, v226
	s_nop 1
	v_add_f32_dpp v226, v226, v226 quad_perm:[1,0,3,2] row_mask:0xf bank_mask:0xf bound_ctrl:1
	s_nop 1
	v_add_f32_dpp v226, v226, v226 quad_perm:[2,3,0,1] row_mask:0xf bank_mask:0xf bound_ctrl:1
	s_nop 1
	v_add_f32_dpp v226, v226, v226 row_half_mirror row_mask:0xf bank_mask:0xf bound_ctrl:1
	s_nop 1
	v_add_f32_dpp v226, v226, v226 row_mirror row_mask:0xf bank_mask:0xf bound_ctrl:1
	s_nop 1
	v_add_f32_dpp v226, v226, v226 row_bcast:15 row_mask:0xa bank_mask:0xf
	s_nop 1
	v_add_f32_dpp v226, v226, v226 row_bcast:31 row_mask:0xc bank_mask:0xf
	s_nop 0
	v_readlane_b32 s12, v226, 63
	s_nop 1
	v_mov_b32_e32 v230, s12
	v_fmamk_f32 v230, v230, 0x3a000000, v233
	v_mul_f32_e32 v231, 0x4b800000, v230
	v_cmp_lt_f32_e32 vcc, v230, v234
	s_nop 1
	v_cndmask_b32_e32 v230, v230, v231, vcc
	v_rsq_f32_e32 v230, v230
	s_nop 0
	v_mul_f32_e32 v231, 0x45800000, v230
	v_cndmask_b32_e32 v232, v230, v231, vcc
	v_mul_f32_e32 v98, v98, v232
	v_mul_f32_e32 v98, v194, v98
	v_add_f32_e32 v130, 1.0, v130
	v_fma_f32 v98, v130, v98, v162
	v_mul_f32_e32 v99, v99, v232
	v_mul_f32_e32 v99, v195, v99
	v_add_f32_e32 v131, 1.0, v131
	v_fma_f32 v99, v131, v99, v163
	v_mul_f32_e32 v100, v100, v232
	v_mul_f32_e32 v100, v196, v100
	v_add_f32_e32 v132, 1.0, v132
	v_fma_f32 v100, v132, v100, v164
	v_mul_f32_e32 v101, v101, v232
	v_mul_f32_e32 v101, v197, v101
	v_add_f32_e32 v133, 1.0, v133
	v_fma_f32 v101, v133, v101, v165
	v_mul_f32_e32 v102, v102, v232
	v_mul_f32_e32 v102, v198, v102
	v_add_f32_e32 v134, 1.0, v134
	v_fma_f32 v102, v134, v102, v166
	v_mul_f32_e32 v103, v103, v232
	v_mul_f32_e32 v103, v199, v103
	v_add_f32_e32 v135, 1.0, v135
	v_fma_f32 v103, v135, v103, v167
	v_mul_f32_e32 v104, v104, v232
	v_mul_f32_e32 v104, v200, v104
	v_add_f32_e32 v136, 1.0, v136
	v_fma_f32 v104, v136, v104, v168
	v_mul_f32_e32 v105, v105, v232
	v_mul_f32_e32 v105, v201, v105
	v_add_f32_e32 v137, 1.0, v137
	v_fma_f32 v105, v137, v105, v169
	v_mul_f32_e32 v106, v106, v232
	v_mul_f32_e32 v106, v202, v106
	v_add_f32_e32 v138, 1.0, v138
	v_fma_f32 v106, v138, v106, v170
	v_mul_f32_e32 v107, v107, v232
	v_mul_f32_e32 v107, v203, v107
	v_add_f32_e32 v139, 1.0, v139
	v_fma_f32 v107, v139, v107, v171
	v_mul_f32_e32 v108, v108, v232
	v_mul_f32_e32 v108, v204, v108
	v_add_f32_e32 v140, 1.0, v140
	v_fma_f32 v108, v140, v108, v172
	v_mul_f32_e32 v109, v109, v232
	v_mul_f32_e32 v109, v205, v109
	v_add_f32_e32 v141, 1.0, v141
	v_fma_f32 v109, v141, v109, v173
	v_mul_f32_e32 v110, v110, v232
	v_mul_f32_e32 v110, v206, v110
	v_add_f32_e32 v142, 1.0, v142
	v_fma_f32 v110, v142, v110, v174
	v_mul_f32_e32 v111, v111, v232
	v_mul_f32_e32 v111, v207, v111
	v_add_f32_e32 v143, 1.0, v143
	v_fma_f32 v111, v143, v111, v175
	v_mul_f32_e32 v112, v112, v232
	v_mul_f32_e32 v112, v208, v112
	v_add_f32_e32 v144, 1.0, v144
	v_fma_f32 v112, v144, v112, v176
	v_mul_f32_e32 v113, v113, v232
	v_mul_f32_e32 v113, v209, v113
	v_add_f32_e32 v145, 1.0, v145
	v_fma_f32 v113, v145, v113, v177
	v_mul_f32_e32 v114, v114, v232
; DEV unsigned pack2(float a, float b) { float2v v = {a, b}; return __builtin_bit_cast(unsigned, __builtin_convertvector(v, bf16x2v)); }
; DEV void ph_adaln_row(const float* xin, const float* g, const float* mod, int sh_off, int sc_off, u16* hout, int row) {
;     ...
;     float y0 = v[i].x * rstd * g4.x * (1.f + sc.x) + sh.x;
;     float y1 = v[i].y * rstd * g4.y * (1.f + sc.y) + sh.y;
;     float y2 = v[i].z * rstd * g4.z * (1.f + sc.z) + sh.z;
;     float y3 = v[i].w * rstd * g4.w * (1.f + sc.w) + sh.w;
;     u32x2 pk; pk[0] = pack2(y0, y1); pk[1] = pack2(y2, y3);
;     *(u32x2*)(hout + (size_t)row * 2048 + col) = pk;
;   }
	v_mul_f32_e32 v114, v210, v114
	v_add_f32_e32 v146, 1.0, v146
	v_fma_f32 v114, v146, v114, v178
	v_mul_f32_e32 v115, v115, v232
	v_mul_f32_e32 v115, v211, v115
	v_add_f32_e32 v147, 1.0, v147
	v_fma_f32 v115, v147, v115, v179
	v_mul_f32_e32 v116, v116, v232
	v_mul_f32_e32 v116, v212, v116
	v_add_f32_e32 v148, 1.0, v148
	v_fma_f32 v116, v148, v116, v180
	v_mul_f32_e32 v117, v117, v232
	v_mul_f32_e32 v117, v213, v117
	v_add_f32_e32 v149, 1.0, v149
	v_fma_f32 v117, v149, v117, v181
	v_mul_f32_e32 v118, v118, v232
	v_mul_f32_e32 v118, v214, v118
	v_add_f32_e32 v150, 1.0, v150
	v_fma_f32 v118, v150, v118, v182
	v_mul_f32_e32 v119, v119, v232
	v_mul_f32_e32 v119, v215, v119
	v_add_f32_e32 v151, 1.0, v151
	v_fma_f32 v119, v151, v119, v183
	v_mul_f32_e32 v120, v120, v232
	v_mul_f32_e32 v120, v216, v120
	v_add_f32_e32 v152, 1.0, v152
	v_fma_f32 v120, v152, v120, v184
	v_mul_f32_e32 v121, v121, v232
	v_mul_f32_e32 v121, v217, v121
	v_add_f32_e32 v153, 1.0, v153
	v_fma_f32 v121, v153, v121, v185
	v_mul_f32_e32 v122, v122, v232
	v_mul_f32_e32 v122, v218, v122
	v_add_f32_e32 v154, 1.0, v154
	v_fma_f32 v122, v154, v122, v186
	v_mul_f32_e32 v123, v123, v232
	v_mul_f32_e32 v123, v219, v123
	v_add_f32_e32 v155, 1.0, v155
	v_fma_f32 v123, v155, v123, v187
	v_mul_f32_e32 v124, v124, v232
	v_mul_f32_e32 v124, v220, v124
	v_add_f32_e32 v156, 1.0, v156
	v_fma_f32 v124, v156, v124, v188
	v_mul_f32_e32 v125, v125, v232
	v_mul_f32_e32 v125, v221, v125
	v_add_f32_e32 v157, 1.0, v157
	v_fma_f32 v125, v157, v125, v189
	v_mul_f32_e32 v126, v126, v232
	v_mul_f32_e32 v126, v222, v126
	v_add_f32_e32 v158, 1.0, v158
	v_fma_f32 v126, v158, v126, v190
	v_mul_f32_e32 v127, v127, v232
	v_mul_f32_e32 v127, v223, v127
	v_add_f32_e32 v159, 1.0, v159
	v_fma_f32 v127, v159, v127, v191
	v_mul_f32_e32 v128, v128, v232
	v_mul_f32_e32 v128, v224, v128
	v_add_f32_e32 v160, 1.0, v160
	v_fma_f32 v128, v160, v128, v192
	v_mul_f32_e32 v129, v129, v232
	v_mul_f32_e32 v129, v225, v129
	v_add_f32_e32 v161, 1.0, v161
	v_fma_f32 v129, v161, v129, v193
	v_cvt_pk_bf16_f32 v98, v98, v99
	v_cvt_pk_bf16_f32 v99, v100, v101
	v_cvt_pk_bf16_f32 v100, v102, v103
	v_cvt_pk_bf16_f32 v101, v104, v105
	v_cvt_pk_bf16_f32 v102, v106, v107
	v_cvt_pk_bf16_f32 v103, v108, v109
	v_cvt_pk_bf16_f32 v104, v110, v111
	v_cvt_pk_bf16_f32 v105, v112, v113
	v_cvt_pk_bf16_f32 v106, v114, v115
	v_cvt_pk_bf16_f32 v107, v116, v117
	v_cvt_pk_bf16_f32 v108, v118, v119
	v_cvt_pk_bf16_f32 v109, v120, v121
	v_cvt_pk_bf16_f32 v110, v122, v123
	v_cvt_pk_bf16_f32 v111, v124, v125
	v_cvt_pk_bf16_f32 v112, v126, v127
	v_cvt_pk_bf16_f32 v113, v128, v129
	s_lshl_b32 s13, s10, 12
	s_add_u32 s8, s80, s13
	s_addc_u32 s9, s81, 0
	global_store_dwordx2 v237, v[98:99], s[8:9]
	global_store_dwordx2 v237, v[100:101], s[8:9] offset:512
	global_store_dwordx2 v237, v[102:103], s[8:9] offset:1024
	global_store_dwordx2 v237, v[104:105], s[8:9] offset:1536
	global_store_dwordx2 v237, v[106:107], s[8:9] offset:2048
	global_store_dwordx2 v237, v[108:109], s[8:9] offset:2560
	global_store_dwordx2 v237, v[110:111], s[8:9] offset:3072
	global_store_dwordx2 v237, v[112:113], s[8:9] offset:3584
	s_add_i32 s10, s10, s11
	s_branch .Lad_loop_p1
.Lad_last_p1_0:
	s_waitcnt vmcnt(0)
	v_mul_f32_e32 v226, v2, v2
	v_mul_f32_e32 v227, v3, v3
	v_mul_f32_e32 v228, v4, v4
	v_mul_f32_e32 v229, v5, v5
	v_fmac_f32_e32 v226, v6, v6
	v_fmac_f32_e32 v227, v7, v7
	v_fmac_f32_e32 v228, v8, v8
	v_fmac_f32_e32 v229, v9, v9
	v_fmac_f32_e32 v226, v10, v10
	v_fmac_f32_e32 v227, v11, v11
	v_fmac_f32_e32 v228, v12, v12
	v_fmac_f32_e32 v229, v13, v13
	v_fmac_f32_e32 v226, v14, v14
	v_fmac_f32_e32 v227, v15, v15
	v_fmac_f32_e32 v228, v16, v16
	v_fmac_f32_e32 v229, v17, v17
	v_fmac_f32_e32 v226, v18, v18
	v_fmac_f32_e32 v227, v19, v19
	v_fmac_f32_e32 v228, v20, v20
	v_fmac_f32_e32 v229, v21, v21
	v_fmac_f32_e32 v226, v22, v22
	v_fmac_f32_e32 v227, v23, v23
	v_fmac_f32_e32 v228, v24, v24
	v_fmac_f32_e32 v229, v25, v25
	v_fmac_f32_e32 v226, v26, v26
	v_fmac_f32_e32 v227, v27, v27
	v_fmac_f32_e32 v228, v28, v28
	v_fmac_f32_e32 v229, v29, v29
	v_fmac_f32_e32 v226, v30, v30
	v_fmac_f32_e32 v227, v31, v31
	v_fmac_f32_e32 v228, v32, v32
	v_fmac_f32_e32 v229, v33, v33
	v_add_f32_e32 v226, v227, v226
	v_add_f32_e32 v228, v229, v228
	v_add_f32_e32 v226, v228, v226
	s_nop 1
	v_add_f32_dpp v226, v226, v226 quad_perm:[1,0,3,2] row_mask:0xf bank_mask:0xf bound_ctrl:1
	s_nop 1
	v_add_f32_dpp v226, v226, v226 quad_perm:[2,3,0,1] row_mask:0xf bank_mask:0xf bound_ctrl:1
	s_nop 1
	v_add_f32_dpp v226, v226, v226 row_half_mirror row_mask:0xf bank_mask:0xf bound_ctrl:1
	s_nop 1
	v_add_f32_dpp v226, v226, v226 row_mirror row_mask:0xf bank_mask:0xf bound_ctrl:1
	s_nop 1
	v_add_f32_dpp v226, v226, v226 row_bcast:15 row_mask:0xa bank_mask:0xf
	s_nop 1
	v_add_f32_dpp v226, v226, v226 row_bcast:31 row_mask:0xc bank_mask:0xf
	s_nop 0
	v_readlane_b32 s12, v226, 63
	s_nop 1
	v_mov_b32_e32 v230, s12
	v_fmamk_f32 v230, v230, 0x3a000000, v233
	v_mul_f32_e32 v231, 0x4b800000, v230
	v_cmp_lt_f32_e32 vcc, v230, v234
	s_nop 1
	v_cndmask_b32_e32 v230, v230, v231, vcc
	v_rsq_f32_e32 v230, v230
	s_nop 0
	v_mul_f32_e32 v231, 0x45800000, v230
	v_cndmask_b32_e32 v232, v230, v231, vcc
	v_mul_f32_e32 v2, v2, v232
	v_mul_f32_e32 v2, v194, v2
	v_add_f32_e32 v34, 1.0, v34
	v_fma_f32 v2, v34, v2, v66
	v_mul_f32_e32 v3, v3, v232
	v_mul_f32_e32 v3, v195, v3
	v_add_f32_e32 v35, 1.0, v35
	v_fma_f32 v3, v35, v3, v67
	v_mul_f32_e32 v4, v4, v232
	v_mul_f32_e32 v4, v196, v4
	v_add_f32_e32 v36, 1.0, v36
	v_fma_f32 v4, v36, v4, v68
	v_mul_f32_e32 v5, v5, v232
	v_mul_f32_e32 v5, v197, v5
	v_add_f32_e32 v37, 1.0, v37
	v_fma_f32 v5, v37, v5, v69
; DEV unsigned pack2(float a, float b) { float2v v = {a, b}; return __builtin_bit_cast(unsigned, __builtin_convertvector(v, bf16x2v)); }
; DEV void ph_adaln_row(const float* xin, const float* g, const float* mod, int sh_off, int sc_off, u16* hout, int row) {
;     ...
;     float y0 = v[i].x * rstd * g4.x * (1.f + sc.x) + sh.x;
;     float y1 = v[i].y * rstd * g4.y * (1.f + sc.y) + sh.y;
;     float y2 = v[i].z * rstd * g4.z * (1.f + sc.z) + sh.z;
;     float y3 = v[i].w * rstd * g4.w * (1.f + sc.w) + sh.w;
;     u32x2 pk; pk[0] = pack2(y0, y1); pk[1] = pack2(y2, y3);
;     *(u32x2*)(hout + (size_t)row * 2048 + col) = pk;
;   }
	v_mul_f32_e32 v6, v6, v232
	v_mul_f32_e32 v6, v198, v6
	v_add_f32_e32 v38, 1.0, v38
	v_fma_f32 v6, v38, v6, v70
	v_mul_f32_e32 v7, v7, v232
	v_mul_f32_e32 v7, v199, v7
	v_add_f32_e32 v39, 1.0, v39
	v_fma_f32 v7, v39, v7, v71
	v_mul_f32_e32 v8, v8, v232
	v_mul_f32_e32 v8, v200, v8
	v_add_f32_e32 v40, 1.0, v40
	v_fma_f32 v8, v40, v8, v72
	v_mul_f32_e32 v9, v9, v232
	v_mul_f32_e32 v9, v201, v9
	v_add_f32_e32 v41, 1.0, v41
	v_fma_f32 v9, v41, v9, v73
	v_mul_f32_e32 v10, v10, v232
	v_mul_f32_e32 v10, v202, v10
	v_add_f32_e32 v42, 1.0, v42
	v_fma_f32 v10, v42, v10, v74
	v_mul_f32_e32 v11, v11, v232
	v_mul_f32_e32 v11, v203, v11
	v_add_f32_e32 v43, 1.0, v43
	v_fma_f32 v11, v43, v11, v75
	v_mul_f32_e32 v12, v12, v232
	v_mul_f32_e32 v12, v204, v12
	v_add_f32_e32 v44, 1.0, v44
	v_fma_f32 v12, v44, v12, v76
	v_mul_f32_e32 v13, v13, v232
	v_mul_f32_e32 v13, v205, v13
	v_add_f32_e32 v45, 1.0, v45
	v_fma_f32 v13, v45, v13, v77
	v_mul_f32_e32 v14, v14, v232
	v_mul_f32_e32 v14, v206, v14
	v_add_f32_e32 v46, 1.0, v46
	v_fma_f32 v14, v46, v14, v78
	v_mul_f32_e32 v15, v15, v232
	v_mul_f32_e32 v15, v207, v15
	v_add_f32_e32 v47, 1.0, v47
	v_fma_f32 v15, v47, v15, v79
	v_mul_f32_e32 v16, v16, v232
	v_mul_f32_e32 v16, v208, v16
	v_add_f32_e32 v48, 1.0, v48
	v_fma_f32 v16, v48, v16, v80
	v_mul_f32_e32 v17, v17, v232
	v_mul_f32_e32 v17, v209, v17
	v_add_f32_e32 v49, 1.0, v49
	v_fma_f32 v17, v49, v17, v81
	v_mul_f32_e32 v18, v18, v232
	v_mul_f32_e32 v18, v210, v18
	v_add_f32_e32 v50, 1.0, v50
	v_fma_f32 v18, v50, v18, v82
	v_mul_f32_e32 v19, v19, v232
	v_mul_f32_e32 v19, v211, v19
	v_add_f32_e32 v51, 1.0, v51
	v_fma_f32 v19, v51, v19, v83
	v_mul_f32_e32 v20, v20, v232
	v_mul_f32_e32 v20, v212, v20
	v_add_f32_e32 v52, 1.0, v52
	v_fma_f32 v20, v52, v20, v84
	v_mul_f32_e32 v21, v21, v232
	v_mul_f32_e32 v21, v213, v21
	v_add_f32_e32 v53, 1.0, v53
	v_fma_f32 v21, v53, v21, v85
	v_mul_f32_e32 v22, v22, v232
	v_mul_f32_e32 v22, v214, v22
	v_add_f32_e32 v54, 1.0, v54
	v_fma_f32 v22, v54, v22, v86
	v_mul_f32_e32 v23, v23, v232
	v_mul_f32_e32 v23, v215, v23
	v_add_f32_e32 v55, 1.0, v55
	v_fma_f32 v23, v55, v23, v87
	v_mul_f32_e32 v24, v24, v232
	v_mul_f32_e32 v24, v216, v24
	v_add_f32_e32 v56, 1.0, v56
	v_fma_f32 v24, v56, v24, v88
	v_mul_f32_e32 v25, v25, v232
	v_mul_f32_e32 v25, v217, v25
	v_add_f32_e32 v57, 1.0, v57
	v_fma_f32 v25, v57, v25, v89
	v_mul_f32_e32 v26, v26, v232
	v_mul_f32_e32 v26, v218, v26
	v_add_f32_e32 v58, 1.0, v58
	v_fma_f32 v26, v58, v26, v90
	v_mul_f32_e32 v27, v27, v232
	v_mul_f32_e32 v27, v219, v27
	v_add_f32_e32 v59, 1.0, v59
	v_fma_f32 v27, v59, v27, v91
	v_mul_f32_e32 v28, v28, v232
	v_mul_f32_e32 v28, v220, v28
	v_add_f32_e32 v60, 1.0, v60
	v_fma_f32 v28, v60, v28, v92
	v_mul_f32_e32 v29, v29, v232
	v_mul_f32_e32 v29, v221, v29
	v_add_f32_e32 v61, 1.0, v61
	v_fma_f32 v29, v61, v29, v93
	v_mul_f32_e32 v30, v30, v232
	v_mul_f32_e32 v30, v222, v30
	v_add_f32_e32 v62, 1.0, v62
	v_fma_f32 v30, v62, v30, v94
	v_mul_f32_e32 v31, v31, v232
	v_mul_f32_e32 v31, v223, v31
	v_add_f32_e32 v63, 1.0, v63
	v_fma_f32 v31, v63, v31, v95
	v_mul_f32_e32 v32, v32, v232
	v_mul_f32_e32 v32, v224, v32
	v_add_f32_e32 v64, 1.0, v64
	v_fma_f32 v32, v64, v32, v96
	v_mul_f32_e32 v33, v33, v232
	v_mul_f32_e32 v33, v225, v33
	v_add_f32_e32 v65, 1.0, v65
	v_fma_f32 v33, v65, v33, v97
	v_cvt_pk_bf16_f32 v2, v2, v3
	v_cvt_pk_bf16_f32 v3, v4, v5
	v_cvt_pk_bf16_f32 v4, v6, v7
	v_cvt_pk_bf16_f32 v5, v8, v9
	v_cvt_pk_bf16_f32 v6, v10, v11
	v_cvt_pk_bf16_f32 v7, v12, v13
	v_cvt_pk_bf16_f32 v8, v14, v15
	v_cvt_pk_bf16_f32 v9, v16, v17
	v_cvt_pk_bf16_f32 v10, v18, v19
	v_cvt_pk_bf16_f32 v11, v20, v21
	v_cvt_pk_bf16_f32 v12, v22, v23
	v_cvt_pk_bf16_f32 v13, v24, v25
	v_cvt_pk_bf16_f32 v14, v26, v27
	v_cvt_pk_bf16_f32 v15, v28, v29
	v_cvt_pk_bf16_f32 v16, v30, v31
	v_cvt_pk_bf16_f32 v17, v32, v33
	s_lshl_b32 s13, s10, 12
	s_add_u32 s8, s80, s13
	s_addc_u32 s9, s81, 0
	global_store_dwordx2 v237, v[2:3], s[8:9]
	global_store_dwordx2 v237, v[4:5], s[8:9] offset:512
	global_store_dwordx2 v237, v[6:7], s[8:9] offset:1024
	global_store_dwordx2 v237, v[8:9], s[8:9] offset:1536
	global_store_dwordx2 v237, v[10:11], s[8:9] offset:2048
	global_store_dwordx2 v237, v[12:13], s[8:9] offset:2560
	global_store_dwordx2 v237, v[14:15], s[8:9] offset:3072
	global_store_dwordx2 v237, v[16:17], s[8:9] offset:3584
	s_branch .Lad_end_p1
; DEV void ph_adaln_row(const float* xin, const float* g, const float* mod, int sh_off, int sc_off, u16* hout, int row) {
;     ...
;   for (int i = 0; i < 8; ++i) {
;     v[i] = *(const float4*)(xr + i * 256 + lane * 4);
;     ss += v[i].x * v[i].x + v[i].y * v[i].y + v[i].z * v[i].z + v[i].w * v[i].w;
;   }
;   ss = wave_sum(ss);
;   const float rstd = rsqrtf(ss * (1.f / 2048.f) + 1e-6f);
;   const float* mb = mod + (size_t)b * 12288;
; #pragma unroll
;   for (int i = 0; i < 8; ++i) {
;     int col = i * 256 + lane * 4;
;     float4 g4 = *(const float4*)(g + col);
;     float4 sc = *(const float4*)(mb + sc_off + col);
;     float4 sh = *(const float4*)(mb + sh_off + col);
;     float y0 = v[i].x * rstd * g4.x * (1.f + sc.x) + sh.x;
;     float y1 = v[i].y * rstd * g4.y * (1.f + sc.y) + sh.y;
;     float y2 = v[i].z * rstd * g4.z * (1.f + sc.z) + sh.z;
;     float y3 = v[i].w * rstd * g4.w * (1.f + sc.w) + sh.w;
.Lad_last_p1_1:
	s_waitcnt vmcnt(0)
	v_mul_f32_e32 v226, v98, v98
	v_mul_f32_e32 v227, v99, v99
	v_mul_f32_e32 v228, v100, v100
	v_mul_f32_e32 v229, v101, v101
	v_fmac_f32_e32 v226, v102, v102
	v_fmac_f32_e32 v227, v103, v103
	v_fmac_f32_e32 v228, v104, v104
	v_fmac_f32_e32 v229, v105, v105
	v_fmac_f32_e32 v226, v106, v106
	v_fmac_f32_e32 v227, v107, v107
	v_fmac_f32_e32 v228, v108, v108
	v_fmac_f32_e32 v229, v109, v109
	v_fmac_f32_e32 v226, v110, v110
	v_fmac_f32_e32 v227, v111, v111
	v_fmac_f32_e32 v228, v112, v112
	v_fmac_f32_e32 v229, v113, v113
	v_fmac_f32_e32 v226, v114, v114
	v_fmac_f32_e32 v227, v115, v115
	v_fmac_f32_e32 v228, v116, v116
	v_fmac_f32_e32 v229, v117, v117
	v_fmac_f32_e32 v226, v118, v118
	v_fmac_f32_e32 v227, v119, v119
	v_fmac_f32_e32 v228, v120, v120
	v_fmac_f32_e32 v229, v121, v121
	v_fmac_f32_e32 v226, v122, v122
	v_fmac_f32_e32 v227, v123, v123
	v_fmac_f32_e32 v228, v124, v124
	v_fmac_f32_e32 v229, v125, v125
	v_fmac_f32_e32 v226, v126, v126
	v_fmac_f32_e32 v227, v127, v127
	v_fmac_f32_e32 v228, v128, v128
	v_fmac_f32_e32 v229, v129, v129
	v_add_f32_e32 v226, v227, v226
	v_add_f32_e32 v228, v229, v228
	v_add_f32_e32 v226, v228, v226
	s_nop 1
	v_add_f32_dpp v226, v226, v226 quad_perm:[1,0,3,2] row_mask:0xf bank_mask:0xf bound_ctrl:1
	s_nop 1
	v_add_f32_dpp v226, v226, v226 quad_perm:[2,3,0,1] row_mask:0xf bank_mask:0xf bound_ctrl:1
	s_nop 1
	v_add_f32_dpp v226, v226, v226 row_half_mirror row_mask:0xf bank_mask:0xf bound_ctrl:1
	s_nop 1
	v_add_f32_dpp v226, v226, v226 row_mirror row_mask:0xf bank_mask:0xf bound_ctrl:1
	s_nop 1
	v_add_f32_dpp v226, v226, v226 row_bcast:15 row_mask:0xa bank_mask:0xf
	s_nop 1
	v_add_f32_dpp v226, v226, v226 row_bcast:31 row_mask:0xc bank_mask:0xf
	s_nop 0
	v_readlane_b32 s12, v226, 63
	s_nop 1
	v_mov_b32_e32 v230, s12
	v_fmamk_f32 v230, v230, 0x3a000000, v233
	v_mul_f32_e32 v231, 0x4b800000, v230
	v_cmp_lt_f32_e32 vcc, v230, v234
	s_nop 1
	v_cndmask_b32_e32 v230, v230, v231, vcc
	v_rsq_f32_e32 v230, v230
	s_nop 0
	v_mul_f32_e32 v231, 0x45800000, v230
	v_cndmask_b32_e32 v232, v230, v231, vcc
	v_mul_f32_e32 v98, v98, v232
	v_mul_f32_e32 v98, v194, v98
	v_add_f32_e32 v130, 1.0, v130
	v_fma_f32 v98, v130, v98, v162
	v_mul_f32_e32 v99, v99, v232
	v_mul_f32_e32 v99, v195, v99
	v_add_f32_e32 v131, 1.0, v131
	v_fma_f32 v99, v131, v99, v163
	v_mul_f32_e32 v100, v100, v232
	v_mul_f32_e32 v100, v196, v100
	v_add_f32_e32 v132, 1.0, v132
	v_fma_f32 v100, v132, v100, v164
	v_mul_f32_e32 v101, v101, v232
	v_mul_f32_e32 v101, v197, v101
	v_add_f32_e32 v133, 1.0, v133
	v_fma_f32 v101, v133, v101, v165
	v_mul_f32_e32 v102, v102, v232
	v_mul_f32_e32 v102, v198, v102
	v_add_f32_e32 v134, 1.0, v134
	v_fma_f32 v102, v134, v102, v166
	v_mul_f32_e32 v103, v103, v232
	v_mul_f32_e32 v103, v199, v103
	v_add_f32_e32 v135, 1.0, v135
	v_fma_f32 v103, v135, v103, v167
	v_mul_f32_e32 v104, v104, v232
	v_mul_f32_e32 v104, v200, v104
	v_add_f32_e32 v136, 1.0, v136
	v_fma_f32 v104, v136, v104, v168
	v_mul_f32_e32 v105, v105, v232
	v_mul_f32_e32 v105, v201, v105
	v_add_f32_e32 v137, 1.0, v137
	v_fma_f32 v105, v137, v105, v169
	v_mul_f32_e32 v106, v106, v232
	v_mul_f32_e32 v106, v202, v106
	v_add_f32_e32 v138, 1.0, v138
	v_fma_f32 v106, v138, v106, v170
	v_mul_f32_e32 v107, v107, v232
	v_mul_f32_e32 v107, v203, v107
	v_add_f32_e32 v139, 1.0, v139
	v_fma_f32 v107, v139, v107, v171
	v_mul_f32_e32 v108, v108, v232
	v_mul_f32_e32 v108, v204, v108
	v_add_f32_e32 v140, 1.0, v140
	v_fma_f32 v108, v140, v108, v172
	v_mul_f32_e32 v109, v109, v232
	v_mul_f32_e32 v109, v205, v109
	v_add_f32_e32 v141, 1.0, v141
	v_fma_f32 v109, v141, v109, v173
	v_mul_f32_e32 v110, v110, v232
	v_mul_f32_e32 v110, v206, v110
	v_add_f32_e32 v142, 1.0, v142
	v_fma_f32 v110, v142, v110, v174
	v_mul_f32_e32 v111, v111, v232
	v_mul_f32_e32 v111, v207, v111
	v_add_f32_e32 v143, 1.0, v143
	v_fma_f32 v111, v143, v111, v175
	v_mul_f32_e32 v112, v112, v232
	v_mul_f32_e32 v112, v208, v112
	v_add_f32_e32 v144, 1.0, v144
	v_fma_f32 v112, v144, v112, v176
	v_mul_f32_e32 v113, v113, v232
	v_mul_f32_e32 v113, v209, v113
	v_add_f32_e32 v145, 1.0, v145
; DEV unsigned pack2(float a, float b) { float2v v = {a, b}; return __builtin_bit_cast(unsigned, __builtin_convertvector(v, bf16x2v)); }
; DEV void ph_adaln_row(const float* xin, const float* g, const float* mod, int sh_off, int sc_off, u16* hout, int row) {
;     ...
;     float y0 = v[i].x * rstd * g4.x * (1.f + sc.x) + sh.x;
;     float y1 = v[i].y * rstd * g4.y * (1.f + sc.y) + sh.y;
;     float y2 = v[i].z * rstd * g4.z * (1.f + sc.z) + sh.z;
;     float y3 = v[i].w * rstd * g4.w * (1.f + sc.w) + sh.w;
;     u32x2 pk; pk[0] = pack2(y0, y1); pk[1] = pack2(y2, y3);
;     *(u32x2*)(hout + (size_t)row * 2048 + col) = pk;
;   }
; DEV void xcd_barrier(unsigned* bar, unsigned x, volatile unsigned* st) {
;   asm volatile("s_waitcnt vmcnt(0)" ::: "memory");
;   __syncthreads();
;   if (threadIdx.x == 0) {
;     __builtin_amdgcn_s_waitcnt(0);
;     unsigned nloc = st[0], nx = st[1];
;     if (nloc == 0u) { xcd_barrier_complete(bar, x, nloc, nx); st[0] = nloc; st[1] = nx; }
	v_fma_f32 v113, v145, v113, v177
	v_mul_f32_e32 v114, v114, v232
	v_mul_f32_e32 v114, v210, v114
	v_add_f32_e32 v146, 1.0, v146
	v_fma_f32 v114, v146, v114, v178
	v_mul_f32_e32 v115, v115, v232
	v_mul_f32_e32 v115, v211, v115
	v_add_f32_e32 v147, 1.0, v147
	v_fma_f32 v115, v147, v115, v179
	v_mul_f32_e32 v116, v116, v232
	v_mul_f32_e32 v116, v212, v116
	v_add_f32_e32 v148, 1.0, v148
	v_fma_f32 v116, v148, v116, v180
	v_mul_f32_e32 v117, v117, v232
	v_mul_f32_e32 v117, v213, v117
	v_add_f32_e32 v149, 1.0, v149
	v_fma_f32 v117, v149, v117, v181
	v_mul_f32_e32 v118, v118, v232
	v_mul_f32_e32 v118, v214, v118
	v_add_f32_e32 v150, 1.0, v150
	v_fma_f32 v118, v150, v118, v182
	v_mul_f32_e32 v119, v119, v232
	v_mul_f32_e32 v119, v215, v119
	v_add_f32_e32 v151, 1.0, v151
	v_fma_f32 v119, v151, v119, v183
	v_mul_f32_e32 v120, v120, v232
	v_mul_f32_e32 v120, v216, v120
	v_add_f32_e32 v152, 1.0, v152
	v_fma_f32 v120, v152, v120, v184
	v_mul_f32_e32 v121, v121, v232
	v_mul_f32_e32 v121, v217, v121
	v_add_f32_e32 v153, 1.0, v153
	v_fma_f32 v121, v153, v121, v185
	v_mul_f32_e32 v122, v122, v232
	v_mul_f32_e32 v122, v218, v122
	v_add_f32_e32 v154, 1.0, v154
	v_fma_f32 v122, v154, v122, v186
	v_mul_f32_e32 v123, v123, v232
	v_mul_f32_e32 v123, v219, v123
	v_add_f32_e32 v155, 1.0, v155
	v_fma_f32 v123, v155, v123, v187
	v_mul_f32_e32 v124, v124, v232
	v_mul_f32_e32 v124, v220, v124
	v_add_f32_e32 v156, 1.0, v156
	v_fma_f32 v124, v156, v124, v188
	v_mul_f32_e32 v125, v125, v232
	v_mul_f32_e32 v125, v221, v125
	v_add_f32_e32 v157, 1.0, v157
	v_fma_f32 v125, v157, v125, v189
	v_mul_f32_e32 v126, v126, v232
	v_mul_f32_e32 v126, v222, v126
	v_add_f32_e32 v158, 1.0, v158
	v_fma_f32 v126, v158, v126, v190
	v_mul_f32_e32 v127, v127, v232
	v_mul_f32_e32 v127, v223, v127
	v_add_f32_e32 v159, 1.0, v159
	v_fma_f32 v127, v159, v127, v191
	v_mul_f32_e32 v128, v128, v232
	v_mul_f32_e32 v128, v224, v128
	v_add_f32_e32 v160, 1.0, v160
	v_fma_f32 v128, v160, v128, v192
	v_mul_f32_e32 v129, v129, v232
	v_mul_f32_e32 v129, v225, v129
	v_add_f32_e32 v161, 1.0, v161
	v_fma_f32 v129, v161, v129, v193
	v_cvt_pk_bf16_f32 v98, v98, v99
	v_cvt_pk_bf16_f32 v99, v100, v101
	v_cvt_pk_bf16_f32 v100, v102, v103
	v_cvt_pk_bf16_f32 v101, v104, v105
	v_cvt_pk_bf16_f32 v102, v106, v107
	v_cvt_pk_bf16_f32 v103, v108, v109
	v_cvt_pk_bf16_f32 v104, v110, v111
	v_cvt_pk_bf16_f32 v105, v112, v113
	v_cvt_pk_bf16_f32 v106, v114, v115
	v_cvt_pk_bf16_f32 v107, v116, v117
	v_cvt_pk_bf16_f32 v108, v118, v119
	v_cvt_pk_bf16_f32 v109, v120, v121
	v_cvt_pk_bf16_f32 v110, v122, v123
	v_cvt_pk_bf16_f32 v111, v124, v125
	v_cvt_pk_bf16_f32 v112, v126, v127
	v_cvt_pk_bf16_f32 v113, v128, v129
	s_lshl_b32 s13, s10, 12
	s_add_u32 s8, s80, s13
	s_addc_u32 s9, s81, 0
	global_store_dwordx2 v237, v[98:99], s[8:9]
	global_store_dwordx2 v237, v[100:101], s[8:9] offset:512
	global_store_dwordx2 v237, v[102:103], s[8:9] offset:1024
	global_store_dwordx2 v237, v[104:105], s[8:9] offset:1536
	global_store_dwordx2 v237, v[106:107], s[8:9] offset:2048
	global_store_dwordx2 v237, v[108:109], s[8:9] offset:2560
	global_store_dwordx2 v237, v[110:111], s[8:9] offset:3072
	global_store_dwordx2 v237, v[112:113], s[8:9] offset:3584
.Lad_end_p1:
.LBB0_192:
	s_or_b64 exec, exec, s[0:1]
	s_waitcnt vmcnt(0)
	s_barrier
	s_mov_b64 s[0:1], exec
	v_readlane_b32 s2, v254, 2
	v_readlane_b32 s3, v254, 3
	s_and_b64 s[2:3], s[0:1], s[2:3]
	s_mov_b64 exec, s[2:3]
	s_cbranch_execz .LBB0_244
	s_mov_b64 s[2:3], src_shared_base
	v_mov_b32_e32 v2, 0x12100
	v_mov_b32_e32 v3, s3
	s_waitcnt vmcnt(0) expcnt(0) lgkmcnt(0)
	flat_load_dword v4, v[2:3] sc0 sc1
	s_waitcnt vmcnt(0)
	v_mov_b32_e32 v2, 0x12104
	flat_load_dword v2, v[2:3] sc0 sc1
	s_waitcnt vmcnt(0) lgkmcnt(0)
	v_cmp_eq_u32_e32 vcc, 0, v4
	s_and_saveexec_b64 s[6:7], vcc
	s_cbranch_execz .LBB0_208
	s_add_u32 s8, s70, 0x1000
	s_addc_u32 s9, s71, 0
	s_add_u32 s10, s70, 0x1100
	s_addc_u32 s11, s71, 0
	s_add_u32 s12, s70, 0x1200
	s_addc_u32 s13, s71, 0
	s_add_u32 s14, s70, 0x1300
	s_addc_u32 s15, s71, 0
	s_mov_b32 s2, 1
	v_mov_b32_e32 v17, 0
	s_branch .LBB0_196

; template <class AF, class EPI>
; DEV void gemm_tile256(AF aptr, const u16* Bt, int ldb, int K, EPI epi, char* smem) {
;     ...
;   auto stage = [&](int kt, int buf) {
;     char* SA = smem + buf * 24576;
;     char* SB = SA + 16384;
; #pragma unroll
;     for (int i = 0; i < 4; ++i) {
;       int bo = tid * 16 + i * 4096, r = bo >> 6, c = (bo & 63) >> 1;
;       __builtin_amdgcn_global_load_lds((const unsigned*)aptr(r, kt * 32 + c), (__attribute__((address_space(3))) unsigned*)(SA + bo), 16, 0, 0);
;     }
; #pragma unroll
;     for (int i = 0; i < 2; ++i) {
;       int bo = tid * 16 + i * 4096, r = bo >> 6, c = (bo & 63) >> 1;
;       __builtin_amdgcn_global_load_lds((const unsigned*)(Bt + (size_t)r * ldb + kt * 32 + c), (__attribute__((address_space(3))) unsigned*)(SB + bo), 16, 0, 0);
;     }
;   };
;   asm volatile("s_waitcnt vmcnt(0)" ::: "memory");
;   __syncthreads();
;   stage(0, 0);
;   stage(1, 1);
;   const unsigned lbase = (unsigned)(size_t)(const __attribute__((address_space(3))) char*)smem;
;   const unsigned aoff = lbase + (wr * 128 + fr) * 64 + fq * 16, boff = lbase + 16384 + (wc * 64 + fr) * 64 + fq * 16;
; __global__ void __launch_bounds__(256, 2) fwd_megakernel(Params p) {
;     ...
;   for (int jt = (bid >> 3); jt < 8 * 37; jt += (nb >> 3)) {
;     const int pn = jt >> 3, pm = (bid & 7) * 8 + (jt & 7);
;     const u16* A = p.h + (size_t)pm * 256 * 2048;
;     gemm_tile256([&](int r, int k) { return A + (size_t)r * 2048 + k; }, p.Wt_in + (size_t)pn * 128 * 2048, 2048, 2048,
.LBB0_247:
	s_and_b32 s57, s3, 7
	s_lshl_b32 s0, s57, 19
	s_add_i32 s0, s6, s0
	s_lshl_b32 s44, s0, 1
	s_and_b32 s0, s93, 7
	s_or_b32 s56, s0, s4
	v_readlane_b32 s16, v255, 9
	v_mov_b32_e32 v144, v0
	s_ashr_i32 s38, s93, 3
	s_lshl_b32 s0, s56, 20
	v_readlane_b32 s20, v255, 13
	v_readlane_b32 s21, v255, 14
	v_ashrrev_i32_e32 v2, 2, v144
	s_add_u32 s40, s20, s0
	v_lshlrev_b32_e32 v148, 4, v144
	v_ashrrev_i32_e32 v3, 31, v2
	s_addc_u32 s41, s21, 0
	s_ashr_i32 s39, s38, 31
	v_lshlrev_b64 v[2:3], 12, v[2:3]
	v_add_u32_e32 v10, 0x1000, v148
	s_lshl_b64 s[0:1], s[38:39], 19
	v_lshl_add_u64 v[4:5], s[40:41], 0, v[2:3]
	v_and_b32_e32 v134, 48, v148
	v_and_b32_e32 v253, 32, v144
	v_xor_b32_e32 v134, v134, v253
	v_readfirstlane_b32 s39, v148
	v_ashrrev_i32_e32 v6, 6, v10
	v_add_u32_e32 v14, 0x2000, v148
	v_readlane_b32 s17, v255, 10
	v_readlane_b32 s18, v255, 11
	v_readlane_b32 s19, v255, 12
	v_readlane_b32 s22, v255, 15
	v_readlane_b32 s23, v255, 16
	v_readlane_b32 s24, v255, 17
	v_readlane_b32 s25, v255, 18
	v_readlane_b32 s26, v255, 19
	v_readlane_b32 s27, v255, 20
	v_readlane_b32 s28, v255, 21
	v_readlane_b32 s29, v255, 22
	v_readlane_b32 s30, v255, 23
	v_readlane_b32 s31, v255, 24
	v_lshl_add_u64 v[4:5], v[4:5], 0, v[134:135]
	s_mov_b32 m0, s39
	v_ashrrev_i32_e32 v7, 31, v6
	v_readfirstlane_b32 s39, v10
	v_ashrrev_i32_e32 v10, 6, v14
	v_add_u32_e32 v18, 0x3000, v148
	v_readlane_b32 s16, v254, 4
	s_waitcnt vmcnt(0)
	s_barrier
; template <class AF, class EPI>
; DEV void gemm_tile256(AF aptr, const u16* Bt, int ldb, int K, EPI epi, char* smem) {
;     ...
;   auto stage = [&](int kt, int buf) {
;     char* SA = smem + buf * 24576;
;     char* SB = SA + 16384;
; #pragma unroll
;     for (int i = 0; i < 4; ++i) {
;       int bo = tid * 16 + i * 4096, r = bo >> 6, c = (bo & 63) >> 1;
;       __builtin_amdgcn_global_load_lds((const unsigned*)aptr(r, kt * 32 + c), (__attribute__((address_space(3))) unsigned*)(SA + bo), 16, 0, 0);
;     }
; #pragma unroll
;     for (int i = 0; i < 2; ++i) {
;       int bo = tid * 16 + i * 4096, r = bo >> 6, c = (bo & 63) >> 1;
;       __builtin_amdgcn_global_load_lds((const unsigned*)(Bt + (size_t)r * ldb + kt * 32 + c), (__attribute__((address_space(3))) unsigned*)(SB + bo), 16, 0, 0);
;     }
;   };
;   asm volatile("s_waitcnt vmcnt(0)" ::: "memory");
;   __syncthreads();
;   stage(0, 0);
;   stage(1, 1);
;   const unsigned lbase = (unsigned)(size_t)(const __attribute__((address_space(3))) char*)smem;
;   const unsigned aoff = lbase + (wr * 128 + fr) * 64 + fq * 16, boff = lbase + 16384 + (wc * 64 + fr) * 64 + fq * 16;
	global_load_lds_dwordx4 v[4:5], off
	v_lshlrev_b64 v[6:7], 12, v[6:7]
	s_mov_b32 m0, s39
	v_ashrrev_i32_e32 v11, 31, v10
	v_readfirstlane_b32 s39, v14
	v_ashrrev_i32_e32 v14, 6, v18
	v_readlane_b32 s26, v254, 14
	v_lshl_add_u64 v[8:9], s[40:41], 0, v[6:7]
	v_lshlrev_b64 v[10:11], 12, v[10:11]
	v_ashrrev_i32_e32 v15, 31, v14
	v_readlane_b32 s27, v254, 15
	s_add_u32 s42, s26, s0
	v_lshl_add_u64 v[8:9], v[8:9], 0, v[134:135]
	v_lshl_add_u64 v[12:13], s[40:41], 0, v[10:11]
	v_lshlrev_b64 v[14:15], 12, v[14:15]
	s_addc_u32 s43, s27, s1
	global_load_lds_dwordx4 v[8:9], off
	v_lshl_add_u64 v[12:13], v[12:13], 0, v[134:135]
	s_mov_b32 m0, s39
	v_lshl_add_u64 v[16:17], s[40:41], 0, v[14:15]
	v_readfirstlane_b32 s39, v18
	v_add_u32_e32 v20, 0x4000, v148
	global_load_lds_dwordx4 v[12:13], off
	v_lshl_add_u64 v[16:17], v[16:17], 0, v[134:135]
	s_mov_b32 m0, s39
	v_lshl_add_u64 v[18:19], s[42:43], 0, v[2:3]
	v_readfirstlane_b32 s39, v20
	v_add_u32_e32 v22, 0x5000, v148
	global_load_lds_dwordx4 v[16:17], off
	v_lshl_add_u64 v[18:19], v[18:19], 0, v[134:135]
	s_mov_b32 m0, s39
	v_lshl_add_u64 v[20:21], s[42:43], 0, v[6:7]
	v_readfirstlane_b32 s39, v22
	v_add_u32_e32 v22, 0x6000, v148
	global_load_lds_dwordx4 v[18:19], off
	v_lshl_add_u64 v[20:21], v[20:21], 0, v[134:135]
	s_mov_b32 m0, s39
	v_readfirstlane_b32 s39, v22
	global_load_lds_dwordx4 v[20:21], off
	v_lshl_add_u64 v[4:5], v[4:5], 0, 64
	s_mov_b32 m0, s39
	s_add_u32 s40, s5, s44
	global_load_lds_dwordx4 v[4:5], off
	v_lshl_add_u64 v[4:5], v[8:9], 0, 64
	v_add_u32_e32 v8, 0x7000, v148
	v_bfe_u32 v147, v144, 4, 2
	v_readfirstlane_b32 s39, v8
	v_add_u32_e32 v8, 0x8000, v148
	s_mov_b32 m0, s39
	v_readfirstlane_b32 s39, v8
	v_add_u32_e32 v8, 0x9000, v148
	global_load_lds_dwordx4 v[4:5], off
	v_lshl_add_u64 v[4:5], v[12:13], 0, 64
	s_mov_b32 m0, s39
	v_readfirstlane_b32 s39, v8
	v_add_u32_e32 v8, 0xa000, v148
	global_load_lds_dwordx4 v[4:5], off
	v_lshl_add_u64 v[4:5], v[16:17], 0, 64
	s_mov_b32 m0, s39
	v_readfirstlane_b32 s39, v8
	v_add_u32_e32 v8, 0xb000, v148
	global_load_lds_dwordx4 v[4:5], off
	v_lshl_add_u64 v[4:5], v[18:19], 0, 64
	s_mov_b32 m0, s39
	v_readfirstlane_b32 s39, v8
	global_load_lds_dwordx4 v[4:5], off
	v_lshl_add_u64 v[4:5], v[20:21], 0, 64
	s_mov_b32 m0, s39
	s_addc_u32 s41, s76, 0
	global_load_lds_dwordx4 v[4:5], off
	v_bfe_u32 v145, v144, 6, 1
	v_ashrrev_i32_e32 v159, 7, v144
	v_and_b32_e32 v146, 15, v144
	v_lshlrev_b32_e32 v8, 4, v147
	v_lshlrev_b32_e32 v253, 2, v144
	v_and_b32_e32 v253, 32, v253
	v_xor_b32_e32 v8, v8, v253
	s_add_u32 s0, s7, s0
	v_lshlrev_b32_e32 v4, 13, v159
	v_lshlrev_b32_e32 v5, 6, v146
	v_lshl_or_b32 v9, v145, 12, v8
	s_movk_i32 s39, 0x4000
	v_or_b32_e32 v2, v2, v134
	v_or_b32_e32 v6, v6, v134
	v_or_b32_e32 v10, v10, v134
	v_or_b32_e32 v14, v14, v134
	s_addc_u32 s1, s8, s1
	v_or3_b32 v149, v4, v8, v5
	v_or3_b32 v150, v5, v9, s39
	v_lshl_add_u64 v[130:131], s[40:41], 0, v[2:3]
	v_lshl_add_u64 v[132:133], s[40:41], 0, v[6:7]
	v_lshl_add_u64 v[136:137], s[40:41], 0, v[10:11]
	v_lshl_add_u64 v[138:139], s[40:41], 0, v[14:15]
	v_lshl_add_u64 v[140:141], s[0:1], 0, v[6:7]
	v_lshl_add_u64 v[142:143], s[0:1], 0, v[2:3]
	s_mov_b64 s[0:1], 0
	s_mov_b32 s39, 0
	s_mov_b32 s42, 0
	v_mov_b32_e32 v2, 0
	v_mov_b32_e32 v3, v135
	v_mov_b32_e32 v4, v135
	v_mov_b32_e32 v5, v135
	v_mov_b32_e32 v6, 0
	v_mov_b32_e32 v7, v135
	v_mov_b32_e32 v8, v135
	v_mov_b32_e32 v9, v135
	v_mov_b32_e32 v10, 0
	v_mov_b32_e32 v11, v135
	v_mov_b32_e32 v12, v135
	v_mov_b32_e32 v13, v135
	v_mov_b32_e32 v14, 0
	v_mov_b32_e32 v15, v135
	v_mov_b32_e32 v16, v135
	v_mov_b32_e32 v17, v135
	v_mov_b32_e32 v18, 0
	v_mov_b32_e32 v19, v135
	v_mov_b32_e32 v20, v135
	v_mov_b32_e32 v21, v135
	v_mov_b32_e32 v22, 0
	v_mov_b32_e32 v23, v135
	v_mov_b32_e32 v24, v135
	v_mov_b32_e32 v25, v135
	v_mov_b32_e32 v26, 0
	v_mov_b32_e32 v27, v135
	v_mov_b32_e32 v28, v135
	v_mov_b32_e32 v29, v135
	v_mov_b32_e32 v30, 0
	v_mov_b32_e32 v31, v135
	v_mov_b32_e32 v32, v135
	v_mov_b32_e32 v33, v135
	v_mov_b32_e32 v34, 0
	v_mov_b32_e32 v35, v135
	v_mov_b32_e32 v36, v135
	v_mov_b32_e32 v37, v135
	v_mov_b32_e32 v38, 0
	v_mov_b32_e32 v39, v135
	v_mov_b32_e32 v40, v135
	v_mov_b32_e32 v41, v135
	v_mov_b32_e32 v42, 0
	v_mov_b32_e32 v43, v135
	v_mov_b32_e32 v44, v135
	v_mov_b32_e32 v45, v135
	v_mov_b32_e32 v94, 0
	v_mov_b32_e32 v95, v135
	v_mov_b32_e32 v96, v135
	v_mov_b32_e32 v97, v135
	v_mov_b32_e32 v98, 0
	v_mov_b32_e32 v99, v135
	v_mov_b32_e32 v100, v135
	v_mov_b32_e32 v101, v135
	v_mov_b32_e32 v102, 0
	v_mov_b32_e32 v103, v135
	v_mov_b32_e32 v104, v135
	v_mov_b32_e32 v105, v135
	v_mov_b32_e32 v106, 0
	v_mov_b32_e32 v107, v135
	v_mov_b32_e32 v108, v135
	v_mov_b32_e32 v109, v135
	v_mov_b32_e32 v110, 0
	v_mov_b32_e32 v111, v135
	v_mov_b32_e32 v112, v135
	v_mov_b32_e32 v113, v135
	v_mov_b32_e32 v114, 0
	v_mov_b32_e32 v115, v135
	v_mov_b32_e32 v116, v135
	v_mov_b32_e32 v117, v135
	v_mov_b32_e32 v118, 0
	v_mov_b32_e32 v119, v135
	v_mov_b32_e32 v120, v135
	v_mov_b32_e32 v121, v135
	v_mov_b32_e32 v122, 0
	v_mov_b32_e32 v123, v135
	v_mov_b32_e32 v124, v135
	v_mov_b32_e32 v125, v135
	v_mov_b32_e32 v126, 0
	v_mov_b32_e32 v127, v135
	v_mov_b32_e32 v128, v135
	v_mov_b32_e32 v129, v135
	v_mov_b32_e32 v46, 0
	v_mov_b32_e32 v47, v135
	v_mov_b32_e32 v48, v135
	v_mov_b32_e32 v49, v135
	v_mov_b32_e32 v50, 0
	v_mov_b32_e32 v51, v135
	v_mov_b32_e32 v52, v135
	v_mov_b32_e32 v53, v135
	v_mov_b32_e32 v54, 0
	v_mov_b32_e32 v55, v135
	v_mov_b32_e32 v56, v135
	v_mov_b32_e32 v57, v135
	v_mov_b32_e32 v58, 0
	v_mov_b32_e32 v59, v135
	v_mov_b32_e32 v60, v135
	v_mov_b32_e32 v61, v135
	v_mov_b32_e32 v62, 0
	v_mov_b32_e32 v63, v135
	v_mov_b32_e32 v64, v135
	v_mov_b32_e32 v65, v135
	v_mov_b32_e32 v66, 0
	v_mov_b32_e32 v67, v135
	v_mov_b32_e32 v68, v135
	v_mov_b32_e32 v69, v135
	v_mov_b32_e32 v70, 0
	v_mov_b32_e32 v71, v135
	v_mov_b32_e32 v72, v135
	v_mov_b32_e32 v73, v135
	v_mov_b32_e32 v74, 0
	v_mov_b32_e32 v75, v135
	v_mov_b32_e32 v76, v135
	v_mov_b32_e32 v77, v135
	v_mov_b32_e32 v78, 0
	v_mov_b32_e32 v79, v135
	v_mov_b32_e32 v80, v135
	v_mov_b32_e32 v81, v135
	v_mov_b32_e32 v82, 0
	v_mov_b32_e32 v83, v135
	v_mov_b32_e32 v84, v135
	v_mov_b32_e32 v85, v135
	v_mov_b32_e32 v86, 0
	v_mov_b32_e32 v87, v135
	v_mov_b32_e32 v88, v135
	v_mov_b32_e32 v89, v135
	v_mov_b32_e32 v90, 0
	v_mov_b32_e32 v91, v135
	v_mov_b32_e32 v92, v135
	v_mov_b32_e32 v93, v135
	v_readlane_b32 s17, v254, 5
	v_readlane_b32 s18, v254, 6
	v_readlane_b32 s19, v254, 7
	v_readlane_b32 s20, v254, 8
	v_readlane_b32 s21, v254, 9
	v_readlane_b32 s22, v254, 10
	v_readlane_b32 s23, v254, 11
	v_readlane_b32 s24, v254, 12
	v_readlane_b32 s25, v254, 13
	v_readlane_b32 s28, v254, 16
	v_readlane_b32 s29, v254, 17
	v_readlane_b32 s30, v254, 18
	v_readlane_b32 s31, v254, 19
	s_branch .LBB0_249

; template <class AF, class EPI>
; DEV void gemm_tile256(AF aptr, const u16* Bt, int ldb, int K, EPI epi, char* smem) {
;     ...
;   for (int t = 0; t < nk; ++t) {
;     if (t + 1 < nk) asm volatile("s_waitcnt vmcnt(6)" ::: "memory");
;     else asm volatile("s_waitcnt vmcnt(0)" ::: "memory");
;     __builtin_amdgcn_s_barrier();
;     if (t + 2 < nk) { int nb2 = buf + 2; if (nb2 >= 3) nb2 -= 3; stage(t + 2, nb2); }
;     const unsigned sa = aoff + buf * 24576, sb = boff + buf * 24576;
;     u32x4 a0, a1, a2, a3, a4, a5, a6, a7, b0, b1, b2, b3;
;     asm volatile("ds_read_b128 %0, %1" : "=v"(b0) : "v"(sb));
;     asm volatile("ds_read_b128 %0, %1 offset:1024" : "=v"(b1) : "v"(sb));
;     asm volatile("ds_read_b128 %0, %1 offset:2048" : "=v"(b2) : "v"(sb));
;     asm volatile("ds_read_b128 %0, %1 offset:3072" : "=v"(b3) : "v"(sb));
;     asm volatile("ds_read_b128 %0, %1" : "=v"(a0) : "v"(sa));
;     asm volatile("ds_read_b128 %0, %1 offset:1024" : "=v"(a1) : "v"(sa));
;     asm volatile("ds_read_b128 %0, %1 offset:2048" : "=v"(a2) : "v"(sa));
;     asm volatile("ds_read_b128 %0, %1 offset:3072" : "=v"(a3) : "v"(sa));
;     asm volatile("ds_read_b128 %0, %1 offset:4096" : "=v"(a4) : "v"(sa));
;     asm volatile("ds_read_b128 %0, %1 offset:5120" : "=v"(a5) : "v"(sa));
;     asm volatile("ds_read_b128 %0, %1 offset:6144" : "=v"(a6) : "v"(sa));
;     asm volatile("ds_read_b128 %0, %1 offset:7168" : "=v"(a7) : "v"(sa));
;     asm volatile("s_waitcnt lgkmcnt(4)" : "+v"(a0), "+v"(a1), "+v"(a2), "+v"(a3), "+v"(b0), "+v"(b1), "+v"(b2), "+v"(b3));
;     bf16x8 Bv[4];
;     Bv[0] = __builtin_bit_cast(bf16x8, b0); Bv[1] = __builtin_bit_cast(bf16x8, b1); Bv[2] = __builtin_bit_cast(bf16x8, b2); Bv[3] = __builtin_bit_cast(bf16x8, b3);
;     {
;       bf16x8 At[4];
;       At[0] = __builtin_bit_cast(bf16x8, a0); At[1] = __builtin_bit_cast(bf16x8, a1); At[2] = __builtin_bit_cast(bf16x8, a2); At[3] = __builtin_bit_cast(bf16x8, a3);
; #pragma unroll
;       for (int m = 0; m < 4; ++m)
; #pragma unroll
;         for (int n = 0; n < 4; ++n) acc[m][n] = __builtin_amdgcn_mfma_f32_16x16x32_bf16(At[m], Bv[n], acc[m][n], 0, 0, 0);
;     }
;     asm volatile("s_waitcnt lgkmcnt(0)" : "+v"(a4), "+v"(a5), "+v"(a6), "+v"(a7));
;     {
;       bf16x8 At[4];
.LBB0_253:
	s_barrier
	s_mul_i32 s40, s39, 0x6000
	v_add_u32_e32 v134, s40, v149
	v_add_u32_e32 v151, s40, v150
	ds_read_b128 v[152:155], v151
	ds_read_b128 v[160:163], v151 offset:1024
	ds_read_b128 v[164:167], v151 offset:2048
	ds_read_b128 v[168:171], v151 offset:3072
	ds_read_b128 v[172:175], v134
	ds_read_b128 v[176:179], v134 offset:1024
	ds_read_b128 v[180:183], v134 offset:2048
	ds_read_b128 v[184:187], v134 offset:3072
	ds_read_b128 v[188:191], v134 offset:4096
	ds_read_b128 v[192:195], v134 offset:5120
	ds_read_b128 v[196:199], v134 offset:6144
	ds_read_b128 v[200:203], v134 offset:7168
	s_cmp_gt_u32 s42, 61
	s_cbranch_scc1 .Lgnodma_g2
	s_cmp_gt_i32 s39, 0
	s_cselect_b32 s40, -1, 2
	s_add_i32 s40, s40, s39
	s_mulk_i32 s40, 0x6000
	v_add_u32_e32 v252, s40, v148
	s_nop 0
	v_readfirstlane_b32 s40, v252
	s_waitcnt lgkmcnt(7)
	v_mfma_f32_16x16x32_bf16 v[126:129], v[172:175], v[152:155], v[126:129]
	v_mfma_f32_16x16x32_bf16 v[122:125], v[172:175], v[160:163], v[122:125]
	v_mfma_f32_16x16x32_bf16 v[118:121], v[172:175], v[164:167], v[118:121]
	v_mfma_f32_16x16x32_bf16 v[114:117], v[172:175], v[168:171], v[114:117]
	v_lshl_add_u64 v[250:251], v[130:131], 0, s[0:1]
	s_mov_b32 m0, s40
	s_nop 0
	global_load_lds_dwordx4 v[250:251], off
	s_waitcnt lgkmcnt(6)
	v_mfma_f32_16x16x32_bf16 v[110:113], v[176:179], v[152:155], v[110:113]
	v_mfma_f32_16x16x32_bf16 v[106:109], v[176:179], v[160:163], v[106:109]
	v_mfma_f32_16x16x32_bf16 v[102:105], v[176:179], v[164:167], v[102:105]
	v_mfma_f32_16x16x32_bf16 v[98:101], v[176:179], v[168:171], v[98:101]
	v_lshl_add_u64 v[250:251], v[132:133], 0, s[0:1]
	s_add_u32 m0, s40, 0x1000
	s_nop 0
	global_load_lds_dwordx4 v[250:251], off
	s_waitcnt lgkmcnt(5)
	v_mfma_f32_16x16x32_bf16 v[94:97], v[180:183], v[152:155], v[94:97]
	v_mfma_f32_16x16x32_bf16 v[42:45], v[180:183], v[160:163], v[42:45]
	v_mfma_f32_16x16x32_bf16 v[38:41], v[180:183], v[164:167], v[38:41]
	v_mfma_f32_16x16x32_bf16 v[34:37], v[180:183], v[168:171], v[34:37]
	v_lshl_add_u64 v[250:251], v[136:137], 0, s[0:1]
	s_add_u32 m0, s40, 0x2000
	s_nop 0
	global_load_lds_dwordx4 v[250:251], off
	s_waitcnt lgkmcnt(4)
	v_mfma_f32_16x16x32_bf16 v[30:33], v[184:187], v[152:155], v[30:33]
	v_mfma_f32_16x16x32_bf16 v[26:29], v[184:187], v[160:163], v[26:29]
	v_mfma_f32_16x16x32_bf16 v[22:25], v[184:187], v[164:167], v[22:25]
	v_mfma_f32_16x16x32_bf16 v[18:21], v[184:187], v[168:171], v[18:21]
	v_lshl_add_u64 v[250:251], v[138:139], 0, s[0:1]
	s_add_u32 m0, s40, 0x3000
	s_nop 0
	global_load_lds_dwordx4 v[250:251], off
	s_waitcnt lgkmcnt(3)
	v_mfma_f32_16x16x32_bf16 v[14:17], v[188:191], v[152:155], v[14:17]
	v_mfma_f32_16x16x32_bf16 v[10:13], v[188:191], v[160:163], v[10:13]
	v_mfma_f32_16x16x32_bf16 v[6:9], v[188:191], v[164:167], v[6:9]
	v_mfma_f32_16x16x32_bf16 v[2:5], v[188:191], v[168:171], v[2:5]
	v_lshl_add_u64 v[250:251], v[142:143], 0, s[0:1]
	s_add_u32 m0, s40, 0x4000
	s_nop 0
	global_load_lds_dwordx4 v[250:251], off
	s_waitcnt lgkmcnt(2)
	v_mfma_f32_16x16x32_bf16 v[46:49], v[192:195], v[152:155], v[46:49]
	v_mfma_f32_16x16x32_bf16 v[50:53], v[192:195], v[160:163], v[50:53]
	v_mfma_f32_16x16x32_bf16 v[54:57], v[192:195], v[164:167], v[54:57]
	v_mfma_f32_16x16x32_bf16 v[58:61], v[192:195], v[168:171], v[58:61]
	v_lshl_add_u64 v[250:251], v[140:141], 0, s[0:1]
	s_add_u32 m0, s40, 0x5000
	s_nop 0
	global_load_lds_dwordx4 v[250:251], off
	s_waitcnt lgkmcnt(1)
	v_mfma_f32_16x16x32_bf16 v[62:65], v[196:199], v[152:155], v[62:65]
	v_mfma_f32_16x16x32_bf16 v[66:69], v[196:199], v[160:163], v[66:69]
	v_mfma_f32_16x16x32_bf16 v[70:73], v[196:199], v[164:167], v[70:73]
	v_mfma_f32_16x16x32_bf16 v[74:77], v[196:199], v[168:171], v[74:77]
	s_waitcnt lgkmcnt(0)
	v_mfma_f32_16x16x32_bf16 v[78:81], v[200:203], v[152:155], v[78:81]
	v_mfma_f32_16x16x32_bf16 v[82:85], v[200:203], v[160:163], v[82:85]
	v_mfma_f32_16x16x32_bf16 v[86:89], v[200:203], v[164:167], v[86:89]
	v_mfma_f32_16x16x32_bf16 v[90:93], v[200:203], v[168:171], v[90:93]
	s_branch .Lgjoin_g2
.Lgnodma_g2:
	s_waitcnt lgkmcnt(7)
	v_mfma_f32_16x16x32_bf16 v[126:129], v[172:175], v[152:155], v[126:129]
	v_mfma_f32_16x16x32_bf16 v[122:125], v[172:175], v[160:163], v[122:125]
	v_mfma_f32_16x16x32_bf16 v[118:121], v[172:175], v[164:167], v[118:121]
	v_mfma_f32_16x16x32_bf16 v[114:117], v[172:175], v[168:171], v[114:117]
	s_waitcnt lgkmcnt(6)
	v_mfma_f32_16x16x32_bf16 v[110:113], v[176:179], v[152:155], v[110:113]
	v_mfma_f32_16x16x32_bf16 v[106:109], v[176:179], v[160:163], v[106:109]
	v_mfma_f32_16x16x32_bf16 v[102:105], v[176:179], v[164:167], v[102:105]
	v_mfma_f32_16x16x32_bf16 v[98:101], v[176:179], v[168:171], v[98:101]
	s_waitcnt lgkmcnt(5)
	v_mfma_f32_16x16x32_bf16 v[94:97], v[180:183], v[152:155], v[94:97]
	v_mfma_f32_16x16x32_bf16 v[42:45], v[180:183], v[160:163], v[42:45]
	v_mfma_f32_16x16x32_bf16 v[38:41], v[180:183], v[164:167], v[38:41]
	v_mfma_f32_16x16x32_bf16 v[34:37], v[180:183], v[168:171], v[34:37]
	s_waitcnt lgkmcnt(4)
	v_mfma_f32_16x16x32_bf16 v[30:33], v[184:187], v[152:155], v[30:33]
	v_mfma_f32_16x16x32_bf16 v[26:29], v[184:187], v[160:163], v[26:29]
	v_mfma_f32_16x16x32_bf16 v[22:25], v[184:187], v[164:167], v[22:25]
	v_mfma_f32_16x16x32_bf16 v[18:21], v[184:187], v[168:171], v[18:21]
	s_waitcnt lgkmcnt(3)
	v_mfma_f32_16x16x32_bf16 v[14:17], v[188:191], v[152:155], v[14:17]
	v_mfma_f32_16x16x32_bf16 v[10:13], v[188:191], v[160:163], v[10:13]
	v_mfma_f32_16x16x32_bf16 v[6:9], v[188:191], v[164:167], v[6:9]
	v_mfma_f32_16x16x32_bf16 v[2:5], v[188:191], v[168:171], v[2:5]
	s_waitcnt lgkmcnt(2)
	v_mfma_f32_16x16x32_bf16 v[46:49], v[192:195], v[152:155], v[46:49]
	v_mfma_f32_16x16x32_bf16 v[50:53], v[192:195], v[160:163], v[50:53]
	v_mfma_f32_16x16x32_bf16 v[54:57], v[192:195], v[164:167], v[54:57]
	v_mfma_f32_16x16x32_bf16 v[58:61], v[192:195], v[168:171], v[58:61]
	s_waitcnt lgkmcnt(1)
	v_mfma_f32_16x16x32_bf16 v[62:65], v[196:199], v[152:155], v[62:65]
	v_mfma_f32_16x16x32_bf16 v[66:69], v[196:199], v[160:163], v[66:69]
	v_mfma_f32_16x16x32_bf16 v[70:73], v[196:199], v[164:167], v[70:73]
	v_mfma_f32_16x16x32_bf16 v[74:77], v[196:199], v[168:171], v[74:77]
	s_waitcnt lgkmcnt(0)
	v_mfma_f32_16x16x32_bf16 v[78:81], v[200:203], v[152:155], v[78:81]
	v_mfma_f32_16x16x32_bf16 v[82:85], v[200:203], v[160:163], v[82:85]
	v_mfma_f32_16x16x32_bf16 v[86:89], v[200:203], v[164:167], v[86:89]
	v_mfma_f32_16x16x32_bf16 v[90:93], v[200:203], v[168:171], v[90:93]
.Lgjoin_g2:
	s_add_i32 s40, s39, 1
	s_cmp_lg_u32 s39, 2
	s_cselect_b32 s39, s40, 0
	s_add_u32 s0, s0, 64
	s_addc_u32 s1, s1, 0
	s_add_i32 s42, s42, 1
	s_cmpk_eq_i32 s0, 0x1000
	s_cbranch_scc0 .LBB0_249

; template <class AF, class EPI>
; DEV void gemm_tile256(AF aptr, const u16* Bt, int ldb, int K, EPI epi, char* smem) {
;     ...
;   auto stage = [&](int kt, int buf) {
;     char* SA = smem + buf * 24576;
;     char* SB = SA + 16384;
; #pragma unroll
;     for (int i = 0; i < 4; ++i) {
;       int bo = tid * 16 + i * 4096, r = bo >> 6, c = (bo & 63) >> 1;
;       __builtin_amdgcn_global_load_lds((const unsigned*)aptr(r, kt * 32 + c), (__attribute__((address_space(3))) unsigned*)(SA + bo), 16, 0, 0);
;     }
; #pragma unroll
;     for (int i = 0; i < 2; ++i) {
;       int bo = tid * 16 + i * 4096, r = bo >> 6, c = (bo & 63) >> 1;
;       __builtin_amdgcn_global_load_lds((const unsigned*)(Bt + (size_t)r * ldb + kt * 32 + c), (__attribute__((address_space(3))) unsigned*)(SB + bo), 16, 0, 0);
;     }
;   };
;   asm volatile("s_waitcnt vmcnt(0)" ::: "memory");
;   __syncthreads();
;   stage(0, 0);
;   stage(1, 1);
;   const unsigned lbase = (unsigned)(size_t)(const __attribute__((address_space(3))) char*)smem;
;   const unsigned aoff = lbase + (wr * 128 + fr) * 64 + fq * 16, boff = lbase + 16384 + (wc * 64 + fr) * 64 + fq * 16;
; __global__ void __launch_bounds__(256, 2) fwd_megakernel(Params p) {
;     ...
;   for (int jt = (bid >> 3); jt < 8 * 16; jt += (nb >> 3)) {
;     const int pn = jt >> 3, pm = (bid & 7) * 8 + (jt & 7), b = pm >> 3;
;     const u16* A = p.y + (size_t)pm * 256 * 2048;
;     const float* gt1 = p.mod + (size_t)b * 12288 + 4096 + pn * 128;
;     gemm_tile256([&](int r, int k) { return A + (size_t)r * 2048 + k; }, p.Wt_out + (size_t)pn * 128 * 2048, 2048, 2048,
.LBB0_1241:
	s_and_b32 s6, s3, 7
	s_lshl_b32 s6, s6, 19
	s_and_b32 s7, s24, 7
	s_add_i32 s25, s16, s6
	s_or_b32 s7, s7, s4
	v_mov_b32_e32 v144, v0
	s_lshl_b32 s28, s25, 1
	s_ashr_i32 s6, s24, 3
	s_lshl_b32 s7, s7, 20
	s_mov_b64 s[26:27], s[54:55]
	s_add_u32 s10, s26, s7
	v_ashrrev_i32_e32 v2, 2, v144
	v_lshlrev_b32_e32 v148, 4, v144
	v_ashrrev_i32_e32 v3, 31, v2
	s_addc_u32 s11, s27, 0
	s_ashr_i32 s7, s6, 31
	v_lshlrev_b64 v[2:3], 12, v[2:3]
	v_add_u32_e32 v10, 0x1000, v148
	s_lshl_b64 s[8:9], s[6:7], 19
	v_lshl_add_u64 v[4:5], s[10:11], 0, v[2:3]
	v_and_b32_e32 v134, 48, v148
	v_and_b32_e32 v253, 32, v144
	v_xor_b32_e32 v134, v134, v253
	v_readfirstlane_b32 s7, v148
	v_ashrrev_i32_e32 v6, 6, v10
	v_add_u32_e32 v14, 0x2000, v148
	v_lshl_add_u64 v[4:5], v[4:5], 0, v[134:135]
	s_mov_b32 m0, s7
	v_ashrrev_i32_e32 v7, 31, v6
	v_readfirstlane_b32 s7, v10
	v_ashrrev_i32_e32 v10, 6, v14
	v_add_u32_e32 v18, 0x3000, v148
	v_readlane_b32 s36, v254, 4
	s_waitcnt vmcnt(0)
	s_barrier
; template <class AF, class EPI>
; DEV void gemm_tile256(AF aptr, const u16* Bt, int ldb, int K, EPI epi, char* smem) {
;     ...
;   auto stage = [&](int kt, int buf) {
;     char* SA = smem + buf * 24576;
;     char* SB = SA + 16384;
; #pragma unroll
;     for (int i = 0; i < 4; ++i) {
;       int bo = tid * 16 + i * 4096, r = bo >> 6, c = (bo & 63) >> 1;
;       __builtin_amdgcn_global_load_lds((const unsigned*)aptr(r, kt * 32 + c), (__attribute__((address_space(3))) unsigned*)(SA + bo), 16, 0, 0);
;     }
; #pragma unroll
;     for (int i = 0; i < 2; ++i) {
;       int bo = tid * 16 + i * 4096, r = bo >> 6, c = (bo & 63) >> 1;
;       __builtin_amdgcn_global_load_lds((const unsigned*)(Bt + (size_t)r * ldb + kt * 32 + c), (__attribute__((address_space(3))) unsigned*)(SB + bo), 16, 0, 0);
;     }
;   };
;   asm volatile("s_waitcnt vmcnt(0)" ::: "memory");
;   __syncthreads();
;   stage(0, 0);
;   stage(1, 1);
;   const unsigned lbase = (unsigned)(size_t)(const __attribute__((address_space(3))) char*)smem;
;   const unsigned aoff = lbase + (wr * 128 + fr) * 64 + fq * 16, boff = lbase + 16384 + (wc * 64 + fr) * 64 + fq * 16;
	global_load_lds_dwordx4 v[4:5], off
	v_lshlrev_b64 v[6:7], 12, v[6:7]
	s_mov_b32 m0, s7
	v_ashrrev_i32_e32 v11, 31, v10
	v_readfirstlane_b32 s7, v14
	v_ashrrev_i32_e32 v14, 6, v18
	v_readlane_b32 s48, v254, 16
	v_lshl_add_u64 v[8:9], s[10:11], 0, v[6:7]
	v_lshlrev_b64 v[10:11], 12, v[10:11]
	v_ashrrev_i32_e32 v15, 31, v14
	v_readlane_b32 s49, v254, 17
	s_add_u32 s26, s48, s8
	v_lshl_add_u64 v[8:9], v[8:9], 0, v[134:135]
	v_lshl_add_u64 v[12:13], s[10:11], 0, v[10:11]
	v_lshlrev_b64 v[14:15], 12, v[14:15]
	s_addc_u32 s27, s49, s9
	global_load_lds_dwordx4 v[8:9], off
	v_lshl_add_u64 v[12:13], v[12:13], 0, v[134:135]
	s_mov_b32 m0, s7
	v_lshl_add_u64 v[16:17], s[10:11], 0, v[14:15]
	v_readfirstlane_b32 s7, v18
	v_add_u32_e32 v20, 0x4000, v148
	global_load_lds_dwordx4 v[12:13], off
	v_lshl_add_u64 v[16:17], v[16:17], 0, v[134:135]
	s_mov_b32 m0, s7
	v_lshl_add_u64 v[18:19], s[26:27], 0, v[2:3]
	v_readfirstlane_b32 s7, v20
	v_add_u32_e32 v22, 0x5000, v148
	global_load_lds_dwordx4 v[16:17], off
	v_lshl_add_u64 v[18:19], v[18:19], 0, v[134:135]
	s_mov_b32 m0, s7
	v_lshl_add_u64 v[20:21], s[26:27], 0, v[6:7]
	v_readfirstlane_b32 s7, v22
	v_add_u32_e32 v22, 0x6000, v148
	global_load_lds_dwordx4 v[18:19], off
	v_lshl_add_u64 v[20:21], v[20:21], 0, v[134:135]
	s_mov_b32 m0, s7
	v_readfirstlane_b32 s7, v22
	global_load_lds_dwordx4 v[20:21], off
	v_lshl_add_u64 v[4:5], v[4:5], 0, 64
	s_mov_b32 m0, s7
	s_add_u32 s10, s14, s28
	global_load_lds_dwordx4 v[4:5], off
	v_lshl_add_u64 v[4:5], v[8:9], 0, 64
	v_add_u32_e32 v8, 0x7000, v148
	v_bfe_u32 v147, v144, 4, 2
	v_readfirstlane_b32 s7, v8
	v_add_u32_e32 v8, 0x8000, v148
	s_mov_b32 m0, s7
	v_readfirstlane_b32 s7, v8
	v_add_u32_e32 v8, 0x9000, v148
	global_load_lds_dwordx4 v[4:5], off
	v_lshl_add_u64 v[4:5], v[12:13], 0, 64
	s_mov_b32 m0, s7
	v_readfirstlane_b32 s7, v8
	v_add_u32_e32 v8, 0xa000, v148
	global_load_lds_dwordx4 v[4:5], off
	v_lshl_add_u64 v[4:5], v[16:17], 0, 64
	s_mov_b32 m0, s7
	v_readfirstlane_b32 s7, v8
	v_add_u32_e32 v8, 0xb000, v148
	global_load_lds_dwordx4 v[4:5], off
	v_lshl_add_u64 v[4:5], v[18:19], 0, 64
	s_mov_b32 m0, s7
	v_readfirstlane_b32 s7, v8
	global_load_lds_dwordx4 v[4:5], off
	v_lshl_add_u64 v[4:5], v[20:21], 0, 64
	s_mov_b32 m0, s7
	s_addc_u32 s11, s15, 0
	global_load_lds_dwordx4 v[4:5], off
	v_bfe_u32 v145, v144, 6, 1
	v_ashrrev_i32_e32 v1, 7, v144
	v_and_b32_e32 v146, 15, v144
	v_lshlrev_b32_e32 v8, 4, v147
	v_lshlrev_b32_e32 v253, 2, v144
	v_and_b32_e32 v253, 32, v253
	v_xor_b32_e32 v8, v8, v253
	s_add_u32 s8, s17, s8
	v_lshlrev_b32_e32 v4, 13, v1
	v_lshlrev_b32_e32 v5, 6, v146
	v_lshl_or_b32 v9, v145, 12, v8
	v_or_b32_e32 v2, v2, v134
	v_or_b32_e32 v6, v6, v134
	v_or_b32_e32 v10, v10, v134
	v_or_b32_e32 v14, v14, v134
	s_addc_u32 s9, s18, s9
	v_or3_b32 v149, v4, v8, v5
	v_or3_b32 v150, v5, v9, s19
	v_lshl_add_u64 v[130:131], s[10:11], 0, v[2:3]
	v_lshl_add_u64 v[132:133], s[10:11], 0, v[6:7]
	v_lshl_add_u64 v[136:137], s[10:11], 0, v[10:11]
	v_lshl_add_u64 v[138:139], s[10:11], 0, v[14:15]
	v_lshl_add_u64 v[140:141], s[8:9], 0, v[6:7]
	v_lshl_add_u64 v[142:143], s[8:9], 0, v[2:3]
	s_mov_b64 s[8:9], 0
	s_mov_b32 s7, 0
	s_mov_b32 s26, 0
	v_mov_b32_e32 v2, 0
	v_mov_b32_e32 v3, v135
	v_mov_b32_e32 v4, v135
	v_mov_b32_e32 v5, v135
	v_mov_b32_e32 v6, 0
	v_mov_b32_e32 v7, v135
	v_mov_b32_e32 v8, v135
	v_mov_b32_e32 v9, v135
	v_mov_b32_e32 v10, 0
	v_mov_b32_e32 v11, v135
	v_mov_b32_e32 v12, v135
	v_mov_b32_e32 v13, v135
	v_mov_b32_e32 v14, 0
	v_mov_b32_e32 v15, v135
	v_mov_b32_e32 v16, v135
	v_mov_b32_e32 v17, v135
	v_mov_b32_e32 v18, 0
	v_mov_b32_e32 v19, v135
	v_mov_b32_e32 v20, v135
	v_mov_b32_e32 v21, v135
	v_mov_b32_e32 v22, 0
	v_mov_b32_e32 v23, v135
	v_mov_b32_e32 v24, v135
	v_mov_b32_e32 v25, v135
	v_mov_b32_e32 v26, 0
	v_mov_b32_e32 v27, v135
	v_mov_b32_e32 v28, v135
	v_mov_b32_e32 v29, v135
	v_mov_b32_e32 v30, 0
	v_mov_b32_e32 v31, v135
	v_mov_b32_e32 v32, v135
	v_mov_b32_e32 v33, v135
	v_mov_b32_e32 v34, 0
	v_mov_b32_e32 v35, v135
	v_mov_b32_e32 v36, v135
	v_mov_b32_e32 v37, v135
	v_mov_b32_e32 v38, 0
	v_mov_b32_e32 v39, v135
	v_mov_b32_e32 v40, v135
	v_mov_b32_e32 v41, v135
	v_mov_b32_e32 v42, 0
	v_mov_b32_e32 v43, v135
	v_mov_b32_e32 v44, v135
	v_mov_b32_e32 v45, v135
	v_mov_b32_e32 v94, 0
	v_mov_b32_e32 v95, v135
	v_mov_b32_e32 v96, v135
	v_mov_b32_e32 v97, v135
	v_mov_b32_e32 v98, 0
	v_mov_b32_e32 v99, v135
	v_mov_b32_e32 v100, v135
	v_mov_b32_e32 v101, v135
	v_mov_b32_e32 v102, 0
	v_mov_b32_e32 v103, v135
	v_mov_b32_e32 v104, v135
	v_mov_b32_e32 v105, v135
	v_mov_b32_e32 v106, 0
	v_mov_b32_e32 v107, v135
	v_mov_b32_e32 v108, v135
	v_mov_b32_e32 v109, v135
	v_mov_b32_e32 v110, 0
	v_mov_b32_e32 v111, v135
	v_mov_b32_e32 v112, v135
	v_mov_b32_e32 v113, v135
	v_mov_b32_e32 v114, 0
	v_mov_b32_e32 v115, v135
	v_mov_b32_e32 v116, v135
	v_mov_b32_e32 v117, v135
	v_mov_b32_e32 v118, 0
	v_mov_b32_e32 v119, v135
	v_mov_b32_e32 v120, v135
	v_mov_b32_e32 v121, v135
	v_mov_b32_e32 v122, 0
	v_mov_b32_e32 v123, v135
	v_mov_b32_e32 v124, v135
	v_mov_b32_e32 v125, v135
	v_mov_b32_e32 v126, 0
	v_mov_b32_e32 v127, v135
	v_mov_b32_e32 v128, v135
	v_mov_b32_e32 v129, v135
	v_mov_b32_e32 v46, 0
	v_mov_b32_e32 v47, v135
	v_mov_b32_e32 v48, v135
	v_mov_b32_e32 v49, v135
	v_mov_b32_e32 v50, 0
	v_mov_b32_e32 v51, v135
	v_mov_b32_e32 v52, v135
	v_mov_b32_e32 v53, v135
	v_mov_b32_e32 v54, 0
	v_mov_b32_e32 v55, v135
	v_mov_b32_e32 v56, v135
	v_mov_b32_e32 v57, v135
	v_mov_b32_e32 v58, 0
	v_mov_b32_e32 v59, v135
	v_mov_b32_e32 v60, v135
	v_mov_b32_e32 v61, v135
	v_mov_b32_e32 v62, 0
	v_mov_b32_e32 v63, v135
	v_mov_b32_e32 v64, v135
	v_mov_b32_e32 v65, v135
	v_mov_b32_e32 v66, 0
	v_mov_b32_e32 v67, v135
	v_mov_b32_e32 v68, v135
	v_mov_b32_e32 v69, v135
	v_mov_b32_e32 v70, 0
	v_mov_b32_e32 v71, v135
	v_mov_b32_e32 v72, v135
	v_mov_b32_e32 v73, v135
	v_mov_b32_e32 v74, 0
	v_mov_b32_e32 v75, v135
	v_mov_b32_e32 v76, v135
	v_mov_b32_e32 v77, v135
	v_mov_b32_e32 v78, 0
	v_mov_b32_e32 v79, v135
	v_mov_b32_e32 v80, v135
	v_mov_b32_e32 v81, v135
	v_mov_b32_e32 v82, 0
	v_mov_b32_e32 v83, v135
	v_mov_b32_e32 v84, v135
	v_mov_b32_e32 v85, v135
	v_mov_b32_e32 v86, 0
	v_mov_b32_e32 v87, v135
	v_mov_b32_e32 v88, v135
	v_mov_b32_e32 v89, v135
	v_mov_b32_e32 v90, 0
	v_mov_b32_e32 v91, v135
	v_mov_b32_e32 v92, v135
	v_mov_b32_e32 v93, v135
	v_readlane_b32 s37, v254, 5
	v_readlane_b32 s38, v254, 6
	v_readlane_b32 s39, v254, 7
	v_readlane_b32 s40, v254, 8
	v_readlane_b32 s41, v254, 9
	v_readlane_b32 s42, v254, 10
	v_readlane_b32 s43, v254, 11
	v_readlane_b32 s44, v254, 12
	v_readlane_b32 s45, v254, 13
	v_readlane_b32 s46, v254, 14
	v_readlane_b32 s47, v254, 15
	v_readlane_b32 s50, v254, 18
	v_readlane_b32 s51, v254, 19
	s_branch .LBB0_1243

; template <class AF, class EPI>
; DEV void gemm_tile256(AF aptr, const u16* Bt, int ldb, int K, EPI epi, char* smem) {
;     ...
;   for (int t = 0; t < nk; ++t) {
;     if (t + 1 < nk) asm volatile("s_waitcnt vmcnt(6)" ::: "memory");
;     else asm volatile("s_waitcnt vmcnt(0)" ::: "memory");
;     __builtin_amdgcn_s_barrier();
;     if (t + 2 < nk) { int nb2 = buf + 2; if (nb2 >= 3) nb2 -= 3; stage(t + 2, nb2); }
;     const unsigned sa = aoff + buf * 24576, sb = boff + buf * 24576;
;     u32x4 a0, a1, a2, a3, a4, a5, a6, a7, b0, b1, b2, b3;
;     asm volatile("ds_read_b128 %0, %1" : "=v"(b0) : "v"(sb));
;     asm volatile("ds_read_b128 %0, %1 offset:1024" : "=v"(b1) : "v"(sb));
;     asm volatile("ds_read_b128 %0, %1 offset:2048" : "=v"(b2) : "v"(sb));
;     asm volatile("ds_read_b128 %0, %1 offset:3072" : "=v"(b3) : "v"(sb));
;     asm volatile("ds_read_b128 %0, %1" : "=v"(a0) : "v"(sa));
;     asm volatile("ds_read_b128 %0, %1 offset:1024" : "=v"(a1) : "v"(sa));
;     asm volatile("ds_read_b128 %0, %1 offset:2048" : "=v"(a2) : "v"(sa));
;     asm volatile("ds_read_b128 %0, %1 offset:3072" : "=v"(a3) : "v"(sa));
;     asm volatile("ds_read_b128 %0, %1 offset:4096" : "=v"(a4) : "v"(sa));
;     asm volatile("ds_read_b128 %0, %1 offset:5120" : "=v"(a5) : "v"(sa));
;     asm volatile("ds_read_b128 %0, %1 offset:6144" : "=v"(a6) : "v"(sa));
;     asm volatile("ds_read_b128 %0, %1 offset:7168" : "=v"(a7) : "v"(sa));
;     asm volatile("s_waitcnt lgkmcnt(4)" : "+v"(a0), "+v"(a1), "+v"(a2), "+v"(a3), "+v"(b0), "+v"(b1), "+v"(b2), "+v"(b3));
;     bf16x8 Bv[4];
;     Bv[0] = __builtin_bit_cast(bf16x8, b0); Bv[1] = __builtin_bit_cast(bf16x8, b1); Bv[2] = __builtin_bit_cast(bf16x8, b2); Bv[3] = __builtin_bit_cast(bf16x8, b3);
;     {
;       bf16x8 At[4];
;       At[0] = __builtin_bit_cast(bf16x8, a0); At[1] = __builtin_bit_cast(bf16x8, a1); At[2] = __builtin_bit_cast(bf16x8, a2); At[3] = __builtin_bit_cast(bf16x8, a3);
; #pragma unroll
;       for (int m = 0; m < 4; ++m)
; #pragma unroll
;         for (int n = 0; n < 4; ++n) acc[m][n] = __builtin_amdgcn_mfma_f32_16x16x32_bf16(At[m], Bv[n], acc[m][n], 0, 0, 0);
;     }
;     asm volatile("s_waitcnt lgkmcnt(0)" : "+v"(a4), "+v"(a5), "+v"(a6), "+v"(a7));
;     {
;       bf16x8 At[4];
.LBB0_1247:
	s_barrier
	s_mul_i32 s10, s7, 0x6000
	v_add_u32_e32 v134, s10, v149
	v_add_u32_e32 v151, s10, v150
	ds_read_b128 v[152:155], v151
	ds_read_b128 v[156:159], v151 offset:1024
	ds_read_b128 v[160:163], v151 offset:2048
	ds_read_b128 v[164:167], v151 offset:3072
	ds_read_b128 v[168:171], v134
	ds_read_b128 v[172:175], v134 offset:1024
	ds_read_b128 v[176:179], v134 offset:2048
	ds_read_b128 v[180:183], v134 offset:3072
	ds_read_b128 v[184:187], v134 offset:4096
	ds_read_b128 v[188:191], v134 offset:5120
	ds_read_b128 v[192:195], v134 offset:6144
	ds_read_b128 v[196:199], v134 offset:7168
	s_cmp_gt_u32 s26, 61
	s_cbranch_scc1 .Lgnodma_g1
	s_cmp_gt_i32 s7, 0
	s_cselect_b32 s10, -1, 2
	s_add_i32 s10, s10, s7
	s_mulk_i32 s10, 0x6000
	v_add_u32_e32 v252, s10, v148
	s_nop 0
	v_readfirstlane_b32 s10, v252
	s_waitcnt lgkmcnt(7)
	v_mfma_f32_16x16x32_bf16 v[126:129], v[168:171], v[152:155], v[126:129]
	v_mfma_f32_16x16x32_bf16 v[122:125], v[168:171], v[156:159], v[122:125]
	v_mfma_f32_16x16x32_bf16 v[118:121], v[168:171], v[160:163], v[118:121]
	v_mfma_f32_16x16x32_bf16 v[114:117], v[168:171], v[164:167], v[114:117]
	v_lshl_add_u64 v[250:251], v[130:131], 0, s[8:9]
	s_mov_b32 m0, s10
	s_nop 0
	global_load_lds_dwordx4 v[250:251], off
	s_waitcnt lgkmcnt(6)
	v_mfma_f32_16x16x32_bf16 v[110:113], v[172:175], v[152:155], v[110:113]
	v_mfma_f32_16x16x32_bf16 v[106:109], v[172:175], v[156:159], v[106:109]
	v_mfma_f32_16x16x32_bf16 v[102:105], v[172:175], v[160:163], v[102:105]
	v_mfma_f32_16x16x32_bf16 v[98:101], v[172:175], v[164:167], v[98:101]
	v_lshl_add_u64 v[250:251], v[132:133], 0, s[8:9]
	s_add_u32 m0, s10, 0x1000
	s_nop 0
	global_load_lds_dwordx4 v[250:251], off
	s_waitcnt lgkmcnt(5)
	v_mfma_f32_16x16x32_bf16 v[94:97], v[176:179], v[152:155], v[94:97]
	v_mfma_f32_16x16x32_bf16 v[42:45], v[176:179], v[156:159], v[42:45]
	v_mfma_f32_16x16x32_bf16 v[38:41], v[176:179], v[160:163], v[38:41]
	v_mfma_f32_16x16x32_bf16 v[34:37], v[176:179], v[164:167], v[34:37]
	v_lshl_add_u64 v[250:251], v[136:137], 0, s[8:9]
	s_add_u32 m0, s10, 0x2000
	s_nop 0
	global_load_lds_dwordx4 v[250:251], off
	s_waitcnt lgkmcnt(4)
	v_mfma_f32_16x16x32_bf16 v[30:33], v[180:183], v[152:155], v[30:33]
	v_mfma_f32_16x16x32_bf16 v[26:29], v[180:183], v[156:159], v[26:29]
	v_mfma_f32_16x16x32_bf16 v[22:25], v[180:183], v[160:163], v[22:25]
	v_mfma_f32_16x16x32_bf16 v[18:21], v[180:183], v[164:167], v[18:21]
	v_lshl_add_u64 v[250:251], v[138:139], 0, s[8:9]
	s_add_u32 m0, s10, 0x3000
	s_nop 0
	global_load_lds_dwordx4 v[250:251], off
	s_waitcnt lgkmcnt(3)
	v_mfma_f32_16x16x32_bf16 v[14:17], v[184:187], v[152:155], v[14:17]
	v_mfma_f32_16x16x32_bf16 v[10:13], v[184:187], v[156:159], v[10:13]
	v_mfma_f32_16x16x32_bf16 v[6:9], v[184:187], v[160:163], v[6:9]
	v_mfma_f32_16x16x32_bf16 v[2:5], v[184:187], v[164:167], v[2:5]
	v_lshl_add_u64 v[250:251], v[142:143], 0, s[8:9]
	s_add_u32 m0, s10, 0x4000
	s_nop 0
	global_load_lds_dwordx4 v[250:251], off
	s_waitcnt lgkmcnt(2)
	v_mfma_f32_16x16x32_bf16 v[46:49], v[188:191], v[152:155], v[46:49]
	v_mfma_f32_16x16x32_bf16 v[50:53], v[188:191], v[156:159], v[50:53]
	v_mfma_f32_16x16x32_bf16 v[54:57], v[188:191], v[160:163], v[54:57]
	v_mfma_f32_16x16x32_bf16 v[58:61], v[188:191], v[164:167], v[58:61]
	v_lshl_add_u64 v[250:251], v[140:141], 0, s[8:9]
	s_add_u32 m0, s10, 0x5000
	s_nop 0
	global_load_lds_dwordx4 v[250:251], off
	s_waitcnt lgkmcnt(1)
	v_mfma_f32_16x16x32_bf16 v[62:65], v[192:195], v[152:155], v[62:65]
	v_mfma_f32_16x16x32_bf16 v[66:69], v[192:195], v[156:159], v[66:69]
	v_mfma_f32_16x16x32_bf16 v[70:73], v[192:195], v[160:163], v[70:73]
	v_mfma_f32_16x16x32_bf16 v[74:77], v[192:195], v[164:167], v[74:77]
	s_waitcnt lgkmcnt(0)
	v_mfma_f32_16x16x32_bf16 v[78:81], v[196:199], v[152:155], v[78:81]
	v_mfma_f32_16x16x32_bf16 v[82:85], v[196:199], v[156:159], v[82:85]
	v_mfma_f32_16x16x32_bf16 v[86:89], v[196:199], v[160:163], v[86:89]
	v_mfma_f32_16x16x32_bf16 v[90:93], v[196:199], v[164:167], v[90:93]
	s_branch .Lgjoin_g1
.Lgnodma_g1:
	s_waitcnt lgkmcnt(7)
	v_mfma_f32_16x16x32_bf16 v[126:129], v[168:171], v[152:155], v[126:129]
	v_mfma_f32_16x16x32_bf16 v[122:125], v[168:171], v[156:159], v[122:125]
	v_mfma_f32_16x16x32_bf16 v[118:121], v[168:171], v[160:163], v[118:121]
	v_mfma_f32_16x16x32_bf16 v[114:117], v[168:171], v[164:167], v[114:117]
	s_waitcnt lgkmcnt(6)
	v_mfma_f32_16x16x32_bf16 v[110:113], v[172:175], v[152:155], v[110:113]
	v_mfma_f32_16x16x32_bf16 v[106:109], v[172:175], v[156:159], v[106:109]
	v_mfma_f32_16x16x32_bf16 v[102:105], v[172:175], v[160:163], v[102:105]
	v_mfma_f32_16x16x32_bf16 v[98:101], v[172:175], v[164:167], v[98:101]
	s_waitcnt lgkmcnt(5)
	v_mfma_f32_16x16x32_bf16 v[94:97], v[176:179], v[152:155], v[94:97]
	v_mfma_f32_16x16x32_bf16 v[42:45], v[176:179], v[156:159], v[42:45]
	v_mfma_f32_16x16x32_bf16 v[38:41], v[176:179], v[160:163], v[38:41]
	v_mfma_f32_16x16x32_bf16 v[34:37], v[176:179], v[164:167], v[34:37]
	s_waitcnt lgkmcnt(4)
	v_mfma_f32_16x16x32_bf16 v[30:33], v[180:183], v[152:155], v[30:33]
	v_mfma_f32_16x16x32_bf16 v[26:29], v[180:183], v[156:159], v[26:29]
	v_mfma_f32_16x16x32_bf16 v[22:25], v[180:183], v[160:163], v[22:25]
	v_mfma_f32_16x16x32_bf16 v[18:21], v[180:183], v[164:167], v[18:21]
	s_waitcnt lgkmcnt(3)
	v_mfma_f32_16x16x32_bf16 v[14:17], v[184:187], v[152:155], v[14:17]
	v_mfma_f32_16x16x32_bf16 v[10:13], v[184:187], v[156:159], v[10:13]
	v_mfma_f32_16x16x32_bf16 v[6:9], v[184:187], v[160:163], v[6:9]
	v_mfma_f32_16x16x32_bf16 v[2:5], v[184:187], v[164:167], v[2:5]
	s_waitcnt lgkmcnt(2)
	v_mfma_f32_16x16x32_bf16 v[46:49], v[188:191], v[152:155], v[46:49]
	v_mfma_f32_16x16x32_bf16 v[50:53], v[188:191], v[156:159], v[50:53]
	v_mfma_f32_16x16x32_bf16 v[54:57], v[188:191], v[160:163], v[54:57]
	v_mfma_f32_16x16x32_bf16 v[58:61], v[188:191], v[164:167], v[58:61]
	s_waitcnt lgkmcnt(1)
	v_mfma_f32_16x16x32_bf16 v[62:65], v[192:195], v[152:155], v[62:65]
	v_mfma_f32_16x16x32_bf16 v[66:69], v[192:195], v[156:159], v[66:69]
	v_mfma_f32_16x16x32_bf16 v[70:73], v[192:195], v[160:163], v[70:73]
	v_mfma_f32_16x16x32_bf16 v[74:77], v[192:195], v[164:167], v[74:77]
	s_waitcnt lgkmcnt(0)
	v_mfma_f32_16x16x32_bf16 v[78:81], v[196:199], v[152:155], v[78:81]
	v_mfma_f32_16x16x32_bf16 v[82:85], v[196:199], v[156:159], v[82:85]
	v_mfma_f32_16x16x32_bf16 v[86:89], v[196:199], v[160:163], v[86:89]
	v_mfma_f32_16x16x32_bf16 v[90:93], v[196:199], v[164:167], v[90:93]
.Lgjoin_g1:
	s_add_i32 s10, s7, 1
	s_cmp_lg_u32 s7, 2
	s_cselect_b32 s7, s10, 0
	s_add_u32 s8, s8, 64
	s_addc_u32 s9, s9, 0
	s_add_i32 s26, s26, 1
	s_cmpk_eq_i32 s8, 0x1000
	s_cbranch_scc0 .LBB0_1243

; DEV int ltid() { int t = threadIdx.x; asm volatile("" : "+v"(t)); return t; }
; DEV void ph_adaln_row(const float* xin, const float* g, const float* mod, int sh_off, int sc_off, u16* hout, int row) {
;   const int lane = ltid() & 63, b = row >> 11;
;   const float* xr = xin + (size_t)row * 2048;
;   float4 v[8];
;   float ss = 0.f;
; #pragma unroll
;   for (int i = 0; i < 8; ++i) {
;     v[i] = *(const float4*)(xr + i * 256 + lane * 4);
;     ss += v[i].x * v[i].x + v[i].y * v[i].y + v[i].z * v[i].z + v[i].w * v[i].w;
;   }
;   ss = wave_sum(ss);
;   const float rstd = rsqrtf(ss * (1.f / 2048.f) + 1e-6f);
;   const float* mb = mod + (size_t)b * 12288;
; #pragma unroll
;   for (int i = 0; i < 8; ++i) {
;     int col = i * 256 + lane * 4;
;     float4 g4 = *(const float4*)(g + col);
;     float4 sc = *(const float4*)(mb + sc_off + col);
;     float4 sh = *(const float4*)(mb + sh_off + col);
; __global__ void __launch_bounds__(256, 2) fwd_megakernel(Params p) {
;     ...
;   for (int row = bid * 4 + wid; row < T_; row += nb * 4) ph_adaln_row(p.out, p.norm_ffn_g, p.mod, 6144, 8192, p.h, row);
.LBB0_1310:
	s_or_b64 exec, exec, s[6:7]
	v_mov_b32_e32 v1, v0
	s_waitcnt lgkmcnt(0)
	s_barrier
	s_movk_i32 s2, 0x4000
	v_ashrrev_i32_e32 v2, 6, v1
	v_add_u32_e32 v1, s84, v2
	v_cmp_gt_i32_e32 vcc, s2, v1
	s_and_saveexec_b64 s[6:7], vcc
	s_cbranch_execz .LBB0_1313
	v_and_b32_e32 v2, 63, v0
	v_lshrrev_b32_e32 v3, 6, v0
	v_lshlrev_b32_e32 v235, 4, v2
	v_lshlrev_b32_e32 v237, 3, v2
	v_readfirstlane_b32 s17, v3
	v_readlane_b32 s12, v254, 0
	v_add_u32_e32 v236, 0x1000, v235
	v_add_u32_e32 v238, 0x8000, v235
	v_add_u32_e32 v239, 0x9000, v235
	v_add_u32_e32 v240, 0x6000, v235
	v_add_u32_e32 v241, 0x7000, v235
	v_mov_b32_e32 v233, 0x358637bd
	v_lshrrev_b32_e32 v3, 3, v2
	v_and_b32_e32 v2, 7, v2
	v_lshlrev_b32_e32 v3, 20, v3
	v_lshl_or_b32 v242, v2, 3, v3
	v_add_u32_e32 v243, 0x800000, v242
	v_add_u32_e32 v244, 0x1000000, v242
	v_add_u32_e32 v245, 0x1800000, v242
	v_add_u32_e32 v246, 0x2000000, v242
	v_add_u32_e32 v247, 0x2800000, v242
	v_add_u32_e32 v248, 0x3000000, v242
	v_add_u32_e32 v249, 0x3800000, v242
	v_mov_b32_e32 v234, 0x800000
	s_lshl_b32 s12, s12, 2
	s_add_i32 s12, s12, s17
	s_lshl_b32 s13, s92, 2
	s_cmpk_lt_u32 s12, 0x4000
	s_cbranch_scc0 .Lad_end_p9
	global_load_dwordx4 v[194:197], v235, s[46:47]
	global_load_dwordx4 v[198:201], v235, s[46:47] offset:1024
	global_load_dwordx4 v[202:205], v235, s[46:47] offset:2048
	global_load_dwordx4 v[206:209], v235, s[46:47] offset:3072
	global_load_dwordx4 v[210:213], v236, s[46:47]
	global_load_dwordx4 v[214:217], v236, s[46:47] offset:1024
	global_load_dwordx4 v[218:221], v236, s[46:47] offset:2048
	global_load_dwordx4 v[222:225], v236, s[46:47] offset:3072
	v_readlane_b32 s2, v254, 12
	v_readlane_b32 s3, v254, 13
	s_lshl_b32 s17, s12, 13
	s_add_u32 s2, s2, s17
	s_addc_u32 s3, s3, 0
	s_lshr_b32 s17, s12, 11
	s_mul_i32 s17, s17, 0xc000
	s_add_u32 s8, s78, s17
	s_addc_u32 s9, s79, 0
	global_load_dwordx4 v[2:5], v235, s[2:3]
	global_load_dwordx4 v[6:9], v235, s[2:3] offset:1024
	global_load_dwordx4 v[10:13], v235, s[2:3] offset:2048
	global_load_dwordx4 v[14:17], v235, s[2:3] offset:3072
	global_load_dwordx4 v[18:21], v236, s[2:3]
	global_load_dwordx4 v[22:25], v236, s[2:3] offset:1024
	global_load_dwordx4 v[26:29], v236, s[2:3] offset:2048
	global_load_dwordx4 v[30:33], v236, s[2:3] offset:3072
	global_load_dwordx4 v[34:37], v238, s[8:9]
	global_load_dwordx4 v[38:41], v238, s[8:9] offset:1024
	global_load_dwordx4 v[42:45], v238, s[8:9] offset:2048
	global_load_dwordx4 v[46:49], v238, s[8:9] offset:3072
	global_load_dwordx4 v[50:53], v239, s[8:9]
	global_load_dwordx4 v[54:57], v239, s[8:9] offset:1024
	global_load_dwordx4 v[58:61], v239, s[8:9] offset:2048
	global_load_dwordx4 v[62:65], v239, s[8:9] offset:3072
	global_load_dwordx4 v[66:69], v240, s[8:9]
	global_load_dwordx4 v[70:73], v240, s[8:9] offset:1024
	global_load_dwordx4 v[74:77], v240, s[8:9] offset:2048
	global_load_dwordx4 v[78:81], v240, s[8:9] offset:3072
	global_load_dwordx4 v[82:85], v241, s[8:9]
	global_load_dwordx4 v[86:89], v241, s[8:9] offset:1024
	global_load_dwordx4 v[90:93], v241, s[8:9] offset:2048
	global_load_dwordx4 v[94:97], v241, s[8:9] offset:3072
.Lad_loop_p9:
	s_add_i32 s16, s12, s13
	s_cmpk_lt_u32 s16, 0x4000
	s_cbranch_scc0 .Lad_last_p9_0
	v_readlane_b32 s2, v254, 12
	v_readlane_b32 s3, v254, 13
	s_lshl_b32 s17, s16, 13
	s_add_u32 s2, s2, s17
	s_addc_u32 s3, s3, 0
	s_lshr_b32 s17, s16, 11
	s_mul_i32 s17, s17, 0xc000
	s_add_u32 s8, s78, s17
	s_addc_u32 s9, s79, 0
	global_load_dwordx4 v[98:101], v235, s[2:3]
	global_load_dwordx4 v[102:105], v235, s[2:3] offset:1024
	global_load_dwordx4 v[106:109], v235, s[2:3] offset:2048
	global_load_dwordx4 v[110:113], v235, s[2:3] offset:3072
	global_load_dwordx4 v[114:117], v236, s[2:3]
	global_load_dwordx4 v[118:121], v236, s[2:3] offset:1024
	global_load_dwordx4 v[122:125], v236, s[2:3] offset:2048
	global_load_dwordx4 v[126:129], v236, s[2:3] offset:3072
	global_load_dwordx4 v[130:133], v238, s[8:9]
	global_load_dwordx4 v[134:137], v238, s[8:9] offset:1024
	global_load_dwordx4 v[138:141], v238, s[8:9] offset:2048
	global_load_dwordx4 v[142:145], v238, s[8:9] offset:3072
	global_load_dwordx4 v[146:149], v239, s[8:9]
	global_load_dwordx4 v[150:153], v239, s[8:9] offset:1024
	global_load_dwordx4 v[154:157], v239, s[8:9] offset:2048
	global_load_dwordx4 v[158:161], v239, s[8:9] offset:3072
	global_load_dwordx4 v[162:165], v240, s[8:9]
	global_load_dwordx4 v[166:169], v240, s[8:9] offset:1024
	global_load_dwordx4 v[170:173], v240, s[8:9] offset:2048
	global_load_dwordx4 v[174:177], v240, s[8:9] offset:3072
	global_load_dwordx4 v[178:181], v241, s[8:9]
	global_load_dwordx4 v[182:185], v241, s[8:9] offset:1024
	global_load_dwordx4 v[186:189], v241, s[8:9] offset:2048
	global_load_dwordx4 v[190:193], v241, s[8:9] offset:3072
	s_waitcnt vmcnt(24)
; DEV unsigned pack2(float a, float b) { float2v v = {a, b}; return __builtin_bit_cast(unsigned, __builtin_convertvector(v, bf16x2v)); }
; DEV void ph_adaln_row(const float* xin, const float* g, const float* mod, int sh_off, int sc_off, u16* hout, int row) {
;     ...
;     ss += v[i].x * v[i].x + v[i].y * v[i].y + v[i].z * v[i].z + v[i].w * v[i].w;
;   }
;   ss = wave_sum(ss);
;   const float rstd = rsqrtf(ss * (1.f / 2048.f) + 1e-6f);
;   const float* mb = mod + (size_t)b * 12288;
; #pragma unroll
;   for (int i = 0; i < 8; ++i) {
;     int col = i * 256 + lane * 4;
;     float4 g4 = *(const float4*)(g + col);
;     float4 sc = *(const float4*)(mb + sc_off + col);
;     float4 sh = *(const float4*)(mb + sh_off + col);
;     float y0 = v[i].x * rstd * g4.x * (1.f + sc.x) + sh.x;
;     float y1 = v[i].y * rstd * g4.y * (1.f + sc.y) + sh.y;
;     float y2 = v[i].z * rstd * g4.z * (1.f + sc.z) + sh.z;
;     float y3 = v[i].w * rstd * g4.w * (1.f + sc.w) + sh.w;
;     u32x2 pk; pk[0] = pack2(y0, y1); pk[1] = pack2(y2, y3);
;     *(u32x2*)(hout + (size_t)row * 2048 + col) = pk;
;   }
	v_mul_f32_e32 v226, v2, v2
	v_mul_f32_e32 v227, v3, v3
	v_mul_f32_e32 v228, v4, v4
	v_mul_f32_e32 v229, v5, v5
	v_fmac_f32_e32 v226, v6, v6
	v_fmac_f32_e32 v227, v7, v7
	v_fmac_f32_e32 v228, v8, v8
	v_fmac_f32_e32 v229, v9, v9
	v_fmac_f32_e32 v226, v10, v10
	v_fmac_f32_e32 v227, v11, v11
	v_fmac_f32_e32 v228, v12, v12
	v_fmac_f32_e32 v229, v13, v13
	v_fmac_f32_e32 v226, v14, v14
	v_fmac_f32_e32 v227, v15, v15
	v_fmac_f32_e32 v228, v16, v16
	v_fmac_f32_e32 v229, v17, v17
	v_fmac_f32_e32 v226, v18, v18
	v_fmac_f32_e32 v227, v19, v19
	v_fmac_f32_e32 v228, v20, v20
	v_fmac_f32_e32 v229, v21, v21
	v_fmac_f32_e32 v226, v22, v22
	v_fmac_f32_e32 v227, v23, v23
	v_fmac_f32_e32 v228, v24, v24
	v_fmac_f32_e32 v229, v25, v25
	v_fmac_f32_e32 v226, v26, v26
	v_fmac_f32_e32 v227, v27, v27
	v_fmac_f32_e32 v228, v28, v28
	v_fmac_f32_e32 v229, v29, v29
	v_fmac_f32_e32 v226, v30, v30
	v_fmac_f32_e32 v227, v31, v31
	v_fmac_f32_e32 v228, v32, v32
	v_fmac_f32_e32 v229, v33, v33
	v_add_f32_e32 v226, v227, v226
	v_add_f32_e32 v228, v229, v228
	v_add_f32_e32 v226, v228, v226
	s_nop 1
	v_add_f32_dpp v226, v226, v226 quad_perm:[1,0,3,2] row_mask:0xf bank_mask:0xf bound_ctrl:1
	s_nop 1
	v_add_f32_dpp v226, v226, v226 quad_perm:[2,3,0,1] row_mask:0xf bank_mask:0xf bound_ctrl:1
	s_nop 1
	v_add_f32_dpp v226, v226, v226 row_half_mirror row_mask:0xf bank_mask:0xf bound_ctrl:1
	s_nop 1
	v_add_f32_dpp v226, v226, v226 row_mirror row_mask:0xf bank_mask:0xf bound_ctrl:1
	s_nop 1
	v_add_f32_dpp v226, v226, v226 row_bcast:15 row_mask:0xa bank_mask:0xf
	s_nop 1
	v_add_f32_dpp v226, v226, v226 row_bcast:31 row_mask:0xc bank_mask:0xf
	s_nop 0
	v_readlane_b32 s16, v226, 63
	s_nop 1
	v_mov_b32_e32 v230, s16
	v_fmamk_f32 v230, v230, 0x3a000000, v233
	v_mul_f32_e32 v231, 0x4b800000, v230
	v_cmp_lt_f32_e32 vcc, v230, v234
	s_nop 1
	v_cndmask_b32_e32 v230, v230, v231, vcc
	v_rsq_f32_e32 v230, v230
	s_nop 0
	v_mul_f32_e32 v231, 0x45800000, v230
	v_cndmask_b32_e32 v232, v230, v231, vcc
	v_mul_f32_e32 v2, v2, v232
	v_mul_f32_e32 v2, v194, v2
	v_add_f32_e32 v34, 1.0, v34
	v_fma_f32 v2, v34, v2, v66
	v_mul_f32_e32 v3, v3, v232
	v_mul_f32_e32 v3, v195, v3
	v_add_f32_e32 v35, 1.0, v35
	v_fma_f32 v3, v35, v3, v67
	v_mul_f32_e32 v4, v4, v232
	v_mul_f32_e32 v4, v196, v4
	v_add_f32_e32 v36, 1.0, v36
	v_fma_f32 v4, v36, v4, v68
	v_mul_f32_e32 v5, v5, v232
	v_mul_f32_e32 v5, v197, v5
	v_add_f32_e32 v37, 1.0, v37
	v_fma_f32 v5, v37, v5, v69
	v_mul_f32_e32 v6, v6, v232
	v_mul_f32_e32 v6, v198, v6
	v_add_f32_e32 v38, 1.0, v38
	v_fma_f32 v6, v38, v6, v70
	v_mul_f32_e32 v7, v7, v232
	v_mul_f32_e32 v7, v199, v7
	v_add_f32_e32 v39, 1.0, v39
	v_fma_f32 v7, v39, v7, v71
	v_mul_f32_e32 v8, v8, v232
	v_mul_f32_e32 v8, v200, v8
	v_add_f32_e32 v40, 1.0, v40
	v_fma_f32 v8, v40, v8, v72
	v_mul_f32_e32 v9, v9, v232
	v_mul_f32_e32 v9, v201, v9
	v_add_f32_e32 v41, 1.0, v41
	v_fma_f32 v9, v41, v9, v73
	v_mul_f32_e32 v10, v10, v232
	v_mul_f32_e32 v10, v202, v10
	v_add_f32_e32 v42, 1.0, v42
	v_fma_f32 v10, v42, v10, v74
	v_mul_f32_e32 v11, v11, v232
	v_mul_f32_e32 v11, v203, v11
	v_add_f32_e32 v43, 1.0, v43
	v_fma_f32 v11, v43, v11, v75
	v_mul_f32_e32 v12, v12, v232
	v_mul_f32_e32 v12, v204, v12
	v_add_f32_e32 v44, 1.0, v44
	v_fma_f32 v12, v44, v12, v76
	v_mul_f32_e32 v13, v13, v232
	v_mul_f32_e32 v13, v205, v13
	v_add_f32_e32 v45, 1.0, v45
	v_fma_f32 v13, v45, v13, v77
	v_mul_f32_e32 v14, v14, v232
	v_mul_f32_e32 v14, v206, v14
	v_add_f32_e32 v46, 1.0, v46
	v_fma_f32 v14, v46, v14, v78
	v_mul_f32_e32 v15, v15, v232
	v_mul_f32_e32 v15, v207, v15
	v_add_f32_e32 v47, 1.0, v47
	v_fma_f32 v15, v47, v15, v79
	v_mul_f32_e32 v16, v16, v232
	v_mul_f32_e32 v16, v208, v16
	v_add_f32_e32 v48, 1.0, v48
	v_fma_f32 v16, v48, v16, v80
	v_mul_f32_e32 v17, v17, v232
	v_mul_f32_e32 v17, v209, v17
	v_add_f32_e32 v49, 1.0, v49
	v_fma_f32 v17, v49, v17, v81
	v_mul_f32_e32 v18, v18, v232
	v_mul_f32_e32 v18, v210, v18
	v_add_f32_e32 v50, 1.0, v50
	v_fma_f32 v18, v50, v18, v82
	v_mul_f32_e32 v19, v19, v232
	v_mul_f32_e32 v19, v211, v19
	v_add_f32_e32 v51, 1.0, v51
	v_fma_f32 v19, v51, v19, v83
	v_mul_f32_e32 v20, v20, v232
	v_mul_f32_e32 v20, v212, v20
	v_add_f32_e32 v52, 1.0, v52
	v_fma_f32 v20, v52, v20, v84
	v_mul_f32_e32 v21, v21, v232
	v_mul_f32_e32 v21, v213, v21
	v_add_f32_e32 v53, 1.0, v53
	v_fma_f32 v21, v53, v21, v85
	v_mul_f32_e32 v22, v22, v232
	v_mul_f32_e32 v22, v214, v22
	v_add_f32_e32 v54, 1.0, v54
	v_fma_f32 v22, v54, v22, v86
	v_mul_f32_e32 v23, v23, v232
	v_mul_f32_e32 v23, v215, v23
	v_add_f32_e32 v55, 1.0, v55
	v_fma_f32 v23, v55, v23, v87
	v_mul_f32_e32 v24, v24, v232
	v_mul_f32_e32 v24, v216, v24
	v_add_f32_e32 v56, 1.0, v56
	v_fma_f32 v24, v56, v24, v88
	v_mul_f32_e32 v25, v25, v232
	v_mul_f32_e32 v25, v217, v25
	v_add_f32_e32 v57, 1.0, v57
	v_fma_f32 v25, v57, v25, v89
	v_mul_f32_e32 v26, v26, v232
	v_mul_f32_e32 v26, v218, v26
	v_add_f32_e32 v58, 1.0, v58
	v_fma_f32 v26, v58, v26, v90
	v_mul_f32_e32 v27, v27, v232
	v_mul_f32_e32 v27, v219, v27
	v_add_f32_e32 v59, 1.0, v59
	v_fma_f32 v27, v59, v27, v91
	v_mul_f32_e32 v28, v28, v232
	v_mul_f32_e32 v28, v220, v28
	v_add_f32_e32 v60, 1.0, v60
	v_fma_f32 v28, v60, v28, v92
	v_mul_f32_e32 v29, v29, v232
	v_mul_f32_e32 v29, v221, v29
	v_add_f32_e32 v61, 1.0, v61
	v_fma_f32 v29, v61, v29, v93
	v_mul_f32_e32 v30, v30, v232
	v_mul_f32_e32 v30, v222, v30
	v_add_f32_e32 v62, 1.0, v62
	v_fma_f32 v30, v62, v30, v94
	v_mul_f32_e32 v31, v31, v232
	v_mul_f32_e32 v31, v223, v31
	v_add_f32_e32 v63, 1.0, v63
	v_fma_f32 v31, v63, v31, v95
	v_mul_f32_e32 v32, v32, v232
	v_mul_f32_e32 v32, v224, v32
	v_add_f32_e32 v64, 1.0, v64
	v_fma_f32 v32, v64, v32, v96
	v_mul_f32_e32 v33, v33, v232
	v_mul_f32_e32 v33, v225, v33
	v_add_f32_e32 v65, 1.0, v65
	v_fma_f32 v33, v65, v33, v97
	v_cvt_pk_bf16_f32 v2, v2, v3
	v_cvt_pk_bf16_f32 v3, v4, v5
	v_cvt_pk_bf16_f32 v4, v6, v7
	v_cvt_pk_bf16_f32 v5, v8, v9
	v_cvt_pk_bf16_f32 v6, v10, v11
	v_cvt_pk_bf16_f32 v7, v12, v13
	v_cvt_pk_bf16_f32 v8, v14, v15
	v_cvt_pk_bf16_f32 v9, v16, v17
	v_cvt_pk_bf16_f32 v10, v18, v19
	v_cvt_pk_bf16_f32 v11, v20, v21
	v_cvt_pk_bf16_f32 v12, v22, v23
	v_cvt_pk_bf16_f32 v13, v24, v25
	v_cvt_pk_bf16_f32 v14, v26, v27
	v_cvt_pk_bf16_f32 v15, v28, v29
	v_cvt_pk_bf16_f32 v16, v30, v31
	v_cvt_pk_bf16_f32 v17, v32, v33
	s_lshl_b32 s17, s12, 6
	s_add_u32 s10, s80, s17
	s_addc_u32 s11, s81, 0
	global_store_dwordx2 v242, v[2:3], s[10:11]
	global_store_dwordx2 v243, v[4:5], s[10:11]
	global_store_dwordx2 v244, v[6:7], s[10:11]
	global_store_dwordx2 v245, v[8:9], s[10:11]
	global_store_dwordx2 v246, v[10:11], s[10:11]
	global_store_dwordx2 v247, v[12:13], s[10:11]
	global_store_dwordx2 v248, v[14:15], s[10:11]
	global_store_dwordx2 v249, v[16:17], s[10:11]
	s_add_i32 s12, s12, s13
	s_add_i32 s16, s12, s13
	s_cmpk_lt_u32 s16, 0x4000
	s_cbranch_scc0 .Lad_last_p9_1
; DEV void ph_adaln_row(const float* xin, const float* g, const float* mod, int sh_off, int sc_off, u16* hout, int row) {
;     ...
; #pragma unroll
;   for (int i = 0; i < 8; ++i) {
;     v[i] = *(const float4*)(xr + i * 256 + lane * 4);
;     ss += v[i].x * v[i].x + v[i].y * v[i].y + v[i].z * v[i].z + v[i].w * v[i].w;
;   }
;   ss = wave_sum(ss);
;   const float rstd = rsqrtf(ss * (1.f / 2048.f) + 1e-6f);
;   const float* mb = mod + (size_t)b * 12288;
; #pragma unroll
;   for (int i = 0; i < 8; ++i) {
;     int col = i * 256 + lane * 4;
;     float4 g4 = *(const float4*)(g + col);
;     float4 sc = *(const float4*)(mb + sc_off + col);
;     float4 sh = *(const float4*)(mb + sh_off + col);
;     float y0 = v[i].x * rstd * g4.x * (1.f + sc.x) + sh.x;
;     float y1 = v[i].y * rstd * g4.y * (1.f + sc.y) + sh.y;
;     float y2 = v[i].z * rstd * g4.z * (1.f + sc.z) + sh.z;
;     float y3 = v[i].w * rstd * g4.w * (1.f + sc.w) + sh.w;
	v_readlane_b32 s2, v254, 12
	v_readlane_b32 s3, v254, 13
	s_lshl_b32 s17, s16, 13
	s_add_u32 s2, s2, s17
	s_addc_u32 s3, s3, 0
	s_lshr_b32 s17, s16, 11
	s_mul_i32 s17, s17, 0xc000
	s_add_u32 s8, s78, s17
	s_addc_u32 s9, s79, 0
	global_load_dwordx4 v[2:5], v235, s[2:3]
	global_load_dwordx4 v[6:9], v235, s[2:3] offset:1024
	global_load_dwordx4 v[10:13], v235, s[2:3] offset:2048
	global_load_dwordx4 v[14:17], v235, s[2:3] offset:3072
	global_load_dwordx4 v[18:21], v236, s[2:3]
	global_load_dwordx4 v[22:25], v236, s[2:3] offset:1024
	global_load_dwordx4 v[26:29], v236, s[2:3] offset:2048
	global_load_dwordx4 v[30:33], v236, s[2:3] offset:3072
	global_load_dwordx4 v[34:37], v238, s[8:9]
	global_load_dwordx4 v[38:41], v238, s[8:9] offset:1024
	global_load_dwordx4 v[42:45], v238, s[8:9] offset:2048
	global_load_dwordx4 v[46:49], v238, s[8:9] offset:3072
	global_load_dwordx4 v[50:53], v239, s[8:9]
	global_load_dwordx4 v[54:57], v239, s[8:9] offset:1024
	global_load_dwordx4 v[58:61], v239, s[8:9] offset:2048
	global_load_dwordx4 v[62:65], v239, s[8:9] offset:3072
	global_load_dwordx4 v[66:69], v240, s[8:9]
	global_load_dwordx4 v[70:73], v240, s[8:9] offset:1024
	global_load_dwordx4 v[74:77], v240, s[8:9] offset:2048
	global_load_dwordx4 v[78:81], v240, s[8:9] offset:3072
	global_load_dwordx4 v[82:85], v241, s[8:9]
	global_load_dwordx4 v[86:89], v241, s[8:9] offset:1024
	global_load_dwordx4 v[90:93], v241, s[8:9] offset:2048
	global_load_dwordx4 v[94:97], v241, s[8:9] offset:3072
	s_waitcnt vmcnt(24)
	v_mul_f32_e32 v226, v98, v98
	v_mul_f32_e32 v227, v99, v99
	v_mul_f32_e32 v228, v100, v100
	v_mul_f32_e32 v229, v101, v101
	v_fmac_f32_e32 v226, v102, v102
	v_fmac_f32_e32 v227, v103, v103
	v_fmac_f32_e32 v228, v104, v104
	v_fmac_f32_e32 v229, v105, v105
	v_fmac_f32_e32 v226, v106, v106
	v_fmac_f32_e32 v227, v107, v107
	v_fmac_f32_e32 v228, v108, v108
	v_fmac_f32_e32 v229, v109, v109
	v_fmac_f32_e32 v226, v110, v110
	v_fmac_f32_e32 v227, v111, v111
	v_fmac_f32_e32 v228, v112, v112
	v_fmac_f32_e32 v229, v113, v113
	v_fmac_f32_e32 v226, v114, v114
	v_fmac_f32_e32 v227, v115, v115
	v_fmac_f32_e32 v228, v116, v116
	v_fmac_f32_e32 v229, v117, v117
	v_fmac_f32_e32 v226, v118, v118
	v_fmac_f32_e32 v227, v119, v119
	v_fmac_f32_e32 v228, v120, v120
	v_fmac_f32_e32 v229, v121, v121
	v_fmac_f32_e32 v226, v122, v122
	v_fmac_f32_e32 v227, v123, v123
	v_fmac_f32_e32 v228, v124, v124
	v_fmac_f32_e32 v229, v125, v125
	v_fmac_f32_e32 v226, v126, v126
	v_fmac_f32_e32 v227, v127, v127
	v_fmac_f32_e32 v228, v128, v128
	v_fmac_f32_e32 v229, v129, v129
	v_add_f32_e32 v226, v227, v226
	v_add_f32_e32 v228, v229, v228
	v_add_f32_e32 v226, v228, v226
	s_nop 1
	v_add_f32_dpp v226, v226, v226 quad_perm:[1,0,3,2] row_mask:0xf bank_mask:0xf bound_ctrl:1
	s_nop 1
	v_add_f32_dpp v226, v226, v226 quad_perm:[2,3,0,1] row_mask:0xf bank_mask:0xf bound_ctrl:1
	s_nop 1
	v_add_f32_dpp v226, v226, v226 row_half_mirror row_mask:0xf bank_mask:0xf bound_ctrl:1
	s_nop 1
	v_add_f32_dpp v226, v226, v226 row_mirror row_mask:0xf bank_mask:0xf bound_ctrl:1
	s_nop 1
	v_add_f32_dpp v226, v226, v226 row_bcast:15 row_mask:0xa bank_mask:0xf
	s_nop 1
	v_add_f32_dpp v226, v226, v226 row_bcast:31 row_mask:0xc bank_mask:0xf
	s_nop 0
	v_readlane_b32 s16, v226, 63
	s_nop 1
	v_mov_b32_e32 v230, s16
	v_fmamk_f32 v230, v230, 0x3a000000, v233
	v_mul_f32_e32 v231, 0x4b800000, v230
	v_cmp_lt_f32_e32 vcc, v230, v234
	s_nop 1
	v_cndmask_b32_e32 v230, v230, v231, vcc
	v_rsq_f32_e32 v230, v230
	s_nop 0
	v_mul_f32_e32 v231, 0x45800000, v230
	v_cndmask_b32_e32 v232, v230, v231, vcc
	v_mul_f32_e32 v98, v98, v232
	v_mul_f32_e32 v98, v194, v98
	v_add_f32_e32 v130, 1.0, v130
	v_fma_f32 v98, v130, v98, v162
	v_mul_f32_e32 v99, v99, v232
	v_mul_f32_e32 v99, v195, v99
	v_add_f32_e32 v131, 1.0, v131
	v_fma_f32 v99, v131, v99, v163
	v_mul_f32_e32 v100, v100, v232
	v_mul_f32_e32 v100, v196, v100
	v_add_f32_e32 v132, 1.0, v132
	v_fma_f32 v100, v132, v100, v164
	v_mul_f32_e32 v101, v101, v232
	v_mul_f32_e32 v101, v197, v101
	v_add_f32_e32 v133, 1.0, v133
	v_fma_f32 v101, v133, v101, v165
	v_mul_f32_e32 v102, v102, v232
	v_mul_f32_e32 v102, v198, v102
	v_add_f32_e32 v134, 1.0, v134
	v_fma_f32 v102, v134, v102, v166
	v_mul_f32_e32 v103, v103, v232
	v_mul_f32_e32 v103, v199, v103
	v_add_f32_e32 v135, 1.0, v135
	v_fma_f32 v103, v135, v103, v167
	v_mul_f32_e32 v104, v104, v232
	v_mul_f32_e32 v104, v200, v104
	v_add_f32_e32 v136, 1.0, v136
	v_fma_f32 v104, v136, v104, v168
	v_mul_f32_e32 v105, v105, v232
	v_mul_f32_e32 v105, v201, v105
	v_add_f32_e32 v137, 1.0, v137
	v_fma_f32 v105, v137, v105, v169
	v_mul_f32_e32 v106, v106, v232
	v_mul_f32_e32 v106, v202, v106
	v_add_f32_e32 v138, 1.0, v138
	v_fma_f32 v106, v138, v106, v170
	v_mul_f32_e32 v107, v107, v232
	v_mul_f32_e32 v107, v203, v107
	v_add_f32_e32 v139, 1.0, v139
	v_fma_f32 v107, v139, v107, v171
	v_mul_f32_e32 v108, v108, v232
	v_mul_f32_e32 v108, v204, v108
	v_add_f32_e32 v140, 1.0, v140
	v_fma_f32 v108, v140, v108, v172
	v_mul_f32_e32 v109, v109, v232
	v_mul_f32_e32 v109, v205, v109
	v_add_f32_e32 v141, 1.0, v141
	v_fma_f32 v109, v141, v109, v173
	v_mul_f32_e32 v110, v110, v232
	v_mul_f32_e32 v110, v206, v110
	v_add_f32_e32 v142, 1.0, v142
	v_fma_f32 v110, v142, v110, v174
	v_mul_f32_e32 v111, v111, v232
	v_mul_f32_e32 v111, v207, v111
	v_add_f32_e32 v143, 1.0, v143
	v_fma_f32 v111, v143, v111, v175
	v_mul_f32_e32 v112, v112, v232
	v_mul_f32_e32 v112, v208, v112
	v_add_f32_e32 v144, 1.0, v144
	v_fma_f32 v112, v144, v112, v176
	v_mul_f32_e32 v113, v113, v232
	v_mul_f32_e32 v113, v209, v113
	v_add_f32_e32 v145, 1.0, v145
	v_fma_f32 v113, v145, v113, v177
	v_mul_f32_e32 v114, v114, v232
; DEV unsigned pack2(float a, float b) { float2v v = {a, b}; return __builtin_bit_cast(unsigned, __builtin_convertvector(v, bf16x2v)); }
; DEV void ph_adaln_row(const float* xin, const float* g, const float* mod, int sh_off, int sc_off, u16* hout, int row) {
;     ...
;     float y0 = v[i].x * rstd * g4.x * (1.f + sc.x) + sh.x;
;     float y1 = v[i].y * rstd * g4.y * (1.f + sc.y) + sh.y;
;     float y2 = v[i].z * rstd * g4.z * (1.f + sc.z) + sh.z;
;     float y3 = v[i].w * rstd * g4.w * (1.f + sc.w) + sh.w;
;     u32x2 pk; pk[0] = pack2(y0, y1); pk[1] = pack2(y2, y3);
;     *(u32x2*)(hout + (size_t)row * 2048 + col) = pk;
;   }
	v_mul_f32_e32 v114, v210, v114
	v_add_f32_e32 v146, 1.0, v146
	v_fma_f32 v114, v146, v114, v178
	v_mul_f32_e32 v115, v115, v232
	v_mul_f32_e32 v115, v211, v115
	v_add_f32_e32 v147, 1.0, v147
	v_fma_f32 v115, v147, v115, v179
	v_mul_f32_e32 v116, v116, v232
	v_mul_f32_e32 v116, v212, v116
	v_add_f32_e32 v148, 1.0, v148
	v_fma_f32 v116, v148, v116, v180
	v_mul_f32_e32 v117, v117, v232
	v_mul_f32_e32 v117, v213, v117
	v_add_f32_e32 v149, 1.0, v149
	v_fma_f32 v117, v149, v117, v181
	v_mul_f32_e32 v118, v118, v232
	v_mul_f32_e32 v118, v214, v118
	v_add_f32_e32 v150, 1.0, v150
	v_fma_f32 v118, v150, v118, v182
	v_mul_f32_e32 v119, v119, v232
	v_mul_f32_e32 v119, v215, v119
	v_add_f32_e32 v151, 1.0, v151
	v_fma_f32 v119, v151, v119, v183
	v_mul_f32_e32 v120, v120, v232
	v_mul_f32_e32 v120, v216, v120
	v_add_f32_e32 v152, 1.0, v152
	v_fma_f32 v120, v152, v120, v184
	v_mul_f32_e32 v121, v121, v232
	v_mul_f32_e32 v121, v217, v121
	v_add_f32_e32 v153, 1.0, v153
	v_fma_f32 v121, v153, v121, v185
	v_mul_f32_e32 v122, v122, v232
	v_mul_f32_e32 v122, v218, v122
	v_add_f32_e32 v154, 1.0, v154
	v_fma_f32 v122, v154, v122, v186
	v_mul_f32_e32 v123, v123, v232
	v_mul_f32_e32 v123, v219, v123
	v_add_f32_e32 v155, 1.0, v155
	v_fma_f32 v123, v155, v123, v187
	v_mul_f32_e32 v124, v124, v232
	v_mul_f32_e32 v124, v220, v124
	v_add_f32_e32 v156, 1.0, v156
	v_fma_f32 v124, v156, v124, v188
	v_mul_f32_e32 v125, v125, v232
	v_mul_f32_e32 v125, v221, v125
	v_add_f32_e32 v157, 1.0, v157
	v_fma_f32 v125, v157, v125, v189
	v_mul_f32_e32 v126, v126, v232
	v_mul_f32_e32 v126, v222, v126
	v_add_f32_e32 v158, 1.0, v158
	v_fma_f32 v126, v158, v126, v190
	v_mul_f32_e32 v127, v127, v232
	v_mul_f32_e32 v127, v223, v127
	v_add_f32_e32 v159, 1.0, v159
	v_fma_f32 v127, v159, v127, v191
	v_mul_f32_e32 v128, v128, v232
	v_mul_f32_e32 v128, v224, v128
	v_add_f32_e32 v160, 1.0, v160
	v_fma_f32 v128, v160, v128, v192
	v_mul_f32_e32 v129, v129, v232
	v_mul_f32_e32 v129, v225, v129
	v_add_f32_e32 v161, 1.0, v161
	v_fma_f32 v129, v161, v129, v193
	v_cvt_pk_bf16_f32 v98, v98, v99
	v_cvt_pk_bf16_f32 v99, v100, v101
	v_cvt_pk_bf16_f32 v100, v102, v103
	v_cvt_pk_bf16_f32 v101, v104, v105
	v_cvt_pk_bf16_f32 v102, v106, v107
	v_cvt_pk_bf16_f32 v103, v108, v109
	v_cvt_pk_bf16_f32 v104, v110, v111
	v_cvt_pk_bf16_f32 v105, v112, v113
	v_cvt_pk_bf16_f32 v106, v114, v115
	v_cvt_pk_bf16_f32 v107, v116, v117
	v_cvt_pk_bf16_f32 v108, v118, v119
	v_cvt_pk_bf16_f32 v109, v120, v121
	v_cvt_pk_bf16_f32 v110, v122, v123
	v_cvt_pk_bf16_f32 v111, v124, v125
	v_cvt_pk_bf16_f32 v112, v126, v127
	v_cvt_pk_bf16_f32 v113, v128, v129
	s_lshl_b32 s17, s12, 6
	s_add_u32 s10, s80, s17
	s_addc_u32 s11, s81, 0
	global_store_dwordx2 v242, v[98:99], s[10:11]
	global_store_dwordx2 v243, v[100:101], s[10:11]
	global_store_dwordx2 v244, v[102:103], s[10:11]
	global_store_dwordx2 v245, v[104:105], s[10:11]
	global_store_dwordx2 v246, v[106:107], s[10:11]
	global_store_dwordx2 v247, v[108:109], s[10:11]
	global_store_dwordx2 v248, v[110:111], s[10:11]
	global_store_dwordx2 v249, v[112:113], s[10:11]
	s_add_i32 s12, s12, s13
	s_branch .Lad_loop_p9
.Lad_last_p9_0:
	s_waitcnt vmcnt(0)
	v_mul_f32_e32 v226, v2, v2
	v_mul_f32_e32 v227, v3, v3
	v_mul_f32_e32 v228, v4, v4
	v_mul_f32_e32 v229, v5, v5
	v_fmac_f32_e32 v226, v6, v6
	v_fmac_f32_e32 v227, v7, v7
	v_fmac_f32_e32 v228, v8, v8
	v_fmac_f32_e32 v229, v9, v9
	v_fmac_f32_e32 v226, v10, v10
	v_fmac_f32_e32 v227, v11, v11
	v_fmac_f32_e32 v228, v12, v12
	v_fmac_f32_e32 v229, v13, v13
	v_fmac_f32_e32 v226, v14, v14
	v_fmac_f32_e32 v227, v15, v15
	v_fmac_f32_e32 v228, v16, v16
	v_fmac_f32_e32 v229, v17, v17
	v_fmac_f32_e32 v226, v18, v18
	v_fmac_f32_e32 v227, v19, v19
	v_fmac_f32_e32 v228, v20, v20
	v_fmac_f32_e32 v229, v21, v21
	v_fmac_f32_e32 v226, v22, v22
	v_fmac_f32_e32 v227, v23, v23
	v_fmac_f32_e32 v228, v24, v24
	v_fmac_f32_e32 v229, v25, v25
	v_fmac_f32_e32 v226, v26, v26
	v_fmac_f32_e32 v227, v27, v27
	v_fmac_f32_e32 v228, v28, v28
	v_fmac_f32_e32 v229, v29, v29
	v_fmac_f32_e32 v226, v30, v30
	v_fmac_f32_e32 v227, v31, v31
	v_fmac_f32_e32 v228, v32, v32
	v_fmac_f32_e32 v229, v33, v33
	v_add_f32_e32 v226, v227, v226
	v_add_f32_e32 v228, v229, v228
	v_add_f32_e32 v226, v228, v226
	s_nop 1
	v_add_f32_dpp v226, v226, v226 quad_perm:[1,0,3,2] row_mask:0xf bank_mask:0xf bound_ctrl:1
	s_nop 1
	v_add_f32_dpp v226, v226, v226 quad_perm:[2,3,0,1] row_mask:0xf bank_mask:0xf bound_ctrl:1
	s_nop 1
	v_add_f32_dpp v226, v226, v226 row_half_mirror row_mask:0xf bank_mask:0xf bound_ctrl:1
	s_nop 1
	v_add_f32_dpp v226, v226, v226 row_mirror row_mask:0xf bank_mask:0xf bound_ctrl:1
	s_nop 1
	v_add_f32_dpp v226, v226, v226 row_bcast:15 row_mask:0xa bank_mask:0xf
	s_nop 1
	v_add_f32_dpp v226, v226, v226 row_bcast:31 row_mask:0xc bank_mask:0xf
	s_nop 0
	v_readlane_b32 s16, v226, 63
	s_nop 1
	v_mov_b32_e32 v230, s16
	v_fmamk_f32 v230, v230, 0x3a000000, v233
	v_mul_f32_e32 v231, 0x4b800000, v230
	v_cmp_lt_f32_e32 vcc, v230, v234
	s_nop 1
	v_cndmask_b32_e32 v230, v230, v231, vcc
	v_rsq_f32_e32 v230, v230
	s_nop 0
	v_mul_f32_e32 v231, 0x45800000, v230
	v_cndmask_b32_e32 v232, v230, v231, vcc
	v_mul_f32_e32 v2, v2, v232
	v_mul_f32_e32 v2, v194, v2
	v_add_f32_e32 v34, 1.0, v34
	v_fma_f32 v2, v34, v2, v66
	v_mul_f32_e32 v3, v3, v232
	v_mul_f32_e32 v3, v195, v3
	v_add_f32_e32 v35, 1.0, v35
	v_fma_f32 v3, v35, v3, v67
	v_mul_f32_e32 v4, v4, v232
	v_mul_f32_e32 v4, v196, v4
	v_add_f32_e32 v36, 1.0, v36
	v_fma_f32 v4, v36, v4, v68
	v_mul_f32_e32 v5, v5, v232
	v_mul_f32_e32 v5, v197, v5
	v_add_f32_e32 v37, 1.0, v37
	v_fma_f32 v5, v37, v5, v69
	v_mul_f32_e32 v6, v6, v232
	v_mul_f32_e32 v6, v198, v6
; DEV unsigned pack2(float a, float b) { float2v v = {a, b}; return __builtin_bit_cast(unsigned, __builtin_convertvector(v, bf16x2v)); }
; DEV void ph_adaln_row(const float* xin, const float* g, const float* mod, int sh_off, int sc_off, u16* hout, int row) {
;     ...
;     float y0 = v[i].x * rstd * g4.x * (1.f + sc.x) + sh.x;
;     float y1 = v[i].y * rstd * g4.y * (1.f + sc.y) + sh.y;
;     float y2 = v[i].z * rstd * g4.z * (1.f + sc.z) + sh.z;
;     float y3 = v[i].w * rstd * g4.w * (1.f + sc.w) + sh.w;
;     u32x2 pk; pk[0] = pack2(y0, y1); pk[1] = pack2(y2, y3);
;     *(u32x2*)(hout + (size_t)row * 2048 + col) = pk;
;   }
	v_add_f32_e32 v38, 1.0, v38
	v_fma_f32 v6, v38, v6, v70
	v_mul_f32_e32 v7, v7, v232
	v_mul_f32_e32 v7, v199, v7
	v_add_f32_e32 v39, 1.0, v39
	v_fma_f32 v7, v39, v7, v71
	v_mul_f32_e32 v8, v8, v232
	v_mul_f32_e32 v8, v200, v8
	v_add_f32_e32 v40, 1.0, v40
	v_fma_f32 v8, v40, v8, v72
	v_mul_f32_e32 v9, v9, v232
	v_mul_f32_e32 v9, v201, v9
	v_add_f32_e32 v41, 1.0, v41
	v_fma_f32 v9, v41, v9, v73
	v_mul_f32_e32 v10, v10, v232
	v_mul_f32_e32 v10, v202, v10
	v_add_f32_e32 v42, 1.0, v42
	v_fma_f32 v10, v42, v10, v74
	v_mul_f32_e32 v11, v11, v232
	v_mul_f32_e32 v11, v203, v11
	v_add_f32_e32 v43, 1.0, v43
	v_fma_f32 v11, v43, v11, v75
	v_mul_f32_e32 v12, v12, v232
	v_mul_f32_e32 v12, v204, v12
	v_add_f32_e32 v44, 1.0, v44
	v_fma_f32 v12, v44, v12, v76
	v_mul_f32_e32 v13, v13, v232
	v_mul_f32_e32 v13, v205, v13
	v_add_f32_e32 v45, 1.0, v45
	v_fma_f32 v13, v45, v13, v77
	v_mul_f32_e32 v14, v14, v232
	v_mul_f32_e32 v14, v206, v14
	v_add_f32_e32 v46, 1.0, v46
	v_fma_f32 v14, v46, v14, v78
	v_mul_f32_e32 v15, v15, v232
	v_mul_f32_e32 v15, v207, v15
	v_add_f32_e32 v47, 1.0, v47
	v_fma_f32 v15, v47, v15, v79
	v_mul_f32_e32 v16, v16, v232
	v_mul_f32_e32 v16, v208, v16
	v_add_f32_e32 v48, 1.0, v48
	v_fma_f32 v16, v48, v16, v80
	v_mul_f32_e32 v17, v17, v232
	v_mul_f32_e32 v17, v209, v17
	v_add_f32_e32 v49, 1.0, v49
	v_fma_f32 v17, v49, v17, v81
	v_mul_f32_e32 v18, v18, v232
	v_mul_f32_e32 v18, v210, v18
	v_add_f32_e32 v50, 1.0, v50
	v_fma_f32 v18, v50, v18, v82
	v_mul_f32_e32 v19, v19, v232
	v_mul_f32_e32 v19, v211, v19
	v_add_f32_e32 v51, 1.0, v51
	v_fma_f32 v19, v51, v19, v83
	v_mul_f32_e32 v20, v20, v232
	v_mul_f32_e32 v20, v212, v20
	v_add_f32_e32 v52, 1.0, v52
	v_fma_f32 v20, v52, v20, v84
	v_mul_f32_e32 v21, v21, v232
	v_mul_f32_e32 v21, v213, v21
	v_add_f32_e32 v53, 1.0, v53
	v_fma_f32 v21, v53, v21, v85
	v_mul_f32_e32 v22, v22, v232
	v_mul_f32_e32 v22, v214, v22
	v_add_f32_e32 v54, 1.0, v54
	v_fma_f32 v22, v54, v22, v86
	v_mul_f32_e32 v23, v23, v232
	v_mul_f32_e32 v23, v215, v23
	v_add_f32_e32 v55, 1.0, v55
	v_fma_f32 v23, v55, v23, v87
	v_mul_f32_e32 v24, v24, v232
	v_mul_f32_e32 v24, v216, v24
	v_add_f32_e32 v56, 1.0, v56
	v_fma_f32 v24, v56, v24, v88
	v_mul_f32_e32 v25, v25, v232
	v_mul_f32_e32 v25, v217, v25
	v_add_f32_e32 v57, 1.0, v57
	v_fma_f32 v25, v57, v25, v89
	v_mul_f32_e32 v26, v26, v232
	v_mul_f32_e32 v26, v218, v26
	v_add_f32_e32 v58, 1.0, v58
	v_fma_f32 v26, v58, v26, v90
	v_mul_f32_e32 v27, v27, v232
	v_mul_f32_e32 v27, v219, v27
	v_add_f32_e32 v59, 1.0, v59
	v_fma_f32 v27, v59, v27, v91
	v_mul_f32_e32 v28, v28, v232
	v_mul_f32_e32 v28, v220, v28
	v_add_f32_e32 v60, 1.0, v60
	v_fma_f32 v28, v60, v28, v92
	v_mul_f32_e32 v29, v29, v232
	v_mul_f32_e32 v29, v221, v29
	v_add_f32_e32 v61, 1.0, v61
	v_fma_f32 v29, v61, v29, v93
	v_mul_f32_e32 v30, v30, v232
	v_mul_f32_e32 v30, v222, v30
	v_add_f32_e32 v62, 1.0, v62
	v_fma_f32 v30, v62, v30, v94
	v_mul_f32_e32 v31, v31, v232
	v_mul_f32_e32 v31, v223, v31
	v_add_f32_e32 v63, 1.0, v63
	v_fma_f32 v31, v63, v31, v95
	v_mul_f32_e32 v32, v32, v232
	v_mul_f32_e32 v32, v224, v32
	v_add_f32_e32 v64, 1.0, v64
	v_fma_f32 v32, v64, v32, v96
	v_mul_f32_e32 v33, v33, v232
	v_mul_f32_e32 v33, v225, v33
	v_add_f32_e32 v65, 1.0, v65
	v_fma_f32 v33, v65, v33, v97
	v_cvt_pk_bf16_f32 v2, v2, v3
	v_cvt_pk_bf16_f32 v3, v4, v5
	v_cvt_pk_bf16_f32 v4, v6, v7
	v_cvt_pk_bf16_f32 v5, v8, v9
	v_cvt_pk_bf16_f32 v6, v10, v11
	v_cvt_pk_bf16_f32 v7, v12, v13
	v_cvt_pk_bf16_f32 v8, v14, v15
	v_cvt_pk_bf16_f32 v9, v16, v17
	v_cvt_pk_bf16_f32 v10, v18, v19
	v_cvt_pk_bf16_f32 v11, v20, v21
	v_cvt_pk_bf16_f32 v12, v22, v23
	v_cvt_pk_bf16_f32 v13, v24, v25
	v_cvt_pk_bf16_f32 v14, v26, v27
	v_cvt_pk_bf16_f32 v15, v28, v29
	v_cvt_pk_bf16_f32 v16, v30, v31
	v_cvt_pk_bf16_f32 v17, v32, v33
	s_lshl_b32 s17, s12, 6
	s_add_u32 s10, s80, s17
	s_addc_u32 s11, s81, 0
	global_store_dwordx2 v242, v[2:3], s[10:11]
	global_store_dwordx2 v243, v[4:5], s[10:11]
	global_store_dwordx2 v244, v[6:7], s[10:11]
	global_store_dwordx2 v245, v[8:9], s[10:11]
	global_store_dwordx2 v246, v[10:11], s[10:11]
	global_store_dwordx2 v247, v[12:13], s[10:11]
	global_store_dwordx2 v248, v[14:15], s[10:11]
	global_store_dwordx2 v249, v[16:17], s[10:11]
	s_branch .Lad_end_p9
.Lad_last_p9_1:
	s_waitcnt vmcnt(0)
; DEV void ph_adaln_row(const float* xin, const float* g, const float* mod, int sh_off, int sc_off, u16* hout, int row) {
;     ...
;   for (int i = 0; i < 8; ++i) {
;     v[i] = *(const float4*)(xr + i * 256 + lane * 4);
;     ss += v[i].x * v[i].x + v[i].y * v[i].y + v[i].z * v[i].z + v[i].w * v[i].w;
;   }
;   ss = wave_sum(ss);
;   const float rstd = rsqrtf(ss * (1.f / 2048.f) + 1e-6f);
;   const float* mb = mod + (size_t)b * 12288;
; #pragma unroll
;   for (int i = 0; i < 8; ++i) {
;     int col = i * 256 + lane * 4;
;     float4 g4 = *(const float4*)(g + col);
;     float4 sc = *(const float4*)(mb + sc_off + col);
;     float4 sh = *(const float4*)(mb + sh_off + col);
;     float y0 = v[i].x * rstd * g4.x * (1.f + sc.x) + sh.x;
;     float y1 = v[i].y * rstd * g4.y * (1.f + sc.y) + sh.y;
;     float y2 = v[i].z * rstd * g4.z * (1.f + sc.z) + sh.z;
;     float y3 = v[i].w * rstd * g4.w * (1.f + sc.w) + sh.w;
	v_mul_f32_e32 v226, v98, v98
	v_mul_f32_e32 v227, v99, v99
	v_mul_f32_e32 v228, v100, v100
	v_mul_f32_e32 v229, v101, v101
	v_fmac_f32_e32 v226, v102, v102
	v_fmac_f32_e32 v227, v103, v103
	v_fmac_f32_e32 v228, v104, v104
	v_fmac_f32_e32 v229, v105, v105
	v_fmac_f32_e32 v226, v106, v106
	v_fmac_f32_e32 v227, v107, v107
	v_fmac_f32_e32 v228, v108, v108
	v_fmac_f32_e32 v229, v109, v109
	v_fmac_f32_e32 v226, v110, v110
	v_fmac_f32_e32 v227, v111, v111
	v_fmac_f32_e32 v228, v112, v112
	v_fmac_f32_e32 v229, v113, v113
	v_fmac_f32_e32 v226, v114, v114
	v_fmac_f32_e32 v227, v115, v115
	v_fmac_f32_e32 v228, v116, v116
	v_fmac_f32_e32 v229, v117, v117
	v_fmac_f32_e32 v226, v118, v118
	v_fmac_f32_e32 v227, v119, v119
	v_fmac_f32_e32 v228, v120, v120
	v_fmac_f32_e32 v229, v121, v121
	v_fmac_f32_e32 v226, v122, v122
	v_fmac_f32_e32 v227, v123, v123
	v_fmac_f32_e32 v228, v124, v124
	v_fmac_f32_e32 v229, v125, v125
	v_fmac_f32_e32 v226, v126, v126
	v_fmac_f32_e32 v227, v127, v127
	v_fmac_f32_e32 v228, v128, v128
	v_fmac_f32_e32 v229, v129, v129
	v_add_f32_e32 v226, v227, v226
	v_add_f32_e32 v228, v229, v228
	v_add_f32_e32 v226, v228, v226
	s_nop 1
	v_add_f32_dpp v226, v226, v226 quad_perm:[1,0,3,2] row_mask:0xf bank_mask:0xf bound_ctrl:1
	s_nop 1
	v_add_f32_dpp v226, v226, v226 quad_perm:[2,3,0,1] row_mask:0xf bank_mask:0xf bound_ctrl:1
	s_nop 1
	v_add_f32_dpp v226, v226, v226 row_half_mirror row_mask:0xf bank_mask:0xf bound_ctrl:1
	s_nop 1
	v_add_f32_dpp v226, v226, v226 row_mirror row_mask:0xf bank_mask:0xf bound_ctrl:1
	s_nop 1
	v_add_f32_dpp v226, v226, v226 row_bcast:15 row_mask:0xa bank_mask:0xf
	s_nop 1
	v_add_f32_dpp v226, v226, v226 row_bcast:31 row_mask:0xc bank_mask:0xf
	s_nop 0
	v_readlane_b32 s16, v226, 63
	s_nop 1
	v_mov_b32_e32 v230, s16
	v_fmamk_f32 v230, v230, 0x3a000000, v233
	v_mul_f32_e32 v231, 0x4b800000, v230
	v_cmp_lt_f32_e32 vcc, v230, v234
	s_nop 1
	v_cndmask_b32_e32 v230, v230, v231, vcc
	v_rsq_f32_e32 v230, v230
	s_nop 0
	v_mul_f32_e32 v231, 0x45800000, v230
	v_cndmask_b32_e32 v232, v230, v231, vcc
	v_mul_f32_e32 v98, v98, v232
	v_mul_f32_e32 v98, v194, v98
	v_add_f32_e32 v130, 1.0, v130
	v_fma_f32 v98, v130, v98, v162
	v_mul_f32_e32 v99, v99, v232
	v_mul_f32_e32 v99, v195, v99
	v_add_f32_e32 v131, 1.0, v131
	v_fma_f32 v99, v131, v99, v163
	v_mul_f32_e32 v100, v100, v232
	v_mul_f32_e32 v100, v196, v100
	v_add_f32_e32 v132, 1.0, v132
	v_fma_f32 v100, v132, v100, v164
	v_mul_f32_e32 v101, v101, v232
	v_mul_f32_e32 v101, v197, v101
	v_add_f32_e32 v133, 1.0, v133
	v_fma_f32 v101, v133, v101, v165
	v_mul_f32_e32 v102, v102, v232
	v_mul_f32_e32 v102, v198, v102
	v_add_f32_e32 v134, 1.0, v134
	v_fma_f32 v102, v134, v102, v166
	v_mul_f32_e32 v103, v103, v232
	v_mul_f32_e32 v103, v199, v103
	v_add_f32_e32 v135, 1.0, v135
	v_fma_f32 v103, v135, v103, v167
	v_mul_f32_e32 v104, v104, v232
	v_mul_f32_e32 v104, v200, v104
	v_add_f32_e32 v136, 1.0, v136
	v_fma_f32 v104, v136, v104, v168
	v_mul_f32_e32 v105, v105, v232
	v_mul_f32_e32 v105, v201, v105
	v_add_f32_e32 v137, 1.0, v137
	v_fma_f32 v105, v137, v105, v169
	v_mul_f32_e32 v106, v106, v232
	v_mul_f32_e32 v106, v202, v106
	v_add_f32_e32 v138, 1.0, v138
	v_fma_f32 v106, v138, v106, v170
	v_mul_f32_e32 v107, v107, v232
	v_mul_f32_e32 v107, v203, v107
	v_add_f32_e32 v139, 1.0, v139
	v_fma_f32 v107, v139, v107, v171
	v_mul_f32_e32 v108, v108, v232
	v_mul_f32_e32 v108, v204, v108
	v_add_f32_e32 v140, 1.0, v140
	v_fma_f32 v108, v140, v108, v172
	v_mul_f32_e32 v109, v109, v232
	v_mul_f32_e32 v109, v205, v109
	v_add_f32_e32 v141, 1.0, v141
	v_fma_f32 v109, v141, v109, v173
	v_mul_f32_e32 v110, v110, v232
	v_mul_f32_e32 v110, v206, v110
	v_add_f32_e32 v142, 1.0, v142
	v_fma_f32 v110, v142, v110, v174
	v_mul_f32_e32 v111, v111, v232
	v_mul_f32_e32 v111, v207, v111
	v_add_f32_e32 v143, 1.0, v143
	v_fma_f32 v111, v143, v111, v175
	v_mul_f32_e32 v112, v112, v232
	v_mul_f32_e32 v112, v208, v112
	v_add_f32_e32 v144, 1.0, v144
	v_fma_f32 v112, v144, v112, v176
	v_mul_f32_e32 v113, v113, v232
	v_mul_f32_e32 v113, v209, v113
	v_add_f32_e32 v145, 1.0, v145
	v_fma_f32 v113, v145, v113, v177
	v_mul_f32_e32 v114, v114, v232
	v_mul_f32_e32 v114, v210, v114
	v_add_f32_e32 v146, 1.0, v146
	v_fma_f32 v114, v146, v114, v178
	v_mul_f32_e32 v115, v115, v232
	v_mul_f32_e32 v115, v211, v115
; DEV unsigned pack2(float a, float b) { float2v v = {a, b}; return __builtin_bit_cast(unsigned, __builtin_convertvector(v, bf16x2v)); }
; DEV void ph_adaln_row(const float* xin, const float* g, const float* mod, int sh_off, int sc_off, u16* hout, int row) {
;     ...
;     float y0 = v[i].x * rstd * g4.x * (1.f + sc.x) + sh.x;
;     float y1 = v[i].y * rstd * g4.y * (1.f + sc.y) + sh.y;
;     float y2 = v[i].z * rstd * g4.z * (1.f + sc.z) + sh.z;
;     float y3 = v[i].w * rstd * g4.w * (1.f + sc.w) + sh.w;
;     u32x2 pk; pk[0] = pack2(y0, y1); pk[1] = pack2(y2, y3);
;     *(u32x2*)(hout + (size_t)row * 2048 + col) = pk;
;   }
; DEV void xcd_barrier(unsigned* bar, unsigned x, volatile unsigned* st) {
;   asm volatile("s_waitcnt vmcnt(0)" ::: "memory");
;   __syncthreads();
;   if (threadIdx.x == 0) {
;     __builtin_amdgcn_s_waitcnt(0);
;     unsigned nloc = st[0], nx = st[1];
;     if (nloc == 0u) { xcd_barrier_complete(bar, x, nloc, nx); st[0] = nloc; st[1] = nx; }
	v_add_f32_e32 v147, 1.0, v147
	v_fma_f32 v115, v147, v115, v179
	v_mul_f32_e32 v116, v116, v232
	v_mul_f32_e32 v116, v212, v116
	v_add_f32_e32 v148, 1.0, v148
	v_fma_f32 v116, v148, v116, v180
	v_mul_f32_e32 v117, v117, v232
	v_mul_f32_e32 v117, v213, v117
	v_add_f32_e32 v149, 1.0, v149
	v_fma_f32 v117, v149, v117, v181
	v_mul_f32_e32 v118, v118, v232
	v_mul_f32_e32 v118, v214, v118
	v_add_f32_e32 v150, 1.0, v150
	v_fma_f32 v118, v150, v118, v182
	v_mul_f32_e32 v119, v119, v232
	v_mul_f32_e32 v119, v215, v119
	v_add_f32_e32 v151, 1.0, v151
	v_fma_f32 v119, v151, v119, v183
	v_mul_f32_e32 v120, v120, v232
	v_mul_f32_e32 v120, v216, v120
	v_add_f32_e32 v152, 1.0, v152
	v_fma_f32 v120, v152, v120, v184
	v_mul_f32_e32 v121, v121, v232
	v_mul_f32_e32 v121, v217, v121
	v_add_f32_e32 v153, 1.0, v153
	v_fma_f32 v121, v153, v121, v185
	v_mul_f32_e32 v122, v122, v232
	v_mul_f32_e32 v122, v218, v122
	v_add_f32_e32 v154, 1.0, v154
	v_fma_f32 v122, v154, v122, v186
	v_mul_f32_e32 v123, v123, v232
	v_mul_f32_e32 v123, v219, v123
	v_add_f32_e32 v155, 1.0, v155
	v_fma_f32 v123, v155, v123, v187
	v_mul_f32_e32 v124, v124, v232
	v_mul_f32_e32 v124, v220, v124
	v_add_f32_e32 v156, 1.0, v156
	v_fma_f32 v124, v156, v124, v188
	v_mul_f32_e32 v125, v125, v232
	v_mul_f32_e32 v125, v221, v125
	v_add_f32_e32 v157, 1.0, v157
	v_fma_f32 v125, v157, v125, v189
	v_mul_f32_e32 v126, v126, v232
	v_mul_f32_e32 v126, v222, v126
	v_add_f32_e32 v158, 1.0, v158
	v_fma_f32 v126, v158, v126, v190
	v_mul_f32_e32 v127, v127, v232
	v_mul_f32_e32 v127, v223, v127
	v_add_f32_e32 v159, 1.0, v159
	v_fma_f32 v127, v159, v127, v191
	v_mul_f32_e32 v128, v128, v232
	v_mul_f32_e32 v128, v224, v128
	v_add_f32_e32 v160, 1.0, v160
	v_fma_f32 v128, v160, v128, v192
	v_mul_f32_e32 v129, v129, v232
	v_mul_f32_e32 v129, v225, v129
	v_add_f32_e32 v161, 1.0, v161
	v_fma_f32 v129, v161, v129, v193
	v_cvt_pk_bf16_f32 v98, v98, v99
	v_cvt_pk_bf16_f32 v99, v100, v101
	v_cvt_pk_bf16_f32 v100, v102, v103
	v_cvt_pk_bf16_f32 v101, v104, v105
	v_cvt_pk_bf16_f32 v102, v106, v107
	v_cvt_pk_bf16_f32 v103, v108, v109
	v_cvt_pk_bf16_f32 v104, v110, v111
	v_cvt_pk_bf16_f32 v105, v112, v113
	v_cvt_pk_bf16_f32 v106, v114, v115
	v_cvt_pk_bf16_f32 v107, v116, v117
	v_cvt_pk_bf16_f32 v108, v118, v119
	v_cvt_pk_bf16_f32 v109, v120, v121
	v_cvt_pk_bf16_f32 v110, v122, v123
	v_cvt_pk_bf16_f32 v111, v124, v125
	v_cvt_pk_bf16_f32 v112, v126, v127
	v_cvt_pk_bf16_f32 v113, v128, v129
	s_lshl_b32 s17, s12, 6
	s_add_u32 s10, s80, s17
	s_addc_u32 s11, s81, 0
	global_store_dwordx2 v242, v[98:99], s[10:11]
	global_store_dwordx2 v243, v[100:101], s[10:11]
	global_store_dwordx2 v244, v[102:103], s[10:11]
	global_store_dwordx2 v245, v[104:105], s[10:11]
	global_store_dwordx2 v246, v[106:107], s[10:11]
	global_store_dwordx2 v247, v[108:109], s[10:11]
	global_store_dwordx2 v248, v[110:111], s[10:11]
	global_store_dwordx2 v249, v[112:113], s[10:11]
.Lad_end_p9:
.LBB0_1313:
	s_or_b64 exec, exec, s[6:7]
	s_waitcnt vmcnt(0)
	s_barrier
	s_mov_b64 s[6:7], exec
	v_readlane_b32 s2, v254, 2
	v_readlane_b32 s3, v254, 3
	v_readlane_b32 s36, v254, 4
	s_and_b64 s[2:3], s[6:7], s[2:3]
	v_readlane_b32 s40, v254, 8
	v_readlane_b32 s41, v254, 9
	v_readlane_b32 s42, v254, 10
	v_readlane_b32 s43, v254, 11
	v_readlane_b32 s44, v254, 12
	v_readlane_b32 s45, v254, 13
	v_readlane_b32 s50, v254, 18
	v_readlane_b32 s51, v254, 19
	v_readlane_b32 s37, v254, 5
	v_readlane_b32 s38, v254, 6
	v_readlane_b32 s39, v254, 7
	v_readlane_b32 s46, v254, 14
	v_readlane_b32 s47, v254, 15
	v_readlane_b32 s48, v254, 16
	v_readlane_b32 s49, v254, 17
	s_mov_b64 exec, s[2:3]
	s_cbranch_execz .LBB0_1365
	s_mov_b64 s[2:3], src_shared_base
	v_mov_b32_e32 v2, 0x12100
	v_mov_b32_e32 v3, s3
	s_waitcnt vmcnt(0) expcnt(0) lgkmcnt(0)
	flat_load_dword v4, v[2:3] sc0 sc1
	s_waitcnt vmcnt(0)
	v_mov_b32_e32 v2, 0x12104
	flat_load_dword v2, v[2:3] sc0 sc1
	s_waitcnt vmcnt(0) lgkmcnt(0)
	v_cmp_eq_u32_e32 vcc, 0, v4
	s_and_saveexec_b64 s[8:9], vcc
	s_cbranch_execz .LBB0_1329
	s_add_u32 s10, s70, 0x1000
	s_addc_u32 s11, s71, 0
	s_add_u32 s12, s70, 0x1100
	s_addc_u32 s13, s71, 0
	s_add_u32 s16, s70, 0x1200
	s_addc_u32 s17, s71, 0
	s_add_u32 s18, s70, 0x1300
	s_addc_u32 s19, s71, 0
	s_mov_b32 s2, 1
	v_mov_b32_e32 v17, 0
	s_branch .LBB0_1317

; template <class AF, class EPI>
; DEV void gemm_tile256(AF aptr, const u16* Bt, int ldb, int K, EPI epi, char* smem) {
;     ...
;   auto stage = [&](int kt, int buf) {
;     char* SA = smem + buf * 24576;
;     char* SB = SA + 16384;
; #pragma unroll
;     for (int i = 0; i < 4; ++i) {
;       int bo = tid * 16 + i * 4096, r = bo >> 6, c = (bo & 63) >> 1;
;       __builtin_amdgcn_global_load_lds((const unsigned*)aptr(r, kt * 32 + c), (__attribute__((address_space(3))) unsigned*)(SA + bo), 16, 0, 0);
;     }
; #pragma unroll
;     for (int i = 0; i < 2; ++i) {
;       int bo = tid * 16 + i * 4096, r = bo >> 6, c = (bo & 63) >> 1;
;       __builtin_amdgcn_global_load_lds((const unsigned*)(Bt + (size_t)r * ldb + kt * 32 + c), (__attribute__((address_space(3))) unsigned*)(SB + bo), 16, 0, 0);
;     }
;   };
;   asm volatile("s_waitcnt vmcnt(0)" ::: "memory");
;   __syncthreads();
;   stage(0, 0);
;   stage(1, 1);
;   const unsigned lbase = (unsigned)(size_t)(const __attribute__((address_space(3))) char*)smem;
;   const unsigned aoff = lbase + (wr * 128 + fr) * 64 + fq * 16, boff = lbase + 16384 + (wc * 64 + fr) * 64 + fq * 16;
; __global__ void __launch_bounds__(256, 2) fwd_megakernel(Params p) {
;     ...
;   for (int jt = (bid >> 3); jt < 8 * 16; jt += (nb >> 3)) {
;     const int pn = jt >> 3, pm = (bid & 7) * 8 + (jt & 7);
;     const u16* A = p.h + (size_t)pm * 256 * 2048;
;     gemm_tile256([&](int r, int k) { return A + (size_t)r * 2048 + k; }, p.Wt_q + (size_t)pn * 128 * 2048, 2048, 2048,
.LBB0_1365:
	s_or_b64 exec, exec, s[6:7]
	v_mov_b32_e32 v1, v0
	s_andn2_b64 vcc, exec, s[0:1]
	s_waitcnt lgkmcnt(0)
	s_barrier
	s_cbranch_vccnz .LBB0_1384
	s_lshl_b32 s0, s94, 3
	s_lshr_b32 s2, s94, 3
	s_and_b32 s3, s0, 56
	s_ashr_i32 s4, s92, 3
	s_mov_b64 s[8:9], s[80:81]
	s_add_u32 s5, s8, 0x200000
	s_addc_u32 s10, s9, 0
	s_and_b32 s0, s94, 7
	s_lshl_b32 s11, s0, 22
	s_add_u32 s12, s50, 0x80
	s_addc_u32 s13, s51, 0
	s_lshl_b32 s14, s0, 23
	v_mov_b32_e32 v131, 0
	s_movk_i32 s15, 0x4000
	s_movk_i32 s16, 0x210
	s_movk_i32 s17, 0x80
	s_mov_b32 s18, 0x10000
	s_mov_b32 s19, 0x20000
	s_mov_b32 s20, 0x30000
	s_mov_b32 s21, 0x80000
	s_mov_b32 s22, 0x90000
	s_mov_b32 s23, 0xa0000
	s_mov_b32 s24, 0xb0000
.LBB0_1367:
	s_and_b32 s25, s2, 7
	s_lshl_b32 s0, s25, 19
	s_and_b32 s1, s58, 7
	s_add_i32 s0, s11, s0
	s_or_b32 s1, s1, s3
	v_mov_b32_e32 v144, v0
	s_lshr_b32 s28, s0, 5
	s_ashr_i32 s0, s58, 3
	s_lshl_b32 s1, s1, 14
	s_mov_b64 s[8:9], s[80:81]
	s_add_u32 s8, s8, s1
	v_ashrrev_i32_e32 v2, 2, v144
	v_lshlrev_b32_e32 v148, 4, v144
	v_ashrrev_i32_e32 v3, 31, v2
	s_addc_u32 s9, s9, 0
	s_ashr_i32 s1, s0, 31
	v_lshlrev_b64 v[2:3], 12, v[2:3]
	v_lshrrev_b64 v[246:247], 6, v[2:3]
	s_mov_b64 s[30:31], 0x100000
	v_add_u32_e32 v10, 0x1000, v148
	s_lshl_b64 s[6:7], s[0:1], 19
	v_lshl_add_u64 v[4:5], s[8:9], 0, v[246:247]
	v_and_b32_e32 v130, 48, v148
	v_and_b32_e32 v253, 32, v144
	v_xor_b32_e32 v130, v130, v253
	v_readfirstlane_b32 s1, v148
	v_ashrrev_i32_e32 v6, 6, v10
	v_add_u32_e32 v14, 0x2000, v148
	v_lshl_add_u64 v[4:5], v[4:5], 0, v[130:131]
	s_mov_b32 m0, s1
	v_ashrrev_i32_e32 v7, 31, v6
	v_readfirstlane_b32 s1, v10
	v_ashrrev_i32_e32 v10, 6, v14
	v_add_u32_e32 v18, 0x3000, v148
	s_waitcnt vmcnt(0)
	s_barrier
; template <class AF, class EPI>
; DEV void gemm_tile256(AF aptr, const u16* Bt, int ldb, int K, EPI epi, char* smem) {
;     ...
;   auto stage = [&](int kt, int buf) {
;     char* SA = smem + buf * 24576;
;     char* SB = SA + 16384;
; #pragma unroll
;     for (int i = 0; i < 4; ++i) {
;       int bo = tid * 16 + i * 4096, r = bo >> 6, c = (bo & 63) >> 1;
;       __builtin_amdgcn_global_load_lds((const unsigned*)aptr(r, kt * 32 + c), (__attribute__((address_space(3))) unsigned*)(SA + bo), 16, 0, 0);
;     }
; #pragma unroll
;     for (int i = 0; i < 2; ++i) {
;       int bo = tid * 16 + i * 4096, r = bo >> 6, c = (bo & 63) >> 1;
;       __builtin_amdgcn_global_load_lds((const unsigned*)(Bt + (size_t)r * ldb + kt * 32 + c), (__attribute__((address_space(3))) unsigned*)(SB + bo), 16, 0, 0);
;     }
;   };
;   asm volatile("s_waitcnt vmcnt(0)" ::: "memory");
;   __syncthreads();
;   stage(0, 0);
;   stage(1, 1);
;   const unsigned lbase = (unsigned)(size_t)(const __attribute__((address_space(3))) char*)smem;
;   const unsigned aoff = lbase + (wr * 128 + fr) * 64 + fq * 16, boff = lbase + 16384 + (wc * 64 + fr) * 64 + fq * 16;
	global_load_lds_dwordx4 v[4:5], off
	v_lshlrev_b64 v[6:7], 12, v[6:7]
	v_lshrrev_b64 v[248:249], 6, v[6:7]
	s_mov_b32 m0, s1
	v_ashrrev_i32_e32 v11, 31, v10
	v_readfirstlane_b32 s1, v14
	v_ashrrev_i32_e32 v14, 6, v18
	v_lshl_add_u64 v[8:9], s[8:9], 0, v[248:249]
	v_lshlrev_b64 v[10:11], 6, v[10:11]
	v_ashrrev_i32_e32 v15, 31, v14
	s_add_u32 s26, s50, s6
	v_lshl_add_u64 v[8:9], v[8:9], 0, v[130:131]
	v_lshl_add_u64 v[12:13], s[8:9], 0, v[10:11]
	v_lshlrev_b64 v[14:15], 6, v[14:15]
	s_addc_u32 s27, s51, s7
	global_load_lds_dwordx4 v[8:9], off
	v_lshl_add_u64 v[12:13], v[12:13], 0, v[130:131]
	s_mov_b32 m0, s1
	v_lshl_add_u64 v[16:17], s[8:9], 0, v[14:15]
	v_readfirstlane_b32 s1, v18
	v_add_u32_e32 v20, 0x4000, v148
	global_load_lds_dwordx4 v[12:13], off
	v_lshl_add_u64 v[16:17], v[16:17], 0, v[130:131]
	s_mov_b32 m0, s1
	v_lshl_add_u64 v[18:19], s[26:27], 0, v[2:3]
	v_readfirstlane_b32 s1, v20
	v_add_u32_e32 v22, 0x5000, v148
	global_load_lds_dwordx4 v[16:17], off
	v_lshl_add_u64 v[18:19], v[18:19], 0, v[130:131]
	s_mov_b32 m0, s1
	v_lshl_add_u64 v[20:21], s[26:27], 0, v[6:7]
	v_readfirstlane_b32 s1, v22
	v_add_u32_e32 v22, 0x6000, v148
	global_load_lds_dwordx4 v[18:19], off
	v_lshl_add_u64 v[20:21], v[20:21], 0, v[130:131]
	s_mov_b32 m0, s1
	v_readfirstlane_b32 s1, v22
	global_load_lds_dwordx4 v[20:21], off
	v_lshl_add_u64 v[4:5], v[4:5], 0, s[30:31]
	s_mov_b32 m0, s1
	s_add_u32 s8, s5, s28
	global_load_lds_dwordx4 v[4:5], off
	v_lshl_add_u64 v[4:5], v[8:9], 0, s[30:31]
	v_add_u32_e32 v8, 0x7000, v148
	v_bfe_u32 v147, v144, 4, 2
	v_readfirstlane_b32 s1, v8
	v_add_u32_e32 v8, 0x8000, v148
	s_mov_b32 m0, s1
	v_readfirstlane_b32 s1, v8
	v_add_u32_e32 v8, 0x9000, v148
	global_load_lds_dwordx4 v[4:5], off
	v_lshl_add_u64 v[4:5], v[12:13], 0, s[30:31]
	s_mov_b32 m0, s1
	v_readfirstlane_b32 s1, v8
	v_add_u32_e32 v8, 0xa000, v148
	global_load_lds_dwordx4 v[4:5], off
	v_lshl_add_u64 v[4:5], v[16:17], 0, s[30:31]
	s_mov_b32 m0, s1
	v_readfirstlane_b32 s1, v8
	v_add_u32_e32 v8, 0xb000, v148
	global_load_lds_dwordx4 v[4:5], off
	v_lshl_add_u64 v[4:5], v[18:19], 0, 64
	s_mov_b32 m0, s1
	v_readfirstlane_b32 s1, v8
	global_load_lds_dwordx4 v[4:5], off
	v_lshl_add_u64 v[4:5], v[20:21], 0, 64
	s_mov_b32 m0, s1
	s_addc_u32 s9, s10, 0
	global_load_lds_dwordx4 v[4:5], off
	v_bfe_u32 v145, v144, 6, 1
	v_ashrrev_i32_e32 v1, 7, v144
	v_and_b32_e32 v146, 15, v144
	v_lshlrev_b32_e32 v8, 4, v147
	v_lshlrev_b32_e32 v253, 2, v144
	v_and_b32_e32 v253, 32, v253
	v_xor_b32_e32 v8, v8, v253
	s_add_u32 s6, s12, s6
	v_lshlrev_b32_e32 v4, 13, v1
	v_lshlrev_b32_e32 v5, 6, v146
	v_lshl_or_b32 v9, v145, 12, v8
	v_or_b32_e32 v2, v2, v130
	v_or_b32_e32 v6, v6, v130
	v_or_b32_e32 v10, v10, v130
	v_or_b32_e32 v14, v14, v130
	s_addc_u32 s7, s13, s7
	v_or3_b32 v149, v4, v8, v5
	v_or3_b32 v150, v5, v9, s15
	v_or_b32_e32 v246, v246, v130
	v_or_b32_e32 v248, v248, v130
	v_lshl_add_u64 v[132:133], s[8:9], 0, v[246:247]
	v_lshl_add_u64 v[134:135], s[8:9], 0, v[248:249]
	v_lshl_add_u64 v[136:137], s[8:9], 0, v[10:11]
	v_lshl_add_u64 v[138:139], s[8:9], 0, v[14:15]
	v_lshl_add_u64 v[140:141], s[6:7], 0, v[6:7]
	v_lshl_add_u64 v[142:143], s[6:7], 0, v[2:3]
	s_mov_b64 s[6:7], 0
	s_mov_b32 s1, 0
	s_mov_b32 s26, 0
	v_mov_b32_e32 v2, 0
	v_mov_b32_e32 v3, v131
	v_mov_b32_e32 v4, v131
	v_mov_b32_e32 v5, v131
	v_mov_b32_e32 v6, 0
	v_mov_b32_e32 v7, v131
	v_mov_b32_e32 v8, v131
	v_mov_b32_e32 v9, v131
	v_mov_b32_e32 v10, 0
	v_mov_b32_e32 v11, v131
	v_mov_b32_e32 v12, v131
	v_mov_b32_e32 v13, v131
	v_mov_b32_e32 v14, 0
	v_mov_b32_e32 v15, v131
	v_mov_b32_e32 v16, v131
	v_mov_b32_e32 v17, v131
	v_mov_b32_e32 v18, 0
	v_mov_b32_e32 v19, v131
	v_mov_b32_e32 v20, v131
	v_mov_b32_e32 v21, v131
	v_mov_b32_e32 v22, 0
	v_mov_b32_e32 v23, v131
	v_mov_b32_e32 v24, v131
	v_mov_b32_e32 v25, v131
	v_mov_b32_e32 v26, 0
	v_mov_b32_e32 v27, v131
	v_mov_b32_e32 v28, v131
	v_mov_b32_e32 v29, v131
	v_mov_b32_e32 v30, 0
	v_mov_b32_e32 v31, v131
	v_mov_b32_e32 v32, v131
	v_mov_b32_e32 v33, v131
	v_mov_b32_e32 v34, 0
	v_mov_b32_e32 v35, v131
	v_mov_b32_e32 v36, v131
	v_mov_b32_e32 v37, v131
	v_mov_b32_e32 v38, 0
	v_mov_b32_e32 v39, v131
	v_mov_b32_e32 v40, v131
	v_mov_b32_e32 v41, v131
	v_mov_b32_e32 v42, 0
	v_mov_b32_e32 v43, v131
	v_mov_b32_e32 v44, v131
	v_mov_b32_e32 v45, v131
	v_mov_b32_e32 v94, 0
	v_mov_b32_e32 v95, v131
	v_mov_b32_e32 v96, v131
	v_mov_b32_e32 v97, v131
	v_mov_b32_e32 v98, 0
	v_mov_b32_e32 v99, v131
	v_mov_b32_e32 v100, v131
	v_mov_b32_e32 v101, v131
	v_mov_b32_e32 v102, 0
	v_mov_b32_e32 v103, v131
	v_mov_b32_e32 v104, v131
	v_mov_b32_e32 v105, v131
	v_mov_b32_e32 v106, 0
	v_mov_b32_e32 v107, v131
	v_mov_b32_e32 v108, v131
	v_mov_b32_e32 v109, v131
	v_mov_b32_e32 v110, 0
	v_mov_b32_e32 v111, v131
	v_mov_b32_e32 v112, v131
	v_mov_b32_e32 v113, v131
	v_mov_b32_e32 v114, 0
	v_mov_b32_e32 v115, v131
	v_mov_b32_e32 v116, v131
	v_mov_b32_e32 v117, v131
	v_mov_b32_e32 v118, 0
	v_mov_b32_e32 v119, v131
	v_mov_b32_e32 v120, v131
	v_mov_b32_e32 v121, v131
	v_mov_b32_e32 v122, 0
	v_mov_b32_e32 v123, v131
	v_mov_b32_e32 v124, v131
	v_mov_b32_e32 v125, v131
	v_mov_b32_e32 v126, 0
	v_mov_b32_e32 v127, v131
	v_mov_b32_e32 v128, v131
	v_mov_b32_e32 v129, v131
	v_mov_b32_e32 v46, 0
	v_mov_b32_e32 v47, v131
	v_mov_b32_e32 v48, v131
	v_mov_b32_e32 v49, v131
	v_mov_b32_e32 v50, 0
	v_mov_b32_e32 v51, v131
	v_mov_b32_e32 v52, v131
	v_mov_b32_e32 v53, v131
	v_mov_b32_e32 v54, 0
	v_mov_b32_e32 v55, v131
	v_mov_b32_e32 v56, v131
	v_mov_b32_e32 v57, v131
	v_mov_b32_e32 v58, 0
	v_mov_b32_e32 v59, v131
	v_mov_b32_e32 v60, v131
	v_mov_b32_e32 v61, v131
	v_mov_b32_e32 v62, 0
	v_mov_b32_e32 v63, v131
	v_mov_b32_e32 v64, v131
	v_mov_b32_e32 v65, v131
	v_mov_b32_e32 v66, 0
	v_mov_b32_e32 v67, v131
	v_mov_b32_e32 v68, v131
	v_mov_b32_e32 v69, v131
	v_mov_b32_e32 v70, 0
	v_mov_b32_e32 v71, v131
	v_mov_b32_e32 v72, v131
	v_mov_b32_e32 v73, v131
	v_mov_b32_e32 v74, 0
	v_mov_b32_e32 v75, v131
	v_mov_b32_e32 v76, v131
	v_mov_b32_e32 v77, v131
	v_mov_b32_e32 v78, 0
	v_mov_b32_e32 v79, v131
	v_mov_b32_e32 v80, v131
	v_mov_b32_e32 v81, v131
	v_mov_b32_e32 v82, 0
	v_mov_b32_e32 v83, v131
	v_mov_b32_e32 v84, v131
	v_mov_b32_e32 v85, v131
	v_mov_b32_e32 v86, 0
	v_mov_b32_e32 v87, v131
	v_mov_b32_e32 v88, v131
	v_mov_b32_e32 v89, v131
	v_mov_b32_e32 v90, 0
	v_mov_b32_e32 v91, v131
	v_mov_b32_e32 v92, v131
	v_mov_b32_e32 v93, v131
	s_branch .LBB0_1369

; template <class AF, class EPI>
; DEV void gemm_tile256(AF aptr, const u16* Bt, int ldb, int K, EPI epi, char* smem) {
;     ...
;     if (t + 1 < nk) asm volatile("s_waitcnt vmcnt(6)" ::: "memory");
;     else asm volatile("s_waitcnt vmcnt(0)" ::: "memory");
;     __builtin_amdgcn_s_barrier();
;     if (t + 2 < nk) { int nb2 = buf + 2; if (nb2 >= 3) nb2 -= 3; stage(t + 2, nb2); }
;     const unsigned sa = aoff + buf * 24576, sb = boff + buf * 24576;
;     u32x4 a0, a1, a2, a3, a4, a5, a6, a7, b0, b1, b2, b3;
;     asm volatile("ds_read_b128 %0, %1" : "=v"(b0) : "v"(sb));
;     asm volatile("ds_read_b128 %0, %1 offset:1024" : "=v"(b1) : "v"(sb));
;     asm volatile("ds_read_b128 %0, %1 offset:2048" : "=v"(b2) : "v"(sb));
;     asm volatile("ds_read_b128 %0, %1 offset:3072" : "=v"(b3) : "v"(sb));
;     asm volatile("ds_read_b128 %0, %1" : "=v"(a0) : "v"(sa));
;     asm volatile("ds_read_b128 %0, %1 offset:1024" : "=v"(a1) : "v"(sa));
;     asm volatile("ds_read_b128 %0, %1 offset:2048" : "=v"(a2) : "v"(sa));
;     asm volatile("ds_read_b128 %0, %1 offset:3072" : "=v"(a3) : "v"(sa));
;     asm volatile("ds_read_b128 %0, %1 offset:4096" : "=v"(a4) : "v"(sa));
;     asm volatile("ds_read_b128 %0, %1 offset:5120" : "=v"(a5) : "v"(sa));
;     asm volatile("ds_read_b128 %0, %1 offset:6144" : "=v"(a6) : "v"(sa));
;     asm volatile("ds_read_b128 %0, %1 offset:7168" : "=v"(a7) : "v"(sa));
;     asm volatile("s_waitcnt lgkmcnt(4)" : "+v"(a0), "+v"(a1), "+v"(a2), "+v"(a3), "+v"(b0), "+v"(b1), "+v"(b2), "+v"(b3));
;     bf16x8 Bv[4];
;     Bv[0] = __builtin_bit_cast(bf16x8, b0); Bv[1] = __builtin_bit_cast(bf16x8, b1); Bv[2] = __builtin_bit_cast(bf16x8, b2); Bv[3] = __builtin_bit_cast(bf16x8, b3);
;     {
;       bf16x8 At[4];
;       At[0] = __builtin_bit_cast(bf16x8, a0); At[1] = __builtin_bit_cast(bf16x8, a1); At[2] = __builtin_bit_cast(bf16x8, a2); At[3] = __builtin_bit_cast(bf16x8, a3);
; #pragma unroll
;       for (int m = 0; m < 4; ++m)
; #pragma unroll
;         for (int n = 0; n < 4; ++n) acc[m][n] = __builtin_amdgcn_mfma_f32_16x16x32_bf16(At[m], Bv[n], acc[m][n], 0, 0, 0);
;     }
;     asm volatile("s_waitcnt lgkmcnt(0)" : "+v"(a4), "+v"(a5), "+v"(a6), "+v"(a7));
;     {
;       bf16x8 At[4];
;       At[0] = __builtin_bit_cast(bf16x8, a4); At[1] = __builtin_bit_cast(bf16x8, a5); At[2] = __builtin_bit_cast(bf16x8, a6); At[3] = __builtin_bit_cast(bf16x8, a7);
.LBB0_1373:
	s_barrier
	s_mul_i32 s8, s1, 0x6000
	v_add_u32_e32 v130, s8, v149
	v_add_u32_e32 v151, s8, v150
	ds_read_b128 v[152:155], v151
	ds_read_b128 v[156:159], v151 offset:1024
	ds_read_b128 v[160:163], v151 offset:2048
	ds_read_b128 v[164:167], v151 offset:3072
	ds_read_b128 v[168:171], v130
	ds_read_b128 v[172:175], v130 offset:1024
	ds_read_b128 v[176:179], v130 offset:2048
	ds_read_b128 v[180:183], v130 offset:3072
	ds_read_b128 v[184:187], v130 offset:4096
	ds_read_b128 v[188:191], v130 offset:5120
	ds_read_b128 v[192:195], v130 offset:6144
	ds_read_b128 v[196:199], v130 offset:7168
	s_cmp_gt_u32 s26, 61
	s_cbranch_scc1 .Lgnodma_g0
	s_cmp_gt_i32 s1, 0
	s_cselect_b32 s8, -1, 2
	s_add_i32 s8, s8, s1
	s_mulk_i32 s8, 0x6000
	v_add_u32_e32 v252, s8, v148
	s_nop 0
	v_readfirstlane_b32 s8, v252
	s_waitcnt lgkmcnt(7)
	v_mfma_f32_16x16x32_bf16 v[126:129], v[168:171], v[152:155], v[126:129]
	v_mfma_f32_16x16x32_bf16 v[122:125], v[168:171], v[156:159], v[122:125]
	v_mfma_f32_16x16x32_bf16 v[118:121], v[168:171], v[160:163], v[118:121]
	v_mfma_f32_16x16x32_bf16 v[114:117], v[168:171], v[164:167], v[114:117]
	s_lshl_b64 s[30:31], s[6:7], 14
	v_lshl_add_u64 v[250:251], v[132:133], 0, s[30:31]
	s_mov_b32 m0, s8
	s_nop 0
	global_load_lds_dwordx4 v[250:251], off
	s_waitcnt lgkmcnt(6)
	v_mfma_f32_16x16x32_bf16 v[110:113], v[172:175], v[152:155], v[110:113]
	v_mfma_f32_16x16x32_bf16 v[106:109], v[172:175], v[156:159], v[106:109]
	v_mfma_f32_16x16x32_bf16 v[102:105], v[172:175], v[160:163], v[102:105]
	v_mfma_f32_16x16x32_bf16 v[98:101], v[172:175], v[164:167], v[98:101]
	v_lshl_add_u64 v[250:251], v[134:135], 0, s[30:31]
	s_add_u32 m0, s8, 0x1000
	s_nop 0
	global_load_lds_dwordx4 v[250:251], off
	s_waitcnt lgkmcnt(5)
	v_mfma_f32_16x16x32_bf16 v[94:97], v[176:179], v[152:155], v[94:97]
	v_mfma_f32_16x16x32_bf16 v[42:45], v[176:179], v[156:159], v[42:45]
	v_mfma_f32_16x16x32_bf16 v[38:41], v[176:179], v[160:163], v[38:41]
	v_mfma_f32_16x16x32_bf16 v[34:37], v[176:179], v[164:167], v[34:37]
	v_lshl_add_u64 v[250:251], v[136:137], 0, s[30:31]
	s_add_u32 m0, s8, 0x2000
	s_nop 0
	global_load_lds_dwordx4 v[250:251], off
	s_waitcnt lgkmcnt(4)
	v_mfma_f32_16x16x32_bf16 v[30:33], v[180:183], v[152:155], v[30:33]
	v_mfma_f32_16x16x32_bf16 v[26:29], v[180:183], v[156:159], v[26:29]
	v_mfma_f32_16x16x32_bf16 v[22:25], v[180:183], v[160:163], v[22:25]
	v_mfma_f32_16x16x32_bf16 v[18:21], v[180:183], v[164:167], v[18:21]
	v_lshl_add_u64 v[250:251], v[138:139], 0, s[30:31]
	s_add_u32 m0, s8, 0x3000
	s_nop 0
	global_load_lds_dwordx4 v[250:251], off
	s_waitcnt lgkmcnt(3)
	v_mfma_f32_16x16x32_bf16 v[14:17], v[184:187], v[152:155], v[14:17]
	v_mfma_f32_16x16x32_bf16 v[10:13], v[184:187], v[156:159], v[10:13]
	v_mfma_f32_16x16x32_bf16 v[6:9], v[184:187], v[160:163], v[6:9]
	v_mfma_f32_16x16x32_bf16 v[2:5], v[184:187], v[164:167], v[2:5]
	v_lshl_add_u64 v[250:251], v[142:143], 0, s[6:7]
	s_add_u32 m0, s8, 0x4000
	s_nop 0
	global_load_lds_dwordx4 v[250:251], off
	s_waitcnt lgkmcnt(2)
	v_mfma_f32_16x16x32_bf16 v[46:49], v[188:191], v[152:155], v[46:49]
	v_mfma_f32_16x16x32_bf16 v[50:53], v[188:191], v[156:159], v[50:53]
	v_mfma_f32_16x16x32_bf16 v[54:57], v[188:191], v[160:163], v[54:57]
	v_mfma_f32_16x16x32_bf16 v[58:61], v[188:191], v[164:167], v[58:61]
	v_lshl_add_u64 v[250:251], v[140:141], 0, s[6:7]
	s_add_u32 m0, s8, 0x5000
	s_nop 0
	global_load_lds_dwordx4 v[250:251], off
	s_waitcnt lgkmcnt(1)
	v_mfma_f32_16x16x32_bf16 v[62:65], v[192:195], v[152:155], v[62:65]
	v_mfma_f32_16x16x32_bf16 v[66:69], v[192:195], v[156:159], v[66:69]
	v_mfma_f32_16x16x32_bf16 v[70:73], v[192:195], v[160:163], v[70:73]
	v_mfma_f32_16x16x32_bf16 v[74:77], v[192:195], v[164:167], v[74:77]
	s_waitcnt lgkmcnt(0)
	v_mfma_f32_16x16x32_bf16 v[78:81], v[196:199], v[152:155], v[78:81]
	v_mfma_f32_16x16x32_bf16 v[82:85], v[196:199], v[156:159], v[82:85]
	v_mfma_f32_16x16x32_bf16 v[86:89], v[196:199], v[160:163], v[86:89]
	v_mfma_f32_16x16x32_bf16 v[90:93], v[196:199], v[164:167], v[90:93]
	s_branch .Lgjoin_g0

; template <class AF, class EPI>
; DEV void gemm_tile256(AF aptr, const u16* Bt, int ldb, int K, EPI epi, char* smem) {
;     ...
;   for (int t = 0; t < nk; ++t) {
;     ...
;     buf = (buf == 2) ? 0 : buf + 1;
;   }
.Lgjoin_g0:
	s_add_i32 s8, s1, 1
	s_cmp_lg_u32 s1, 2
	s_cselect_b32 s1, s8, 0
	s_add_u32 s6, s6, 64
	s_addc_u32 s7, s7, 0
	s_add_i32 s26, s26, 1
	s_cmpk_eq_i32 s6, 0x1000
	s_cbranch_scc0 .LBB0_1369

; DEV int ltid() { int t = threadIdx.x; asm volatile("" : "+v"(t)); return t; }
; DEV float bflo(unsigned u) { return __uint_as_float(u << 16); }
; DEV float bfhi(unsigned u) { return __uint_as_float(u & 0xffff0000u); }
; DEV void peer_gather_token(const Params& p, int tok) {
;   const int lane = ltid() & 63, b = tok >> 11;
;   float hx[32], acc[32];
;   {
;     const u16* hr = p.h + (size_t)tok * 2048 + lane * 32;
; #pragma unroll
;     for (int q = 0; q < 4; ++q) {
;       u32x4 v = *(const u32x4*)(hr + q * 8);
; #pragma unroll
;       for (int e = 0; e < 4; ++e) { hx[q * 8 + 2 * e] = bflo(v[e]); hx[q * 8 + 2 * e + 1] = bfhi(v[e]); }
;     }
;   }
; #pragma unroll
;   for (int e = 0; e < 32; ++e) acc[e] = 0.f;
;   const int e0 = p.eidx[(size_t)tok * 128 + lane], e1 = p.eidx[(size_t)tok * 128 + 64 + lane];
;   const int g0 = __builtin_bit_cast(int, p.gw[(size_t)tok * 128 + lane]), g1 = __builtin_bit_cast(int, p.gw[(size_t)tok * 128 + 64 + lane]);
;   u32x2 dn[4][3], up[4][3];
.LBB0_1567:
	s_or_b64 exec, exec, s[0:1]
	s_waitcnt lgkmcnt(0)
	s_barrier
	s_mov_b64 exec, -1
	v_lshrrev_b32_e32 v2, 6, v0
	v_and_b32_e32 v3, 63, v0
	s_nop 0
	v_readfirstlane_b32 s38, v2
	s_add_i32 s20, s84, s38
	s_mov_b32 s90, s38
	s_lshl_b32 s21, s92, 2
	s_cmpk_lt_u32 s20, 0x4000
	s_cbranch_scc0 .Lp12_end
	v_lshlrev_b32_e32 v1, 4, v3
	v_lshlrev_b32_e32 v242, 2, v3
	v_lshlrev_b32_e32 v243, 3, v3
	v_lshlrev_b32_e32 v244, 4, v3
	v_add_u32_e32 v245, 0x1000, v244
	v_lshrrev_b32_e32 v2, 3, v3
	v_and_b32_e32 v246, 7, v3
	v_lshlrev_b32_e32 v2, 20, v2
	v_lshl_or_b32 v246, v246, 3, v2
	v_add_u32_e32 v247, 0x800000, v246
	v_add_u32_e32 v248, 0x1000000, v246
	v_add_u32_e32 v249, 0x1800000, v246
	v_add_u32_e32 v250, 0x2000000, v246
	v_add_u32_e32 v251, 0x2800000, v246
	v_add_u32_e32 v252, 0x3000000, v246
	v_add_u32_e32 v253, 0x3800000, v246
	v_mov_b32_e32 v212, 0x3c800000
	v_mov_b32_e32 v213, 0x3ba10414
	v_mov_b32_e32 v214, 0xb9c68948
	v_mov_b32_e32 v215, 0x7f800000
	v_mov_b32_e32 v207, 0
	s_mov_b32 s9, 0x378e98ab
	s_mov_b32 s10, 0x3b7cd369
	s_mov_b32 s11, 0xbcc618b2
	s_mov_b32 s12, 0x3dda74e4
	s_mov_b32 s13, 0x3f228afd
	s_mov_b32 s14, 0x3e03c728
	s_mov_b32 s15, 0xbfb8aa3b
	s_mov_b32 s16, 0x42ce8ed0
	s_mov_b32 s17, 0xc2b17218
	s_brev_b32 s18, -2
	s_mov_b32 s43, 1
	s_lshl_b32 s38, s20, 9
	s_add_u32 s58, s66, s38
	s_addc_u32 s59, s67, 0
	global_load_dword v216, v242, s[58:59]
	global_load_dword v217, v242, s[58:59] offset:256
	s_add_u32 s58, s68, s38
	s_addc_u32 s59, s69, 0
	global_load_dword v218, v242, s[58:59]
	global_load_dword v219, v242, s[58:59] offset:256
	s_lshl_b32 s38, s20, 6
	s_add_u32 s58, s80, s38
	s_addc_u32 s59, s81, 0
	global_load_dwordx2 v[220:221], v246, s[58:59]
	global_load_dwordx2 v[222:223], v247, s[58:59]
	global_load_dwordx2 v[224:225], v248, s[58:59]
	global_load_dwordx2 v[226:227], v249, s[58:59]
	global_load_dwordx2 v[228:229], v250, s[58:59]
	global_load_dwordx2 v[230:231], v251, s[58:59]
	global_load_dwordx2 v[232:233], v252, s[58:59]
	global_load_dwordx2 v[234:235], v253, s[58:59]
	s_waitcnt vmcnt(0) lgkmcnt(0)
	s_mov_b32 s36, 0
	s_mov_b32 s37, 0
	v_and_b32_e32 v236, 63, v0
	v_lshrrev_b32_e32 v241, 6, v0
	v_lshl_or_b32 v237, v216, 7, v236
	v_or_b32_e32 v238, 64, v236
	v_lshl_or_b32 v238, v217, 7, v238
	v_mov_b32_e32 v239, 0
	v_mov_b32_e32 v240, 0
	v_lshlrev_b32_e32 v241, 10, v241
	v_lshl_add_u32 v241, v236, 2, v241
	v_readlane_b32 s46, v237, 0
	v_readlane_b32 s47, v238, 0
	s_nop 1
	v_cmp_lt_u32_e64 s[48:49], s46, v237
	v_cmp_lt_u32_e64 s[50:51], s46, v238
	v_cmp_lt_u32_e64 s[52:53], s47, v237
	v_cmp_lt_u32_e64 s[54:55], s47, v238
	v_readlane_b32 s46, v237, 1
	v_readlane_b32 s47, v238, 1
	v_addc_co_u32_e64 v239, s[56:57], 0, v239, s[48:49]
	v_addc_co_u32_e64 v240, s[56:57], 0, v240, s[50:51]
	v_addc_co_u32_e64 v239, s[56:57], 0, v239, s[52:53]
	v_addc_co_u32_e64 v240, s[56:57], 0, v240, s[54:55]
	v_cmp_lt_u32_e64 s[48:49], s46, v237
	v_cmp_lt_u32_e64 s[50:51], s46, v238
	v_cmp_lt_u32_e64 s[52:53], s47, v237
	v_cmp_lt_u32_e64 s[54:55], s47, v238
	v_readlane_b32 s46, v237, 2
	v_readlane_b32 s47, v238, 2
	v_addc_co_u32_e64 v239, s[56:57], 0, v239, s[48:49]
	v_addc_co_u32_e64 v240, s[56:57], 0, v240, s[50:51]
	v_addc_co_u32_e64 v239, s[56:57], 0, v239, s[52:53]
	v_addc_co_u32_e64 v240, s[56:57], 0, v240, s[54:55]
	v_cmp_lt_u32_e64 s[48:49], s46, v237
	v_cmp_lt_u32_e64 s[50:51], s46, v238
	v_cmp_lt_u32_e64 s[52:53], s47, v237
	v_cmp_lt_u32_e64 s[54:55], s47, v238
	v_readlane_b32 s46, v237, 3
	v_readlane_b32 s47, v238, 3
	v_addc_co_u32_e64 v239, s[56:57], 0, v239, s[48:49]
	v_addc_co_u32_e64 v240, s[56:57], 0, v240, s[50:51]
	v_addc_co_u32_e64 v239, s[56:57], 0, v239, s[52:53]
	v_addc_co_u32_e64 v240, s[56:57], 0, v240, s[54:55]
	v_cmp_lt_u32_e64 s[48:49], s46, v237
	v_cmp_lt_u32_e64 s[50:51], s46, v238
	v_cmp_lt_u32_e64 s[52:53], s47, v237
	v_cmp_lt_u32_e64 s[54:55], s47, v238
	v_readlane_b32 s46, v237, 4
	v_readlane_b32 s47, v238, 4
	v_addc_co_u32_e64 v239, s[56:57], 0, v239, s[48:49]
	v_addc_co_u32_e64 v240, s[56:57], 0, v240, s[50:51]
	v_addc_co_u32_e64 v239, s[56:57], 0, v239, s[52:53]
	v_addc_co_u32_e64 v240, s[56:57], 0, v240, s[54:55]
	v_cmp_lt_u32_e64 s[48:49], s46, v237
	v_cmp_lt_u32_e64 s[50:51], s46, v238
	v_cmp_lt_u32_e64 s[52:53], s47, v237
	v_cmp_lt_u32_e64 s[54:55], s47, v238
	v_readlane_b32 s46, v237, 5
	v_readlane_b32 s47, v238, 5
	v_addc_co_u32_e64 v239, s[56:57], 0, v239, s[48:49]
	v_addc_co_u32_e64 v240, s[56:57], 0, v240, s[50:51]
	v_addc_co_u32_e64 v239, s[56:57], 0, v239, s[52:53]
	v_addc_co_u32_e64 v240, s[56:57], 0, v240, s[54:55]
	v_cmp_lt_u32_e64 s[48:49], s46, v237
	v_cmp_lt_u32_e64 s[50:51], s46, v238
	v_cmp_lt_u32_e64 s[52:53], s47, v237
	v_cmp_lt_u32_e64 s[54:55], s47, v238
	v_readlane_b32 s46, v237, 6
	v_readlane_b32 s47, v238, 6
	v_addc_co_u32_e64 v239, s[56:57], 0, v239, s[48:49]
	v_addc_co_u32_e64 v240, s[56:57], 0, v240, s[50:51]
	v_addc_co_u32_e64 v239, s[56:57], 0, v239, s[52:53]
	v_addc_co_u32_e64 v240, s[56:57], 0, v240, s[54:55]
	v_cmp_lt_u32_e64 s[48:49], s46, v237
	v_cmp_lt_u32_e64 s[50:51], s46, v238
	v_cmp_lt_u32_e64 s[52:53], s47, v237
	v_cmp_lt_u32_e64 s[54:55], s47, v238
	v_readlane_b32 s46, v237, 7
	v_readlane_b32 s47, v238, 7
	v_addc_co_u32_e64 v239, s[56:57], 0, v239, s[48:49]
	v_addc_co_u32_e64 v240, s[56:57], 0, v240, s[50:51]
	v_addc_co_u32_e64 v239, s[56:57], 0, v239, s[52:53]
	v_addc_co_u32_e64 v240, s[56:57], 0, v240, s[54:55]
	v_cmp_lt_u32_e64 s[48:49], s46, v237
	v_cmp_lt_u32_e64 s[50:51], s46, v238
	v_cmp_lt_u32_e64 s[52:53], s47, v237
	v_cmp_lt_u32_e64 s[54:55], s47, v238
	v_readlane_b32 s46, v237, 8
	v_readlane_b32 s47, v238, 8
	v_addc_co_u32_e64 v239, s[56:57], 0, v239, s[48:49]
; DEV void peer_gather_token(const Params& p, int tok) {
;     ...
;   const int e0 = p.eidx[(size_t)tok * 128 + lane], e1 = p.eidx[(size_t)tok * 128 + 64 + lane];
;   const int g0 = __builtin_bit_cast(int, p.gw[(size_t)tok * 128 + lane]), g1 = __builtin_bit_cast(int, p.gw[(size_t)tok * 128 + 64 + lane]);
;   u32x2 dn[4][3], up[4][3];
;   auto issue = [&](int k, int slot) {
;     const int e = (k < 64) ? __builtin_amdgcn_readlane(e0, k) : __builtin_amdgcn_readlane(e1, k - 64);
	v_addc_co_u32_e64 v240, s[56:57], 0, v240, s[50:51]
	v_addc_co_u32_e64 v239, s[56:57], 0, v239, s[52:53]
	v_addc_co_u32_e64 v240, s[56:57], 0, v240, s[54:55]
	v_cmp_lt_u32_e64 s[48:49], s46, v237
	v_cmp_lt_u32_e64 s[50:51], s46, v238
	v_cmp_lt_u32_e64 s[52:53], s47, v237
	v_cmp_lt_u32_e64 s[54:55], s47, v238
	v_readlane_b32 s46, v237, 9
	v_readlane_b32 s47, v238, 9
	v_addc_co_u32_e64 v239, s[56:57], 0, v239, s[48:49]
	v_addc_co_u32_e64 v240, s[56:57], 0, v240, s[50:51]
	v_addc_co_u32_e64 v239, s[56:57], 0, v239, s[52:53]
	v_addc_co_u32_e64 v240, s[56:57], 0, v240, s[54:55]
	v_cmp_lt_u32_e64 s[48:49], s46, v237
	v_cmp_lt_u32_e64 s[50:51], s46, v238
	v_cmp_lt_u32_e64 s[52:53], s47, v237
	v_cmp_lt_u32_e64 s[54:55], s47, v238
	v_readlane_b32 s46, v237, 10
	v_readlane_b32 s47, v238, 10
	v_addc_co_u32_e64 v239, s[56:57], 0, v239, s[48:49]
	v_addc_co_u32_e64 v240, s[56:57], 0, v240, s[50:51]
	v_addc_co_u32_e64 v239, s[56:57], 0, v239, s[52:53]
	v_addc_co_u32_e64 v240, s[56:57], 0, v240, s[54:55]
	v_cmp_lt_u32_e64 s[48:49], s46, v237
	v_cmp_lt_u32_e64 s[50:51], s46, v238
	v_cmp_lt_u32_e64 s[52:53], s47, v237
	v_cmp_lt_u32_e64 s[54:55], s47, v238
	v_readlane_b32 s46, v237, 11
	v_readlane_b32 s47, v238, 11
	v_addc_co_u32_e64 v239, s[56:57], 0, v239, s[48:49]
	v_addc_co_u32_e64 v240, s[56:57], 0, v240, s[50:51]
	v_addc_co_u32_e64 v239, s[56:57], 0, v239, s[52:53]
	v_addc_co_u32_e64 v240, s[56:57], 0, v240, s[54:55]
	v_cmp_lt_u32_e64 s[48:49], s46, v237
	v_cmp_lt_u32_e64 s[50:51], s46, v238
	v_cmp_lt_u32_e64 s[52:53], s47, v237
	v_cmp_lt_u32_e64 s[54:55], s47, v238
	v_readlane_b32 s46, v237, 12
	v_readlane_b32 s47, v238, 12
	v_addc_co_u32_e64 v239, s[56:57], 0, v239, s[48:49]
	v_addc_co_u32_e64 v240, s[56:57], 0, v240, s[50:51]
	v_addc_co_u32_e64 v239, s[56:57], 0, v239, s[52:53]
	v_addc_co_u32_e64 v240, s[56:57], 0, v240, s[54:55]
	v_cmp_lt_u32_e64 s[48:49], s46, v237
	v_cmp_lt_u32_e64 s[50:51], s46, v238
	v_cmp_lt_u32_e64 s[52:53], s47, v237
	v_cmp_lt_u32_e64 s[54:55], s47, v238
	v_readlane_b32 s46, v237, 13
	v_readlane_b32 s47, v238, 13
	v_addc_co_u32_e64 v239, s[56:57], 0, v239, s[48:49]
	v_addc_co_u32_e64 v240, s[56:57], 0, v240, s[50:51]
	v_addc_co_u32_e64 v239, s[56:57], 0, v239, s[52:53]
	v_addc_co_u32_e64 v240, s[56:57], 0, v240, s[54:55]
	v_cmp_lt_u32_e64 s[48:49], s46, v237
	v_cmp_lt_u32_e64 s[50:51], s46, v238
	v_cmp_lt_u32_e64 s[52:53], s47, v237
	v_cmp_lt_u32_e64 s[54:55], s47, v238
	v_readlane_b32 s46, v237, 14
	v_readlane_b32 s47, v238, 14
	v_addc_co_u32_e64 v239, s[56:57], 0, v239, s[48:49]
	v_addc_co_u32_e64 v240, s[56:57], 0, v240, s[50:51]
	v_addc_co_u32_e64 v239, s[56:57], 0, v239, s[52:53]
	v_addc_co_u32_e64 v240, s[56:57], 0, v240, s[54:55]
	v_cmp_lt_u32_e64 s[48:49], s46, v237
	v_cmp_lt_u32_e64 s[50:51], s46, v238
	v_cmp_lt_u32_e64 s[52:53], s47, v237
	v_cmp_lt_u32_e64 s[54:55], s47, v238
	v_readlane_b32 s46, v237, 15
	v_readlane_b32 s47, v238, 15
	v_addc_co_u32_e64 v239, s[56:57], 0, v239, s[48:49]
	v_addc_co_u32_e64 v240, s[56:57], 0, v240, s[50:51]
	v_addc_co_u32_e64 v239, s[56:57], 0, v239, s[52:53]
	v_addc_co_u32_e64 v240, s[56:57], 0, v240, s[54:55]
	v_cmp_lt_u32_e64 s[48:49], s46, v237
	v_cmp_lt_u32_e64 s[50:51], s46, v238
	v_cmp_lt_u32_e64 s[52:53], s47, v237
	v_cmp_lt_u32_e64 s[54:55], s47, v238
	v_readlane_b32 s46, v237, 16
	v_readlane_b32 s47, v238, 16
	v_addc_co_u32_e64 v239, s[56:57], 0, v239, s[48:49]
	v_addc_co_u32_e64 v240, s[56:57], 0, v240, s[50:51]
	v_addc_co_u32_e64 v239, s[56:57], 0, v239, s[52:53]
	v_addc_co_u32_e64 v240, s[56:57], 0, v240, s[54:55]
	v_cmp_lt_u32_e64 s[48:49], s46, v237
	v_cmp_lt_u32_e64 s[50:51], s46, v238
	v_cmp_lt_u32_e64 s[52:53], s47, v237
	v_cmp_lt_u32_e64 s[54:55], s47, v238
	v_readlane_b32 s46, v237, 17
	v_readlane_b32 s47, v238, 17
	v_addc_co_u32_e64 v239, s[56:57], 0, v239, s[48:49]
	v_addc_co_u32_e64 v240, s[56:57], 0, v240, s[50:51]
	v_addc_co_u32_e64 v239, s[56:57], 0, v239, s[52:53]
	v_addc_co_u32_e64 v240, s[56:57], 0, v240, s[54:55]
	v_cmp_lt_u32_e64 s[48:49], s46, v237
	v_cmp_lt_u32_e64 s[50:51], s46, v238
	v_cmp_lt_u32_e64 s[52:53], s47, v237
	v_cmp_lt_u32_e64 s[54:55], s47, v238
	v_readlane_b32 s46, v237, 18
	v_readlane_b32 s47, v238, 18
	v_addc_co_u32_e64 v239, s[56:57], 0, v239, s[48:49]
	v_addc_co_u32_e64 v240, s[56:57], 0, v240, s[50:51]
	v_addc_co_u32_e64 v239, s[56:57], 0, v239, s[52:53]
	v_addc_co_u32_e64 v240, s[56:57], 0, v240, s[54:55]
	v_cmp_lt_u32_e64 s[48:49], s46, v237
	v_cmp_lt_u32_e64 s[50:51], s46, v238
	v_cmp_lt_u32_e64 s[52:53], s47, v237
	v_cmp_lt_u32_e64 s[54:55], s47, v238
	v_readlane_b32 s46, v237, 19
	v_readlane_b32 s47, v238, 19
	v_addc_co_u32_e64 v239, s[56:57], 0, v239, s[48:49]
	v_addc_co_u32_e64 v240, s[56:57], 0, v240, s[50:51]
	v_addc_co_u32_e64 v239, s[56:57], 0, v239, s[52:53]
	v_addc_co_u32_e64 v240, s[56:57], 0, v240, s[54:55]
	v_cmp_lt_u32_e64 s[48:49], s46, v237
	v_cmp_lt_u32_e64 s[50:51], s46, v238
	v_cmp_lt_u32_e64 s[52:53], s47, v237
	v_cmp_lt_u32_e64 s[54:55], s47, v238
	v_readlane_b32 s46, v237, 20
	v_readlane_b32 s47, v238, 20
	v_addc_co_u32_e64 v239, s[56:57], 0, v239, s[48:49]
	v_addc_co_u32_e64 v240, s[56:57], 0, v240, s[50:51]
	v_addc_co_u32_e64 v239, s[56:57], 0, v239, s[52:53]
	v_addc_co_u32_e64 v240, s[56:57], 0, v240, s[54:55]
	v_cmp_lt_u32_e64 s[48:49], s46, v237
	v_cmp_lt_u32_e64 s[50:51], s46, v238
	v_cmp_lt_u32_e64 s[52:53], s47, v237
	v_cmp_lt_u32_e64 s[54:55], s47, v238
	v_readlane_b32 s46, v237, 21
	v_readlane_b32 s47, v238, 21
	v_addc_co_u32_e64 v239, s[56:57], 0, v239, s[48:49]
	v_addc_co_u32_e64 v240, s[56:57], 0, v240, s[50:51]
	v_addc_co_u32_e64 v239, s[56:57], 0, v239, s[52:53]
; DEV void peer_gather_token(const Params& p, int tok) {
;     ...
;   const int e0 = p.eidx[(size_t)tok * 128 + lane], e1 = p.eidx[(size_t)tok * 128 + 64 + lane];
;   const int g0 = __builtin_bit_cast(int, p.gw[(size_t)tok * 128 + lane]), g1 = __builtin_bit_cast(int, p.gw[(size_t)tok * 128 + 64 + lane]);
;   u32x2 dn[4][3], up[4][3];
;   auto issue = [&](int k, int slot) {
;     const int e = (k < 64) ? __builtin_amdgcn_readlane(e0, k) : __builtin_amdgcn_readlane(e1, k - 64);
	v_addc_co_u32_e64 v240, s[56:57], 0, v240, s[54:55]
	v_cmp_lt_u32_e64 s[48:49], s46, v237
	v_cmp_lt_u32_e64 s[50:51], s46, v238
	v_cmp_lt_u32_e64 s[52:53], s47, v237
	v_cmp_lt_u32_e64 s[54:55], s47, v238
	v_readlane_b32 s46, v237, 22
	v_readlane_b32 s47, v238, 22
	v_addc_co_u32_e64 v239, s[56:57], 0, v239, s[48:49]
	v_addc_co_u32_e64 v240, s[56:57], 0, v240, s[50:51]
	v_addc_co_u32_e64 v239, s[56:57], 0, v239, s[52:53]
	v_addc_co_u32_e64 v240, s[56:57], 0, v240, s[54:55]
	v_cmp_lt_u32_e64 s[48:49], s46, v237
	v_cmp_lt_u32_e64 s[50:51], s46, v238
	v_cmp_lt_u32_e64 s[52:53], s47, v237
	v_cmp_lt_u32_e64 s[54:55], s47, v238
	v_readlane_b32 s46, v237, 23
	v_readlane_b32 s47, v238, 23
	v_addc_co_u32_e64 v239, s[56:57], 0, v239, s[48:49]
	v_addc_co_u32_e64 v240, s[56:57], 0, v240, s[50:51]
	v_addc_co_u32_e64 v239, s[56:57], 0, v239, s[52:53]
	v_addc_co_u32_e64 v240, s[56:57], 0, v240, s[54:55]
	v_cmp_lt_u32_e64 s[48:49], s46, v237
	v_cmp_lt_u32_e64 s[50:51], s46, v238
	v_cmp_lt_u32_e64 s[52:53], s47, v237
	v_cmp_lt_u32_e64 s[54:55], s47, v238
	v_readlane_b32 s46, v237, 24
	v_readlane_b32 s47, v238, 24
	v_addc_co_u32_e64 v239, s[56:57], 0, v239, s[48:49]
	v_addc_co_u32_e64 v240, s[56:57], 0, v240, s[50:51]
	v_addc_co_u32_e64 v239, s[56:57], 0, v239, s[52:53]
	v_addc_co_u32_e64 v240, s[56:57], 0, v240, s[54:55]
	v_cmp_lt_u32_e64 s[48:49], s46, v237
	v_cmp_lt_u32_e64 s[50:51], s46, v238
	v_cmp_lt_u32_e64 s[52:53], s47, v237
	v_cmp_lt_u32_e64 s[54:55], s47, v238
	v_readlane_b32 s46, v237, 25
	v_readlane_b32 s47, v238, 25
	v_addc_co_u32_e64 v239, s[56:57], 0, v239, s[48:49]
	v_addc_co_u32_e64 v240, s[56:57], 0, v240, s[50:51]
	v_addc_co_u32_e64 v239, s[56:57], 0, v239, s[52:53]
	v_addc_co_u32_e64 v240, s[56:57], 0, v240, s[54:55]
	v_cmp_lt_u32_e64 s[48:49], s46, v237
	v_cmp_lt_u32_e64 s[50:51], s46, v238
	v_cmp_lt_u32_e64 s[52:53], s47, v237
	v_cmp_lt_u32_e64 s[54:55], s47, v238
	v_readlane_b32 s46, v237, 26
	v_readlane_b32 s47, v238, 26
	v_addc_co_u32_e64 v239, s[56:57], 0, v239, s[48:49]
	v_addc_co_u32_e64 v240, s[56:57], 0, v240, s[50:51]
	v_addc_co_u32_e64 v239, s[56:57], 0, v239, s[52:53]
	v_addc_co_u32_e64 v240, s[56:57], 0, v240, s[54:55]
	v_cmp_lt_u32_e64 s[48:49], s46, v237
	v_cmp_lt_u32_e64 s[50:51], s46, v238
	v_cmp_lt_u32_e64 s[52:53], s47, v237
	v_cmp_lt_u32_e64 s[54:55], s47, v238
	v_readlane_b32 s46, v237, 27
	v_readlane_b32 s47, v238, 27
	v_addc_co_u32_e64 v239, s[56:57], 0, v239, s[48:49]
	v_addc_co_u32_e64 v240, s[56:57], 0, v240, s[50:51]
	v_addc_co_u32_e64 v239, s[56:57], 0, v239, s[52:53]
	v_addc_co_u32_e64 v240, s[56:57], 0, v240, s[54:55]
	v_cmp_lt_u32_e64 s[48:49], s46, v237
	v_cmp_lt_u32_e64 s[50:51], s46, v238
	v_cmp_lt_u32_e64 s[52:53], s47, v237
	v_cmp_lt_u32_e64 s[54:55], s47, v238
	v_readlane_b32 s46, v237, 28
	v_readlane_b32 s47, v238, 28
	v_addc_co_u32_e64 v239, s[56:57], 0, v239, s[48:49]
	v_addc_co_u32_e64 v240, s[56:57], 0, v240, s[50:51]
	v_addc_co_u32_e64 v239, s[56:57], 0, v239, s[52:53]
	v_addc_co_u32_e64 v240, s[56:57], 0, v240, s[54:55]
	v_cmp_lt_u32_e64 s[48:49], s46, v237
	v_cmp_lt_u32_e64 s[50:51], s46, v238
	v_cmp_lt_u32_e64 s[52:53], s47, v237
	v_cmp_lt_u32_e64 s[54:55], s47, v238
	v_readlane_b32 s46, v237, 29
	v_readlane_b32 s47, v238, 29
	v_addc_co_u32_e64 v239, s[56:57], 0, v239, s[48:49]
	v_addc_co_u32_e64 v240, s[56:57], 0, v240, s[50:51]
	v_addc_co_u32_e64 v239, s[56:57], 0, v239, s[52:53]
	v_addc_co_u32_e64 v240, s[56:57], 0, v240, s[54:55]
	v_cmp_lt_u32_e64 s[48:49], s46, v237
	v_cmp_lt_u32_e64 s[50:51], s46, v238
	v_cmp_lt_u32_e64 s[52:53], s47, v237
	v_cmp_lt_u32_e64 s[54:55], s47, v238
	v_readlane_b32 s46, v237, 30
	v_readlane_b32 s47, v238, 30
	v_addc_co_u32_e64 v239, s[56:57], 0, v239, s[48:49]
	v_addc_co_u32_e64 v240, s[56:57], 0, v240, s[50:51]
	v_addc_co_u32_e64 v239, s[56:57], 0, v239, s[52:53]
	v_addc_co_u32_e64 v240, s[56:57], 0, v240, s[54:55]
	v_cmp_lt_u32_e64 s[48:49], s46, v237
	v_cmp_lt_u32_e64 s[50:51], s46, v238
	v_cmp_lt_u32_e64 s[52:53], s47, v237
	v_cmp_lt_u32_e64 s[54:55], s47, v238
	v_readlane_b32 s46, v237, 31
	v_readlane_b32 s47, v238, 31
	v_addc_co_u32_e64 v239, s[56:57], 0, v239, s[48:49]
	v_addc_co_u32_e64 v240, s[56:57], 0, v240, s[50:51]
	v_addc_co_u32_e64 v239, s[56:57], 0, v239, s[52:53]
	v_addc_co_u32_e64 v240, s[56:57], 0, v240, s[54:55]
	v_cmp_lt_u32_e64 s[48:49], s46, v237
	v_cmp_lt_u32_e64 s[50:51], s46, v238
	v_cmp_lt_u32_e64 s[52:53], s47, v237
	v_cmp_lt_u32_e64 s[54:55], s47, v238
	v_readlane_b32 s46, v237, 32
	v_readlane_b32 s47, v238, 32
	v_addc_co_u32_e64 v239, s[56:57], 0, v239, s[48:49]
	v_addc_co_u32_e64 v240, s[56:57], 0, v240, s[50:51]
	v_addc_co_u32_e64 v239, s[56:57], 0, v239, s[52:53]
	v_addc_co_u32_e64 v240, s[56:57], 0, v240, s[54:55]
	v_cmp_lt_u32_e64 s[48:49], s46, v237
	v_cmp_lt_u32_e64 s[50:51], s46, v238
	v_cmp_lt_u32_e64 s[52:53], s47, v237
	v_cmp_lt_u32_e64 s[54:55], s47, v238
	v_readlane_b32 s46, v237, 33
	v_readlane_b32 s47, v238, 33
	v_addc_co_u32_e64 v239, s[56:57], 0, v239, s[48:49]
	v_addc_co_u32_e64 v240, s[56:57], 0, v240, s[50:51]
	v_addc_co_u32_e64 v239, s[56:57], 0, v239, s[52:53]
	v_addc_co_u32_e64 v240, s[56:57], 0, v240, s[54:55]
	v_cmp_lt_u32_e64 s[48:49], s46, v237
	v_cmp_lt_u32_e64 s[50:51], s46, v238
	v_cmp_lt_u32_e64 s[52:53], s47, v237
	v_cmp_lt_u32_e64 s[54:55], s47, v238
	v_readlane_b32 s46, v237, 34
	v_readlane_b32 s47, v238, 34
	v_addc_co_u32_e64 v239, s[56:57], 0, v239, s[48:49]
	v_addc_co_u32_e64 v240, s[56:57], 0, v240, s[50:51]
	v_addc_co_u32_e64 v239, s[56:57], 0, v239, s[52:53]
	v_addc_co_u32_e64 v240, s[56:57], 0, v240, s[54:55]
	v_cmp_lt_u32_e64 s[48:49], s46, v237
	v_cmp_lt_u32_e64 s[50:51], s46, v238
; DEV void peer_gather_token(const Params& p, int tok) {
;     ...
;   const int e0 = p.eidx[(size_t)tok * 128 + lane], e1 = p.eidx[(size_t)tok * 128 + 64 + lane];
;   const int g0 = __builtin_bit_cast(int, p.gw[(size_t)tok * 128 + lane]), g1 = __builtin_bit_cast(int, p.gw[(size_t)tok * 128 + 64 + lane]);
;   u32x2 dn[4][3], up[4][3];
;   auto issue = [&](int k, int slot) {
;     const int e = (k < 64) ? __builtin_amdgcn_readlane(e0, k) : __builtin_amdgcn_readlane(e1, k - 64);
	v_cmp_lt_u32_e64 s[52:53], s47, v237
	v_cmp_lt_u32_e64 s[54:55], s47, v238
	v_readlane_b32 s46, v237, 35
	v_readlane_b32 s47, v238, 35
	v_addc_co_u32_e64 v239, s[56:57], 0, v239, s[48:49]
	v_addc_co_u32_e64 v240, s[56:57], 0, v240, s[50:51]
	v_addc_co_u32_e64 v239, s[56:57], 0, v239, s[52:53]
	v_addc_co_u32_e64 v240, s[56:57], 0, v240, s[54:55]
	v_cmp_lt_u32_e64 s[48:49], s46, v237
	v_cmp_lt_u32_e64 s[50:51], s46, v238
	v_cmp_lt_u32_e64 s[52:53], s47, v237
	v_cmp_lt_u32_e64 s[54:55], s47, v238
	v_readlane_b32 s46, v237, 36
	v_readlane_b32 s47, v238, 36
	v_addc_co_u32_e64 v239, s[56:57], 0, v239, s[48:49]
	v_addc_co_u32_e64 v240, s[56:57], 0, v240, s[50:51]
	v_addc_co_u32_e64 v239, s[56:57], 0, v239, s[52:53]
	v_addc_co_u32_e64 v240, s[56:57], 0, v240, s[54:55]
	v_cmp_lt_u32_e64 s[48:49], s46, v237
	v_cmp_lt_u32_e64 s[50:51], s46, v238
	v_cmp_lt_u32_e64 s[52:53], s47, v237
	v_cmp_lt_u32_e64 s[54:55], s47, v238
	v_readlane_b32 s46, v237, 37
	v_readlane_b32 s47, v238, 37
	v_addc_co_u32_e64 v239, s[56:57], 0, v239, s[48:49]
	v_addc_co_u32_e64 v240, s[56:57], 0, v240, s[50:51]
	v_addc_co_u32_e64 v239, s[56:57], 0, v239, s[52:53]
	v_addc_co_u32_e64 v240, s[56:57], 0, v240, s[54:55]
	v_cmp_lt_u32_e64 s[48:49], s46, v237
	v_cmp_lt_u32_e64 s[50:51], s46, v238
	v_cmp_lt_u32_e64 s[52:53], s47, v237
	v_cmp_lt_u32_e64 s[54:55], s47, v238
	v_readlane_b32 s46, v237, 38
	v_readlane_b32 s47, v238, 38
	v_addc_co_u32_e64 v239, s[56:57], 0, v239, s[48:49]
	v_addc_co_u32_e64 v240, s[56:57], 0, v240, s[50:51]
	v_addc_co_u32_e64 v239, s[56:57], 0, v239, s[52:53]
	v_addc_co_u32_e64 v240, s[56:57], 0, v240, s[54:55]
	v_cmp_lt_u32_e64 s[48:49], s46, v237
	v_cmp_lt_u32_e64 s[50:51], s46, v238
	v_cmp_lt_u32_e64 s[52:53], s47, v237
	v_cmp_lt_u32_e64 s[54:55], s47, v238
	v_readlane_b32 s46, v237, 39
	v_readlane_b32 s47, v238, 39
	v_addc_co_u32_e64 v239, s[56:57], 0, v239, s[48:49]
	v_addc_co_u32_e64 v240, s[56:57], 0, v240, s[50:51]
	v_addc_co_u32_e64 v239, s[56:57], 0, v239, s[52:53]
	v_addc_co_u32_e64 v240, s[56:57], 0, v240, s[54:55]
	v_cmp_lt_u32_e64 s[48:49], s46, v237
	v_cmp_lt_u32_e64 s[50:51], s46, v238
	v_cmp_lt_u32_e64 s[52:53], s47, v237
	v_cmp_lt_u32_e64 s[54:55], s47, v238
	v_readlane_b32 s46, v237, 40
	v_readlane_b32 s47, v238, 40
	v_addc_co_u32_e64 v239, s[56:57], 0, v239, s[48:49]
	v_addc_co_u32_e64 v240, s[56:57], 0, v240, s[50:51]
	v_addc_co_u32_e64 v239, s[56:57], 0, v239, s[52:53]
	v_addc_co_u32_e64 v240, s[56:57], 0, v240, s[54:55]
	v_cmp_lt_u32_e64 s[48:49], s46, v237
	v_cmp_lt_u32_e64 s[50:51], s46, v238
	v_cmp_lt_u32_e64 s[52:53], s47, v237
	v_cmp_lt_u32_e64 s[54:55], s47, v238
	v_readlane_b32 s46, v237, 41
	v_readlane_b32 s47, v238, 41
	v_addc_co_u32_e64 v239, s[56:57], 0, v239, s[48:49]
	v_addc_co_u32_e64 v240, s[56:57], 0, v240, s[50:51]
	v_addc_co_u32_e64 v239, s[56:57], 0, v239, s[52:53]
	v_addc_co_u32_e64 v240, s[56:57], 0, v240, s[54:55]
	v_cmp_lt_u32_e64 s[48:49], s46, v237
	v_cmp_lt_u32_e64 s[50:51], s46, v238
	v_cmp_lt_u32_e64 s[52:53], s47, v237
	v_cmp_lt_u32_e64 s[54:55], s47, v238
	v_readlane_b32 s46, v237, 42
	v_readlane_b32 s47, v238, 42
	v_addc_co_u32_e64 v239, s[56:57], 0, v239, s[48:49]
	v_addc_co_u32_e64 v240, s[56:57], 0, v240, s[50:51]
	v_addc_co_u32_e64 v239, s[56:57], 0, v239, s[52:53]
	v_addc_co_u32_e64 v240, s[56:57], 0, v240, s[54:55]
	v_cmp_lt_u32_e64 s[48:49], s46, v237
	v_cmp_lt_u32_e64 s[50:51], s46, v238
	v_cmp_lt_u32_e64 s[52:53], s47, v237
	v_cmp_lt_u32_e64 s[54:55], s47, v238
	v_readlane_b32 s46, v237, 43
	v_readlane_b32 s47, v238, 43
	v_addc_co_u32_e64 v239, s[56:57], 0, v239, s[48:49]
	v_addc_co_u32_e64 v240, s[56:57], 0, v240, s[50:51]
	v_addc_co_u32_e64 v239, s[56:57], 0, v239, s[52:53]
	v_addc_co_u32_e64 v240, s[56:57], 0, v240, s[54:55]
	v_cmp_lt_u32_e64 s[48:49], s46, v237
	v_cmp_lt_u32_e64 s[50:51], s46, v238
	v_cmp_lt_u32_e64 s[52:53], s47, v237
	v_cmp_lt_u32_e64 s[54:55], s47, v238
	v_readlane_b32 s46, v237, 44
	v_readlane_b32 s47, v238, 44
	v_addc_co_u32_e64 v239, s[56:57], 0, v239, s[48:49]
	v_addc_co_u32_e64 v240, s[56:57], 0, v240, s[50:51]
	v_addc_co_u32_e64 v239, s[56:57], 0, v239, s[52:53]
	v_addc_co_u32_e64 v240, s[56:57], 0, v240, s[54:55]
	v_cmp_lt_u32_e64 s[48:49], s46, v237
	v_cmp_lt_u32_e64 s[50:51], s46, v238
	v_cmp_lt_u32_e64 s[52:53], s47, v237
	v_cmp_lt_u32_e64 s[54:55], s47, v238
	v_readlane_b32 s46, v237, 45
	v_readlane_b32 s47, v238, 45
	v_addc_co_u32_e64 v239, s[56:57], 0, v239, s[48:49]
	v_addc_co_u32_e64 v240, s[56:57], 0, v240, s[50:51]
	v_addc_co_u32_e64 v239, s[56:57], 0, v239, s[52:53]
	v_addc_co_u32_e64 v240, s[56:57], 0, v240, s[54:55]
	v_cmp_lt_u32_e64 s[48:49], s46, v237
	v_cmp_lt_u32_e64 s[50:51], s46, v238
	v_cmp_lt_u32_e64 s[52:53], s47, v237
	v_cmp_lt_u32_e64 s[54:55], s47, v238
	v_readlane_b32 s46, v237, 46
	v_readlane_b32 s47, v238, 46
	v_addc_co_u32_e64 v239, s[56:57], 0, v239, s[48:49]
	v_addc_co_u32_e64 v240, s[56:57], 0, v240, s[50:51]
	v_addc_co_u32_e64 v239, s[56:57], 0, v239, s[52:53]
	v_addc_co_u32_e64 v240, s[56:57], 0, v240, s[54:55]
	v_cmp_lt_u32_e64 s[48:49], s46, v237
	v_cmp_lt_u32_e64 s[50:51], s46, v238
	v_cmp_lt_u32_e64 s[52:53], s47, v237
	v_cmp_lt_u32_e64 s[54:55], s47, v238
	v_readlane_b32 s46, v237, 47
	v_readlane_b32 s47, v238, 47
	v_addc_co_u32_e64 v239, s[56:57], 0, v239, s[48:49]
	v_addc_co_u32_e64 v240, s[56:57], 0, v240, s[50:51]
	v_addc_co_u32_e64 v239, s[56:57], 0, v239, s[52:53]
	v_addc_co_u32_e64 v240, s[56:57], 0, v240, s[54:55]
	v_cmp_lt_u32_e64 s[48:49], s46, v237
	v_cmp_lt_u32_e64 s[50:51], s46, v238
	v_cmp_lt_u32_e64 s[52:53], s47, v237
	v_cmp_lt_u32_e64 s[54:55], s47, v238
	v_readlane_b32 s46, v237, 48
	v_readlane_b32 s47, v238, 48
; DEV void peer_gather_token(const Params& p, int tok) {
;     ...
;   const int e0 = p.eidx[(size_t)tok * 128 + lane], e1 = p.eidx[(size_t)tok * 128 + 64 + lane];
;   const int g0 = __builtin_bit_cast(int, p.gw[(size_t)tok * 128 + lane]), g1 = __builtin_bit_cast(int, p.gw[(size_t)tok * 128 + 64 + lane]);
;   u32x2 dn[4][3], up[4][3];
;   auto issue = [&](int k, int slot) {
;     const int e = (k < 64) ? __builtin_amdgcn_readlane(e0, k) : __builtin_amdgcn_readlane(e1, k - 64);
	v_addc_co_u32_e64 v239, s[56:57], 0, v239, s[48:49]
	v_addc_co_u32_e64 v240, s[56:57], 0, v240, s[50:51]
	v_addc_co_u32_e64 v239, s[56:57], 0, v239, s[52:53]
	v_addc_co_u32_e64 v240, s[56:57], 0, v240, s[54:55]
	v_cmp_lt_u32_e64 s[48:49], s46, v237
	v_cmp_lt_u32_e64 s[50:51], s46, v238
	v_cmp_lt_u32_e64 s[52:53], s47, v237
	v_cmp_lt_u32_e64 s[54:55], s47, v238
	v_readlane_b32 s46, v237, 49
	v_readlane_b32 s47, v238, 49
	v_addc_co_u32_e64 v239, s[56:57], 0, v239, s[48:49]
	v_addc_co_u32_e64 v240, s[56:57], 0, v240, s[50:51]
	v_addc_co_u32_e64 v239, s[56:57], 0, v239, s[52:53]
	v_addc_co_u32_e64 v240, s[56:57], 0, v240, s[54:55]
	v_cmp_lt_u32_e64 s[48:49], s46, v237
	v_cmp_lt_u32_e64 s[50:51], s46, v238
	v_cmp_lt_u32_e64 s[52:53], s47, v237
	v_cmp_lt_u32_e64 s[54:55], s47, v238
	v_readlane_b32 s46, v237, 50
	v_readlane_b32 s47, v238, 50
	v_addc_co_u32_e64 v239, s[56:57], 0, v239, s[48:49]
	v_addc_co_u32_e64 v240, s[56:57], 0, v240, s[50:51]
	v_addc_co_u32_e64 v239, s[56:57], 0, v239, s[52:53]
	v_addc_co_u32_e64 v240, s[56:57], 0, v240, s[54:55]
	v_cmp_lt_u32_e64 s[48:49], s46, v237
	v_cmp_lt_u32_e64 s[50:51], s46, v238
	v_cmp_lt_u32_e64 s[52:53], s47, v237
	v_cmp_lt_u32_e64 s[54:55], s47, v238
	v_readlane_b32 s46, v237, 51
	v_readlane_b32 s47, v238, 51
	v_addc_co_u32_e64 v239, s[56:57], 0, v239, s[48:49]
	v_addc_co_u32_e64 v240, s[56:57], 0, v240, s[50:51]
	v_addc_co_u32_e64 v239, s[56:57], 0, v239, s[52:53]
	v_addc_co_u32_e64 v240, s[56:57], 0, v240, s[54:55]
	v_cmp_lt_u32_e64 s[48:49], s46, v237
	v_cmp_lt_u32_e64 s[50:51], s46, v238
	v_cmp_lt_u32_e64 s[52:53], s47, v237
	v_cmp_lt_u32_e64 s[54:55], s47, v238
	v_readlane_b32 s46, v237, 52
	v_readlane_b32 s47, v238, 52
	v_addc_co_u32_e64 v239, s[56:57], 0, v239, s[48:49]
	v_addc_co_u32_e64 v240, s[56:57], 0, v240, s[50:51]
	v_addc_co_u32_e64 v239, s[56:57], 0, v239, s[52:53]
	v_addc_co_u32_e64 v240, s[56:57], 0, v240, s[54:55]
	v_cmp_lt_u32_e64 s[48:49], s46, v237
	v_cmp_lt_u32_e64 s[50:51], s46, v238
	v_cmp_lt_u32_e64 s[52:53], s47, v237
	v_cmp_lt_u32_e64 s[54:55], s47, v238
	v_readlane_b32 s46, v237, 53
	v_readlane_b32 s47, v238, 53
	v_addc_co_u32_e64 v239, s[56:57], 0, v239, s[48:49]
	v_addc_co_u32_e64 v240, s[56:57], 0, v240, s[50:51]
	v_addc_co_u32_e64 v239, s[56:57], 0, v239, s[52:53]
	v_addc_co_u32_e64 v240, s[56:57], 0, v240, s[54:55]
	v_cmp_lt_u32_e64 s[48:49], s46, v237
	v_cmp_lt_u32_e64 s[50:51], s46, v238
	v_cmp_lt_u32_e64 s[52:53], s47, v237
	v_cmp_lt_u32_e64 s[54:55], s47, v238
	v_readlane_b32 s46, v237, 54
	v_readlane_b32 s47, v238, 54
	v_addc_co_u32_e64 v239, s[56:57], 0, v239, s[48:49]
	v_addc_co_u32_e64 v240, s[56:57], 0, v240, s[50:51]
	v_addc_co_u32_e64 v239, s[56:57], 0, v239, s[52:53]
	v_addc_co_u32_e64 v240, s[56:57], 0, v240, s[54:55]
	v_cmp_lt_u32_e64 s[48:49], s46, v237
	v_cmp_lt_u32_e64 s[50:51], s46, v238
	v_cmp_lt_u32_e64 s[52:53], s47, v237
	v_cmp_lt_u32_e64 s[54:55], s47, v238
	v_readlane_b32 s46, v237, 55
	v_readlane_b32 s47, v238, 55
	v_addc_co_u32_e64 v239, s[56:57], 0, v239, s[48:49]
	v_addc_co_u32_e64 v240, s[56:57], 0, v240, s[50:51]
	v_addc_co_u32_e64 v239, s[56:57], 0, v239, s[52:53]
	v_addc_co_u32_e64 v240, s[56:57], 0, v240, s[54:55]
	v_cmp_lt_u32_e64 s[48:49], s46, v237
	v_cmp_lt_u32_e64 s[50:51], s46, v238
	v_cmp_lt_u32_e64 s[52:53], s47, v237
	v_cmp_lt_u32_e64 s[54:55], s47, v238
	v_readlane_b32 s46, v237, 56
	v_readlane_b32 s47, v238, 56
	v_addc_co_u32_e64 v239, s[56:57], 0, v239, s[48:49]
	v_addc_co_u32_e64 v240, s[56:57], 0, v240, s[50:51]
	v_addc_co_u32_e64 v239, s[56:57], 0, v239, s[52:53]
	v_addc_co_u32_e64 v240, s[56:57], 0, v240, s[54:55]
	v_cmp_lt_u32_e64 s[48:49], s46, v237
	v_cmp_lt_u32_e64 s[50:51], s46, v238
; DEV void peer_gather_token(const Params& p, int tok) {
;     ...
;   const int e0 = p.eidx[(size_t)tok * 128 + lane], e1 = p.eidx[(size_t)tok * 128 + 64 + lane];
;   const int g0 = __builtin_bit_cast(int, p.gw[(size_t)tok * 128 + lane]), g1 = __builtin_bit_cast(int, p.gw[(size_t)tok * 128 + 64 + lane]);
;   u32x2 dn[4][3], up[4][3];
;   auto issue = [&](int k, int slot) {
;     const int e = (k < 64) ? __builtin_amdgcn_readlane(e0, k) : __builtin_amdgcn_readlane(e1, k - 64);
	v_cmp_lt_u32_e64 s[52:53], s47, v237
	v_cmp_lt_u32_e64 s[54:55], s47, v238
	v_readlane_b32 s46, v237, 57
	v_readlane_b32 s47, v238, 57
	v_addc_co_u32_e64 v239, s[56:57], 0, v239, s[48:49]
	v_addc_co_u32_e64 v240, s[56:57], 0, v240, s[50:51]
	v_addc_co_u32_e64 v239, s[56:57], 0, v239, s[52:53]
	v_addc_co_u32_e64 v240, s[56:57], 0, v240, s[54:55]
	v_cmp_lt_u32_e64 s[48:49], s46, v237
	v_cmp_lt_u32_e64 s[50:51], s46, v238
	v_cmp_lt_u32_e64 s[52:53], s47, v237
	v_cmp_lt_u32_e64 s[54:55], s47, v238
	v_readlane_b32 s46, v237, 58
	v_readlane_b32 s47, v238, 58
	v_addc_co_u32_e64 v239, s[56:57], 0, v239, s[48:49]
	v_addc_co_u32_e64 v240, s[56:57], 0, v240, s[50:51]
	v_addc_co_u32_e64 v239, s[56:57], 0, v239, s[52:53]
	v_addc_co_u32_e64 v240, s[56:57], 0, v240, s[54:55]
	v_cmp_lt_u32_e64 s[48:49], s46, v237
	v_cmp_lt_u32_e64 s[50:51], s46, v238
	v_cmp_lt_u32_e64 s[52:53], s47, v237
	v_cmp_lt_u32_e64 s[54:55], s47, v238
	v_readlane_b32 s46, v237, 59
	v_readlane_b32 s47, v238, 59
	v_addc_co_u32_e64 v239, s[56:57], 0, v239, s[48:49]
	v_addc_co_u32_e64 v240, s[56:57], 0, v240, s[50:51]
	v_addc_co_u32_e64 v239, s[56:57], 0, v239, s[52:53]
	v_addc_co_u32_e64 v240, s[56:57], 0, v240, s[54:55]
	v_cmp_lt_u32_e64 s[48:49], s46, v237
	v_cmp_lt_u32_e64 s[50:51], s46, v238
	v_cmp_lt_u32_e64 s[52:53], s47, v237
	v_cmp_lt_u32_e64 s[54:55], s47, v238
	v_readlane_b32 s46, v237, 60
	v_readlane_b32 s47, v238, 60
	v_addc_co_u32_e64 v239, s[56:57], 0, v239, s[48:49]
	v_addc_co_u32_e64 v240, s[56:57], 0, v240, s[50:51]
	v_addc_co_u32_e64 v239, s[56:57], 0, v239, s[52:53]
	v_addc_co_u32_e64 v240, s[56:57], 0, v240, s[54:55]
	v_cmp_lt_u32_e64 s[48:49], s46, v237
	v_cmp_lt_u32_e64 s[50:51], s46, v238
	v_cmp_lt_u32_e64 s[52:53], s47, v237
	v_cmp_lt_u32_e64 s[54:55], s47, v238
	v_readlane_b32 s46, v237, 61
	v_readlane_b32 s47, v238, 61
	v_addc_co_u32_e64 v239, s[56:57], 0, v239, s[48:49]
	v_addc_co_u32_e64 v240, s[56:57], 0, v240, s[50:51]
	v_addc_co_u32_e64 v239, s[56:57], 0, v239, s[52:53]
	v_addc_co_u32_e64 v240, s[56:57], 0, v240, s[54:55]
	v_cmp_lt_u32_e64 s[48:49], s46, v237
	v_cmp_lt_u32_e64 s[50:51], s46, v238
	v_cmp_lt_u32_e64 s[52:53], s47, v237
	v_cmp_lt_u32_e64 s[54:55], s47, v238
	v_readlane_b32 s46, v237, 62
	v_readlane_b32 s47, v238, 62
	v_addc_co_u32_e64 v239, s[56:57], 0, v239, s[48:49]
	v_addc_co_u32_e64 v240, s[56:57], 0, v240, s[50:51]
	v_addc_co_u32_e64 v239, s[56:57], 0, v239, s[52:53]
	v_addc_co_u32_e64 v240, s[56:57], 0, v240, s[54:55]
	v_cmp_lt_u32_e64 s[48:49], s46, v237
	v_cmp_lt_u32_e64 s[50:51], s46, v238
	v_cmp_lt_u32_e64 s[52:53], s47, v237
	v_cmp_lt_u32_e64 s[54:55], s47, v238
	v_readlane_b32 s46, v237, 63
	v_readlane_b32 s47, v238, 63
	v_addc_co_u32_e64 v239, s[56:57], 0, v239, s[48:49]
	v_addc_co_u32_e64 v240, s[56:57], 0, v240, s[50:51]
	v_addc_co_u32_e64 v239, s[56:57], 0, v239, s[52:53]
	v_addc_co_u32_e64 v240, s[56:57], 0, v240, s[54:55]
	v_cmp_lt_u32_e64 s[48:49], s46, v237
	v_cmp_lt_u32_e64 s[50:51], s46, v238
	v_cmp_lt_u32_e64 s[52:53], s47, v237
	v_cmp_lt_u32_e64 s[54:55], s47, v238
	s_nop 1
	v_addc_co_u32_e64 v239, s[56:57], 0, v239, s[48:49]
	v_addc_co_u32_e64 v240, s[56:57], 0, v240, s[50:51]
	v_addc_co_u32_e64 v239, s[56:57], 0, v239, s[52:53]
	v_addc_co_u32_e64 v240, s[56:57], 0, v240, s[54:55]
	v_and_b32_e32 v237, 0xfffffc00, v241
	v_lshl_add_u32 v239, v239, 2, v237
	v_lshl_add_u32 v240, v240, 2, v237
	ds_write_b32 v239, v216
	ds_write_b32 v240, v217
	ds_write_b32 v239, v218 offset:512
	ds_write_b32 v240, v219 offset:512
	s_waitcnt lgkmcnt(0)
	ds_read_b32 v216, v241
	ds_read_b32 v217, v241 offset:256
	ds_read_b32 v218, v241 offset:512
	ds_read_b32 v219, v241 offset:768
	s_waitcnt lgkmcnt(0)
	s_branch .Lp12_switch

; DEV float bflo(unsigned u) { return __uint_as_float(u << 16); }
; DEV float bfhi(unsigned u) { return __uint_as_float(u & 0xffff0000u); }
; DEV float gelu_exact(float v) { return 0.5f * v * (1.f + erff(v * 0.7071067811865476f)); }
; DEV void peer_gather_token(const Params& p, int tok) {
;     ...
;     const u16* hr = p.h + (size_t)tok * 2048 + lane * 32;
; #pragma unroll
;     for (int q = 0; q < 4; ++q) {
;       u32x4 v = *(const u32x4*)(hr + q * 8);
; #pragma unroll
;       for (int e = 0; e < 4; ++e) { hx[q * 8 + 2 * e] = bflo(v[e]); hx[q * 8 + 2 * e + 1] = bfhi(v[e]); }
;     }
;   }
; #pragma unroll
;   for (int e = 0; e < 32; ++e) acc[e] = 0.f;
;   const int e0 = p.eidx[(size_t)tok * 128 + lane], e1 = p.eidx[(size_t)tok * 128 + 64 + lane];
;   const int g0 = __builtin_bit_cast(int, p.gw[(size_t)tok * 128 + lane]), g1 = __builtin_bit_cast(int, p.gw[(size_t)tok * 128 + 64 + lane]);
;     ...
;       const float d = wave_sum_fast((d0 + d1) + (d2 + d3)) * (1.f / DOWN_SCALE);
;       const float gk = __builtin_bit_cast(float, (k < 64) ? __builtin_amdgcn_readlane(g0, k) : __builtin_amdgcn_readlane(g1, k - 64));
;       const float act = gelu_exact(d) * gk * (1.f / UP_SCALE);
;       const v6u uq = v6u{up[s][0][0], up[s][0][1], up[s][1][0], up[s][1][1], up[s][2][0], up[s][2][1]};
;       const v32f uv = __builtin_amdgcn_cvt_scalef32_pk32_f32_fp6(uq, 1.0f);
; #pragma unroll
;       for (int i = 0; i < 32; ++i) acc[i] += act * uv[i];
.Ljn_15:
	v_bfi_b32 v209, s18, v210, v205
	v_mul_f32_e32 v208, 0.5, v204
	v_add_f32_e32 v209, 1.0, v209
	v_mul_f32_e32 v208, v208, v209
	v_mul_f32_e32 v208, s26, v208
	v_mul_f32_e32 v206, 0x3e800000, v208
	v_pk_fma_f32 v[66:67], v[2:3], v[206:207], v[66:67] op_sel_hi:[1,0,1]
	v_pk_fma_f32 v[68:69], v[4:5], v[206:207], v[68:69] op_sel_hi:[1,0,1]
	v_pk_fma_f32 v[70:71], v[6:7], v[206:207], v[70:71] op_sel_hi:[1,0,1]
	v_pk_fma_f32 v[72:73], v[8:9], v[206:207], v[72:73] op_sel_hi:[1,0,1]
	v_pk_fma_f32 v[74:75], v[10:11], v[206:207], v[74:75] op_sel_hi:[1,0,1]
	v_pk_fma_f32 v[76:77], v[12:13], v[206:207], v[76:77] op_sel_hi:[1,0,1]
	v_pk_fma_f32 v[78:79], v[14:15], v[206:207], v[78:79] op_sel_hi:[1,0,1]
	v_pk_fma_f32 v[80:81], v[16:17], v[206:207], v[80:81] op_sel_hi:[1,0,1]
	v_pk_fma_f32 v[82:83], v[18:19], v[206:207], v[82:83] op_sel_hi:[1,0,1]
	v_pk_fma_f32 v[84:85], v[20:21], v[206:207], v[84:85] op_sel_hi:[1,0,1]
	v_pk_fma_f32 v[86:87], v[22:23], v[206:207], v[86:87] op_sel_hi:[1,0,1]
	v_pk_fma_f32 v[88:89], v[24:25], v[206:207], v[88:89] op_sel_hi:[1,0,1]
	v_pk_fma_f32 v[90:91], v[26:27], v[206:207], v[90:91] op_sel_hi:[1,0,1]
	v_pk_fma_f32 v[92:93], v[28:29], v[206:207], v[92:93] op_sel_hi:[1,0,1]
	v_pk_fma_f32 v[94:95], v[30:31], v[206:207], v[94:95] op_sel_hi:[1,0,1]
	v_pk_fma_f32 v[96:97], v[32:33], v[206:207], v[96:97] op_sel_hi:[1,0,1]
	s_add_i32 s22, s22, 1
	s_add_i32 s23, s23, 8
	s_and_b32 s23, s23, 63
	s_add_i32 s24, s24, 8
	s_and_b32 s24, s24, 63
	s_cmp_lt_u32 s22, 14
	s_cbranch_scc1 .Lp12_main
	s_add_i32 s60, s20, s21
	s_cmpk_lt_u32 s60, 0x4000
	s_cselect_b32 s60, s60, s20
	s_lshl_b32 s38, s60, 9
	s_add_u32 s58, s66, s38
	s_addc_u32 s59, s67, 0
	global_load_dword v216, v242, s[58:59]
	global_load_dword v217, v242, s[58:59] offset:256
	s_add_u32 s58, s68, s38
	s_addc_u32 s59, s69, 0
	global_load_dword v218, v242, s[58:59]
	global_load_dword v219, v242, s[58:59] offset:256
	s_lshl_b32 s38, s60, 6
	s_add_u32 s58, s80, s38
	s_addc_u32 s59, s81, 0
	global_load_dwordx2 v[220:221], v246, s[58:59]
	global_load_dwordx2 v[222:223], v247, s[58:59]
	global_load_dwordx2 v[224:225], v248, s[58:59]
	global_load_dwordx2 v[226:227], v249, s[58:59]
	global_load_dwordx2 v[228:229], v250, s[58:59]
	global_load_dwordx2 v[230:231], v251, s[58:59]
	global_load_dwordx2 v[232:233], v252, s[58:59]
	global_load_dwordx2 v[234:235], v253, s[58:59]
	s_waitcnt vmcnt(33)
	v_cvt_scalef32_pk32_f32_fp6 v[2:33], v[98:103], 1.0
	v_mul_f32_e32 v200, v2, v34
	v_mul_f32_e32 v201, v3, v35
	v_mul_f32_e32 v202, v4, v36
	v_mul_f32_e32 v203, v5, v37
	v_fmac_f32_e32 v200, v6, v38
	v_fmac_f32_e32 v201, v7, v39
	v_fmac_f32_e32 v202, v8, v40
	v_fmac_f32_e32 v203, v9, v41
	v_fmac_f32_e32 v200, v10, v42
	v_fmac_f32_e32 v201, v11, v43
	v_fmac_f32_e32 v202, v12, v44
	v_fmac_f32_e32 v203, v13, v45
	v_fmac_f32_e32 v200, v14, v46
	v_fmac_f32_e32 v201, v15, v47
	v_fmac_f32_e32 v202, v16, v48
	v_fmac_f32_e32 v203, v17, v49
	v_fmac_f32_e32 v200, v18, v50
	v_fmac_f32_e32 v201, v19, v51
	v_fmac_f32_e32 v202, v20, v52
	v_fmac_f32_e32 v203, v21, v53
	v_fmac_f32_e32 v200, v22, v54
	v_fmac_f32_e32 v201, v23, v55
	v_fmac_f32_e32 v202, v24, v56
	v_fmac_f32_e32 v203, v25, v57
	v_fmac_f32_e32 v200, v26, v58
	v_fmac_f32_e32 v201, v27, v59
	v_fmac_f32_e32 v202, v28, v60
	v_fmac_f32_e32 v203, v29, v61
	v_fmac_f32_e32 v200, v30, v62
	v_fmac_f32_e32 v201, v31, v63
	v_fmac_f32_e32 v202, v32, v64
	v_fmac_f32_e32 v203, v33, v65
	v_add_f32_e32 v200, v201, v200
	v_add_f32_e32 v202, v203, v202
	v_cvt_scalef32_pk32_f32_fp6 v[2:33], v[104:109], 1.0
	v_add_f32_e32 v200, v202, v200
	s_add_i32 s38, s24, 0
	v_readlane_b32 s26, v199, s38
	s_add_i32 s39, s23, 0
	v_readlane_b32 s25, v198, s39
	v_add_f32_dpp v200, v200, v200 quad_perm:[1,0,3,2] row_mask:0xf bank_mask:0xf bound_ctrl:1
	s_nop 1
	v_add_f32_dpp v200, v200, v200 quad_perm:[2,3,0,1] row_mask:0xf bank_mask:0xf bound_ctrl:1
	s_nop 1
	v_add_f32_dpp v200, v200, v200 row_half_mirror row_mask:0xf bank_mask:0xf bound_ctrl:1
	s_nop 1
	v_add_f32_dpp v200, v200, v200 row_mirror row_mask:0xf bank_mask:0xf bound_ctrl:1
	s_nop 1
	v_add_f32_dpp v200, v200, v200 row_bcast:15 row_mask:0xa bank_mask:0xf
	s_nop 1
	v_add_f32_dpp v200, v200, v200 row_bcast:31 row_mask:0xc bank_mask:0xf
	s_nop 0
	v_readlane_b32 s27, v200, 63
	s_mul_i32 s40, s25, 0xc00
	s_add_u32 s28, s62, s40
	s_addc_u32 s29, s63, 0
	global_load_dwordx4 v[98:101], v1, s[28:29]
	global_load_dwordx4 v[102:105], v1, s[28:29] offset:2048
	global_load_dwordx4 v[106:109], v1, s[28:29] offset:1024
	v_mul_f32_e32 v204, s27, v212
	v_mul_f32_e32 v205, 0x3f3504f3, v204
	v_cmp_lt_f32_e64 s[32:33], |v205|, 1.0
	s_and_b64 vcc, exec, s[32:33]
	s_cbranch_vccnz .Lsm_17
	v_fma_f32 v208, |v205|, s9, v214
	v_fma_f32 v208, |v205|, v208, s10
	v_fma_f32 v208, |v205|, v208, s11
	v_fma_f32 v208, |v205|, v208, s12
	v_fma_f32 v208, |v205|, v208, s13
	v_fma_f32 v208, |v205|, v208, s14
	v_fma_f32 v208, |v205|, v208, |v205|
	v_mul_f32_e32 v209, 0xbfb8aa3b, v208
	v_fma_f32 v210, v208, s15, -v209
	v_rndne_f32_e32 v211, v209
	v_fmac_f32_e32 v210, 0xb2a5705f, v208
	v_sub_f32_e32 v209, v209, v211
	v_add_f32_e32 v209, v209, v210
	v_cvt_i32_f32_e32 v210, v211
	v_exp_f32_e32 v209, v209
	v_cmp_nlt_f32_e32 vcc, s16, v208
	v_ldexp_f32 v209, v209, v210
	s_nop 0
	v_cndmask_b32_e32 v209, 0, v209, vcc
	v_cmp_ngt_f32_e32 vcc, s17, v208
	s_nop 1
	v_cndmask_b32_e32 v208, v215, v209, vcc
	v_sub_f32_e32 v210, 1.0, v208
	s_branch .Ljn_17

; DEV float gelu_exact(float v) { return 0.5f * v * (1.f + erff(v * 0.7071067811865476f)); }
; DEV void peer_gather_token(const Params& p, int tok) {
;     ...
;       const v6u dq = v6u{dn[s][0][0], dn[s][0][1], dn[s][1][0], dn[s][1][1], dn[s][2][0], dn[s][2][1]};
;       const v32f dv = __builtin_amdgcn_cvt_scalef32_pk32_f32_fp6(dq, 1.0f);
;       float d0 = 0.f, d1 = 0.f, d2 = 0.f, d3 = 0.f;
; #pragma unroll
;       for (int i = 0; i < 8; ++i) { d0 += dv[4 * i] * hx[4 * i]; d1 += dv[4 * i + 1] * hx[4 * i + 1]; d2 += dv[4 * i + 2] * hx[4 * i + 2]; d3 += dv[4 * i + 3] * hx[4 * i + 3]; }
;       const float d = wave_sum_fast((d0 + d1) + (d2 + d3)) * (1.f / DOWN_SCALE);
;       const float gk = __builtin_bit_cast(float, (k < 64) ? __builtin_amdgcn_readlane(g0, k) : __builtin_amdgcn_readlane(g1, k - 64));
;       const float act = gelu_exact(d) * gk * (1.f / UP_SCALE);
;       const v6u uq = v6u{up[s][0][0], up[s][0][1], up[s][1][0], up[s][1][1], up[s][2][0], up[s][2][1]};
;       const v32f uv = __builtin_amdgcn_cvt_scalef32_pk32_f32_fp6(uq, 1.0f);
; #pragma unroll
;       for (int i = 0; i < 32; ++i) acc[i] += act * uv[i];
.Ljn_17:
	v_bfi_b32 v209, s18, v210, v205
	v_mul_f32_e32 v208, 0.5, v204
	v_add_f32_e32 v209, 1.0, v209
	v_mul_f32_e32 v208, v208, v209
	v_mul_f32_e32 v208, s26, v208
	v_mul_f32_e32 v206, 0x3e800000, v208
	v_pk_fma_f32 v[66:67], v[2:3], v[206:207], v[66:67] op_sel_hi:[1,0,1]
	v_pk_fma_f32 v[68:69], v[4:5], v[206:207], v[68:69] op_sel_hi:[1,0,1]
	v_pk_fma_f32 v[70:71], v[6:7], v[206:207], v[70:71] op_sel_hi:[1,0,1]
	v_pk_fma_f32 v[72:73], v[8:9], v[206:207], v[72:73] op_sel_hi:[1,0,1]
	v_pk_fma_f32 v[74:75], v[10:11], v[206:207], v[74:75] op_sel_hi:[1,0,1]
	v_pk_fma_f32 v[76:77], v[12:13], v[206:207], v[76:77] op_sel_hi:[1,0,1]
	v_pk_fma_f32 v[78:79], v[14:15], v[206:207], v[78:79] op_sel_hi:[1,0,1]
	v_pk_fma_f32 v[80:81], v[16:17], v[206:207], v[80:81] op_sel_hi:[1,0,1]
	v_pk_fma_f32 v[82:83], v[18:19], v[206:207], v[82:83] op_sel_hi:[1,0,1]
	v_pk_fma_f32 v[84:85], v[20:21], v[206:207], v[84:85] op_sel_hi:[1,0,1]
	v_pk_fma_f32 v[86:87], v[22:23], v[206:207], v[86:87] op_sel_hi:[1,0,1]
	v_pk_fma_f32 v[88:89], v[24:25], v[206:207], v[88:89] op_sel_hi:[1,0,1]
	v_pk_fma_f32 v[90:91], v[26:27], v[206:207], v[90:91] op_sel_hi:[1,0,1]
	v_pk_fma_f32 v[92:93], v[28:29], v[206:207], v[92:93] op_sel_hi:[1,0,1]
	v_pk_fma_f32 v[94:95], v[30:31], v[206:207], v[94:95] op_sel_hi:[1,0,1]
	v_pk_fma_f32 v[96:97], v[32:33], v[206:207], v[96:97] op_sel_hi:[1,0,1]
	s_waitcnt vmcnt(33)
	v_cvt_scalef32_pk32_f32_fp6 v[2:33], v[110:115], 1.0
	v_mul_f32_e32 v200, v2, v34
	v_mul_f32_e32 v201, v3, v35
	v_mul_f32_e32 v202, v4, v36
	v_mul_f32_e32 v203, v5, v37
	v_fmac_f32_e32 v200, v6, v38
	v_fmac_f32_e32 v201, v7, v39
	v_fmac_f32_e32 v202, v8, v40
	v_fmac_f32_e32 v203, v9, v41
	v_fmac_f32_e32 v200, v10, v42
	v_fmac_f32_e32 v201, v11, v43
	v_fmac_f32_e32 v202, v12, v44
	v_fmac_f32_e32 v203, v13, v45
	v_fmac_f32_e32 v200, v14, v46
	v_fmac_f32_e32 v201, v15, v47
	v_fmac_f32_e32 v202, v16, v48
	v_fmac_f32_e32 v203, v17, v49
	v_fmac_f32_e32 v200, v18, v50
	v_fmac_f32_e32 v201, v19, v51
	v_fmac_f32_e32 v202, v20, v52
	v_fmac_f32_e32 v203, v21, v53
	v_fmac_f32_e32 v200, v22, v54
	v_fmac_f32_e32 v201, v23, v55
	v_fmac_f32_e32 v202, v24, v56
	v_fmac_f32_e32 v203, v25, v57
	v_fmac_f32_e32 v200, v26, v58
	v_fmac_f32_e32 v201, v27, v59
	v_fmac_f32_e32 v202, v28, v60
	v_fmac_f32_e32 v203, v29, v61
	v_fmac_f32_e32 v200, v30, v62
	v_fmac_f32_e32 v201, v31, v63
	v_fmac_f32_e32 v202, v32, v64
	v_fmac_f32_e32 v203, v33, v65
	v_add_f32_e32 v200, v201, v200
	v_add_f32_e32 v202, v203, v202
	v_cvt_scalef32_pk32_f32_fp6 v[2:33], v[116:121], 1.0
	v_add_f32_e32 v200, v202, v200
	s_add_i32 s38, s24, 1
	v_readlane_b32 s26, v199, s38
	s_add_i32 s39, s23, 1
	v_readlane_b32 s25, v198, s39
	v_add_f32_dpp v200, v200, v200 quad_perm:[1,0,3,2] row_mask:0xf bank_mask:0xf bound_ctrl:1
	s_nop 1
	v_add_f32_dpp v200, v200, v200 quad_perm:[2,3,0,1] row_mask:0xf bank_mask:0xf bound_ctrl:1
	s_nop 1
	v_add_f32_dpp v200, v200, v200 row_half_mirror row_mask:0xf bank_mask:0xf bound_ctrl:1
	s_nop 1
	v_add_f32_dpp v200, v200, v200 row_mirror row_mask:0xf bank_mask:0xf bound_ctrl:1
	s_nop 1
	v_add_f32_dpp v200, v200, v200 row_bcast:15 row_mask:0xa bank_mask:0xf
	s_nop 1
	v_add_f32_dpp v200, v200, v200 row_bcast:31 row_mask:0xc bank_mask:0xf
	s_nop 0
	v_readlane_b32 s27, v200, 63
	s_mul_i32 s40, s25, 0xc00
	s_add_u32 s28, s62, s40
	s_addc_u32 s29, s63, 0
	global_load_dwordx4 v[110:113], v1, s[28:29]
	global_load_dwordx4 v[114:117], v1, s[28:29] offset:2048
	global_load_dwordx4 v[118:121], v1, s[28:29] offset:1024
	v_mul_f32_e32 v204, s27, v212
	v_mul_f32_e32 v205, 0x3f3504f3, v204
	v_cmp_lt_f32_e64 s[32:33], |v205|, 1.0
	s_and_b64 vcc, exec, s[32:33]
	s_cbranch_vccnz .Lsm_19
	v_fma_f32 v208, |v205|, s9, v214
	v_fma_f32 v208, |v205|, v208, s10
	v_fma_f32 v208, |v205|, v208, s11
	v_fma_f32 v208, |v205|, v208, s12
	v_fma_f32 v208, |v205|, v208, s13
	v_fma_f32 v208, |v205|, v208, s14
	v_fma_f32 v208, |v205|, v208, |v205|
	v_mul_f32_e32 v209, 0xbfb8aa3b, v208
	v_fma_f32 v210, v208, s15, -v209
	v_rndne_f32_e32 v211, v209
	v_fmac_f32_e32 v210, 0xb2a5705f, v208
	v_sub_f32_e32 v209, v209, v211
	v_add_f32_e32 v209, v209, v210
	v_cvt_i32_f32_e32 v210, v211
	v_exp_f32_e32 v209, v209
	v_cmp_nlt_f32_e32 vcc, s16, v208
	v_ldexp_f32 v209, v209, v210
	s_nop 0
	v_cndmask_b32_e32 v209, 0, v209, vcc
	v_cmp_ngt_f32_e32 vcc, s17, v208
	s_nop 1
	v_cndmask_b32_e32 v208, v215, v209, vcc
	v_sub_f32_e32 v210, 1.0, v208
	s_branch .Ljn_19

; DEV float gelu_exact(float v) { return 0.5f * v * (1.f + erff(v * 0.7071067811865476f)); }
; DEV void peer_gather_token(const Params& p, int tok) {
;     ...
;       const v6u dq = v6u{dn[s][0][0], dn[s][0][1], dn[s][1][0], dn[s][1][1], dn[s][2][0], dn[s][2][1]};
;       const v32f dv = __builtin_amdgcn_cvt_scalef32_pk32_f32_fp6(dq, 1.0f);
;       float d0 = 0.f, d1 = 0.f, d2 = 0.f, d3 = 0.f;
; #pragma unroll
;       for (int i = 0; i < 8; ++i) { d0 += dv[4 * i] * hx[4 * i]; d1 += dv[4 * i + 1] * hx[4 * i + 1]; d2 += dv[4 * i + 2] * hx[4 * i + 2]; d3 += dv[4 * i + 3] * hx[4 * i + 3]; }
;       const float d = wave_sum_fast((d0 + d1) + (d2 + d3)) * (1.f / DOWN_SCALE);
;       const float gk = __builtin_bit_cast(float, (k < 64) ? __builtin_amdgcn_readlane(g0, k) : __builtin_amdgcn_readlane(g1, k - 64));
;       const float act = gelu_exact(d) * gk * (1.f / UP_SCALE);
;       const v6u uq = v6u{up[s][0][0], up[s][0][1], up[s][1][0], up[s][1][1], up[s][2][0], up[s][2][1]};
;       const v32f uv = __builtin_amdgcn_cvt_scalef32_pk32_f32_fp6(uq, 1.0f);
; #pragma unroll
;       for (int i = 0; i < 32; ++i) acc[i] += act * uv[i];
.Ljn_19:
	v_bfi_b32 v209, s18, v210, v205
	v_mul_f32_e32 v208, 0.5, v204
	v_add_f32_e32 v209, 1.0, v209
	v_mul_f32_e32 v208, v208, v209
	v_mul_f32_e32 v208, s26, v208
	v_mul_f32_e32 v206, 0x3e800000, v208
	v_pk_fma_f32 v[66:67], v[2:3], v[206:207], v[66:67] op_sel_hi:[1,0,1]
	v_pk_fma_f32 v[68:69], v[4:5], v[206:207], v[68:69] op_sel_hi:[1,0,1]
	v_pk_fma_f32 v[70:71], v[6:7], v[206:207], v[70:71] op_sel_hi:[1,0,1]
	v_pk_fma_f32 v[72:73], v[8:9], v[206:207], v[72:73] op_sel_hi:[1,0,1]
	v_pk_fma_f32 v[74:75], v[10:11], v[206:207], v[74:75] op_sel_hi:[1,0,1]
	v_pk_fma_f32 v[76:77], v[12:13], v[206:207], v[76:77] op_sel_hi:[1,0,1]
	v_pk_fma_f32 v[78:79], v[14:15], v[206:207], v[78:79] op_sel_hi:[1,0,1]
	v_pk_fma_f32 v[80:81], v[16:17], v[206:207], v[80:81] op_sel_hi:[1,0,1]
	v_pk_fma_f32 v[82:83], v[18:19], v[206:207], v[82:83] op_sel_hi:[1,0,1]
	v_pk_fma_f32 v[84:85], v[20:21], v[206:207], v[84:85] op_sel_hi:[1,0,1]
	v_pk_fma_f32 v[86:87], v[22:23], v[206:207], v[86:87] op_sel_hi:[1,0,1]
	v_pk_fma_f32 v[88:89], v[24:25], v[206:207], v[88:89] op_sel_hi:[1,0,1]
	v_pk_fma_f32 v[90:91], v[26:27], v[206:207], v[90:91] op_sel_hi:[1,0,1]
	v_pk_fma_f32 v[92:93], v[28:29], v[206:207], v[92:93] op_sel_hi:[1,0,1]
	v_pk_fma_f32 v[94:95], v[30:31], v[206:207], v[94:95] op_sel_hi:[1,0,1]
	v_pk_fma_f32 v[96:97], v[32:33], v[206:207], v[96:97] op_sel_hi:[1,0,1]
	s_waitcnt vmcnt(33)
	v_cvt_scalef32_pk32_f32_fp6 v[2:33], v[122:127], 1.0
	v_mul_f32_e32 v200, v2, v34
	v_mul_f32_e32 v201, v3, v35
	v_mul_f32_e32 v202, v4, v36
	v_mul_f32_e32 v203, v5, v37
	v_fmac_f32_e32 v200, v6, v38
	v_fmac_f32_e32 v201, v7, v39
	v_fmac_f32_e32 v202, v8, v40
	v_fmac_f32_e32 v203, v9, v41
	v_fmac_f32_e32 v200, v10, v42
	v_fmac_f32_e32 v201, v11, v43
	v_fmac_f32_e32 v202, v12, v44
	v_fmac_f32_e32 v203, v13, v45
	v_fmac_f32_e32 v200, v14, v46
	v_fmac_f32_e32 v201, v15, v47
	v_fmac_f32_e32 v202, v16, v48
	v_fmac_f32_e32 v203, v17, v49
	v_fmac_f32_e32 v200, v18, v50
	v_fmac_f32_e32 v201, v19, v51
	v_fmac_f32_e32 v202, v20, v52
	v_fmac_f32_e32 v203, v21, v53
	v_fmac_f32_e32 v200, v22, v54
	v_fmac_f32_e32 v201, v23, v55
	v_fmac_f32_e32 v202, v24, v56
	v_fmac_f32_e32 v203, v25, v57
	v_fmac_f32_e32 v200, v26, v58
	v_fmac_f32_e32 v201, v27, v59
	v_fmac_f32_e32 v202, v28, v60
	v_fmac_f32_e32 v203, v29, v61
	v_fmac_f32_e32 v200, v30, v62
	v_fmac_f32_e32 v201, v31, v63
	v_fmac_f32_e32 v202, v32, v64
	v_fmac_f32_e32 v203, v33, v65
	v_add_f32_e32 v200, v201, v200
	v_add_f32_e32 v202, v203, v202
	v_cvt_scalef32_pk32_f32_fp6 v[2:33], v[128:133], 1.0
	v_add_f32_e32 v200, v202, v200
	s_add_i32 s38, s24, 2
	v_readlane_b32 s26, v199, s38
	s_add_i32 s39, s23, 2
	v_readlane_b32 s25, v198, s39
	v_add_f32_dpp v200, v200, v200 quad_perm:[1,0,3,2] row_mask:0xf bank_mask:0xf bound_ctrl:1
	s_nop 1
	v_add_f32_dpp v200, v200, v200 quad_perm:[2,3,0,1] row_mask:0xf bank_mask:0xf bound_ctrl:1
	s_nop 1
	v_add_f32_dpp v200, v200, v200 row_half_mirror row_mask:0xf bank_mask:0xf bound_ctrl:1
	s_nop 1
	v_add_f32_dpp v200, v200, v200 row_mirror row_mask:0xf bank_mask:0xf bound_ctrl:1
	s_nop 1
	v_add_f32_dpp v200, v200, v200 row_bcast:15 row_mask:0xa bank_mask:0xf
	s_nop 1
	v_add_f32_dpp v200, v200, v200 row_bcast:31 row_mask:0xc bank_mask:0xf
	s_nop 0
	v_readlane_b32 s27, v200, 63
	s_mul_i32 s40, s25, 0xc00
	s_add_u32 s28, s62, s40
	s_addc_u32 s29, s63, 0
	global_load_dwordx4 v[122:125], v1, s[28:29]
	global_load_dwordx4 v[126:129], v1, s[28:29] offset:2048
	global_load_dwordx4 v[130:133], v1, s[28:29] offset:1024
	v_mul_f32_e32 v204, s27, v212
	v_mul_f32_e32 v205, 0x3f3504f3, v204
	v_cmp_lt_f32_e64 s[32:33], |v205|, 1.0
	s_and_b64 vcc, exec, s[32:33]
	s_cbranch_vccnz .Lsm_21
	v_fma_f32 v208, |v205|, s9, v214
	v_fma_f32 v208, |v205|, v208, s10
	v_fma_f32 v208, |v205|, v208, s11
	v_fma_f32 v208, |v205|, v208, s12
	v_fma_f32 v208, |v205|, v208, s13
	v_fma_f32 v208, |v205|, v208, s14
	v_fma_f32 v208, |v205|, v208, |v205|
	v_mul_f32_e32 v209, 0xbfb8aa3b, v208
	v_fma_f32 v210, v208, s15, -v209
	v_rndne_f32_e32 v211, v209
	v_fmac_f32_e32 v210, 0xb2a5705f, v208
	v_sub_f32_e32 v209, v209, v211
	v_add_f32_e32 v209, v209, v210
	v_cvt_i32_f32_e32 v210, v211
	v_exp_f32_e32 v209, v209
	v_cmp_nlt_f32_e32 vcc, s16, v208
	v_ldexp_f32 v209, v209, v210
	s_nop 0
	v_cndmask_b32_e32 v209, 0, v209, vcc
	v_cmp_ngt_f32_e32 vcc, s17, v208
	s_nop 1
	v_cndmask_b32_e32 v208, v215, v209, vcc
	v_sub_f32_e32 v210, 1.0, v208
	s_branch .Ljn_21

; DEV float gelu_exact(float v) { return 0.5f * v * (1.f + erff(v * 0.7071067811865476f)); }
; DEV void peer_gather_token(const Params& p, int tok) {
;     ...
;       const v6u dq = v6u{dn[s][0][0], dn[s][0][1], dn[s][1][0], dn[s][1][1], dn[s][2][0], dn[s][2][1]};
;       const v32f dv = __builtin_amdgcn_cvt_scalef32_pk32_f32_fp6(dq, 1.0f);
;       float d0 = 0.f, d1 = 0.f, d2 = 0.f, d3 = 0.f;
; #pragma unroll
;       for (int i = 0; i < 8; ++i) { d0 += dv[4 * i] * hx[4 * i]; d1 += dv[4 * i + 1] * hx[4 * i + 1]; d2 += dv[4 * i + 2] * hx[4 * i + 2]; d3 += dv[4 * i + 3] * hx[4 * i + 3]; }
;       const float d = wave_sum_fast((d0 + d1) + (d2 + d3)) * (1.f / DOWN_SCALE);
;       const float gk = __builtin_bit_cast(float, (k < 64) ? __builtin_amdgcn_readlane(g0, k) : __builtin_amdgcn_readlane(g1, k - 64));
;       const float act = gelu_exact(d) * gk * (1.f / UP_SCALE);
;       const v6u uq = v6u{up[s][0][0], up[s][0][1], up[s][1][0], up[s][1][1], up[s][2][0], up[s][2][1]};
;       const v32f uv = __builtin_amdgcn_cvt_scalef32_pk32_f32_fp6(uq, 1.0f);
; #pragma unroll
;       for (int i = 0; i < 32; ++i) acc[i] += act * uv[i];
.Ljn_21:
	v_bfi_b32 v209, s18, v210, v205
	v_mul_f32_e32 v208, 0.5, v204
	v_add_f32_e32 v209, 1.0, v209
	v_mul_f32_e32 v208, v208, v209
	v_mul_f32_e32 v208, s26, v208
	v_mul_f32_e32 v206, 0x3e800000, v208
	v_pk_fma_f32 v[66:67], v[2:3], v[206:207], v[66:67] op_sel_hi:[1,0,1]
	v_pk_fma_f32 v[68:69], v[4:5], v[206:207], v[68:69] op_sel_hi:[1,0,1]
	v_pk_fma_f32 v[70:71], v[6:7], v[206:207], v[70:71] op_sel_hi:[1,0,1]
	v_pk_fma_f32 v[72:73], v[8:9], v[206:207], v[72:73] op_sel_hi:[1,0,1]
	v_pk_fma_f32 v[74:75], v[10:11], v[206:207], v[74:75] op_sel_hi:[1,0,1]
	v_pk_fma_f32 v[76:77], v[12:13], v[206:207], v[76:77] op_sel_hi:[1,0,1]
	v_pk_fma_f32 v[78:79], v[14:15], v[206:207], v[78:79] op_sel_hi:[1,0,1]
	v_pk_fma_f32 v[80:81], v[16:17], v[206:207], v[80:81] op_sel_hi:[1,0,1]
	v_pk_fma_f32 v[82:83], v[18:19], v[206:207], v[82:83] op_sel_hi:[1,0,1]
	v_pk_fma_f32 v[84:85], v[20:21], v[206:207], v[84:85] op_sel_hi:[1,0,1]
	v_pk_fma_f32 v[86:87], v[22:23], v[206:207], v[86:87] op_sel_hi:[1,0,1]
	v_pk_fma_f32 v[88:89], v[24:25], v[206:207], v[88:89] op_sel_hi:[1,0,1]
	v_pk_fma_f32 v[90:91], v[26:27], v[206:207], v[90:91] op_sel_hi:[1,0,1]
	v_pk_fma_f32 v[92:93], v[28:29], v[206:207], v[92:93] op_sel_hi:[1,0,1]
	v_pk_fma_f32 v[94:95], v[30:31], v[206:207], v[94:95] op_sel_hi:[1,0,1]
	v_pk_fma_f32 v[96:97], v[32:33], v[206:207], v[96:97] op_sel_hi:[1,0,1]
	s_waitcnt vmcnt(33)
	v_cvt_scalef32_pk32_f32_fp6 v[2:33], v[134:139], 1.0
	v_mul_f32_e32 v200, v2, v34
	v_mul_f32_e32 v201, v3, v35
	v_mul_f32_e32 v202, v4, v36
	v_mul_f32_e32 v203, v5, v37
	v_fmac_f32_e32 v200, v6, v38
	v_fmac_f32_e32 v201, v7, v39
	v_fmac_f32_e32 v202, v8, v40
	v_fmac_f32_e32 v203, v9, v41
	v_fmac_f32_e32 v200, v10, v42
	v_fmac_f32_e32 v201, v11, v43
	v_fmac_f32_e32 v202, v12, v44
	v_fmac_f32_e32 v203, v13, v45
	v_fmac_f32_e32 v200, v14, v46
	v_fmac_f32_e32 v201, v15, v47
	v_fmac_f32_e32 v202, v16, v48
	v_fmac_f32_e32 v203, v17, v49
	v_fmac_f32_e32 v200, v18, v50
	v_fmac_f32_e32 v201, v19, v51
	v_fmac_f32_e32 v202, v20, v52
	v_fmac_f32_e32 v203, v21, v53
	v_fmac_f32_e32 v200, v22, v54
	v_fmac_f32_e32 v201, v23, v55
	v_fmac_f32_e32 v202, v24, v56
	v_fmac_f32_e32 v203, v25, v57
	v_fmac_f32_e32 v200, v26, v58
	v_fmac_f32_e32 v201, v27, v59
	v_fmac_f32_e32 v202, v28, v60
	v_fmac_f32_e32 v203, v29, v61
	v_fmac_f32_e32 v200, v30, v62
	v_fmac_f32_e32 v201, v31, v63
	v_fmac_f32_e32 v202, v32, v64
	v_fmac_f32_e32 v203, v33, v65
	v_add_f32_e32 v200, v201, v200
	v_add_f32_e32 v202, v203, v202
	v_cvt_scalef32_pk32_f32_fp6 v[2:33], v[140:145], 1.0
	v_add_f32_e32 v200, v202, v200
	s_add_i32 s38, s24, 3
	v_readlane_b32 s26, v199, s38
	s_add_i32 s39, s23, 3
	v_readlane_b32 s25, v198, s39
	v_add_f32_dpp v200, v200, v200 quad_perm:[1,0,3,2] row_mask:0xf bank_mask:0xf bound_ctrl:1
	s_nop 1
	v_add_f32_dpp v200, v200, v200 quad_perm:[2,3,0,1] row_mask:0xf bank_mask:0xf bound_ctrl:1
	s_nop 1
	v_add_f32_dpp v200, v200, v200 row_half_mirror row_mask:0xf bank_mask:0xf bound_ctrl:1
	s_nop 1
	v_add_f32_dpp v200, v200, v200 row_mirror row_mask:0xf bank_mask:0xf bound_ctrl:1
	s_nop 1
	v_add_f32_dpp v200, v200, v200 row_bcast:15 row_mask:0xa bank_mask:0xf
	s_nop 1
	v_add_f32_dpp v200, v200, v200 row_bcast:31 row_mask:0xc bank_mask:0xf
	s_nop 0
	v_readlane_b32 s27, v200, 63
	s_mul_i32 s40, s25, 0xc00
	s_add_u32 s28, s62, s40
	s_addc_u32 s29, s63, 0
	global_load_dwordx4 v[134:137], v1, s[28:29]
	global_load_dwordx4 v[138:141], v1, s[28:29] offset:2048
	global_load_dwordx4 v[142:145], v1, s[28:29] offset:1024
	v_mul_f32_e32 v204, s27, v212
	v_mul_f32_e32 v205, 0x3f3504f3, v204
	v_cmp_lt_f32_e64 s[32:33], |v205|, 1.0
	s_and_b64 vcc, exec, s[32:33]
	s_cbranch_vccnz .Lsm_23
	v_fma_f32 v208, |v205|, s9, v214
	v_fma_f32 v208, |v205|, v208, s10
	v_fma_f32 v208, |v205|, v208, s11
	v_fma_f32 v208, |v205|, v208, s12
	v_fma_f32 v208, |v205|, v208, s13
	v_fma_f32 v208, |v205|, v208, s14
	v_fma_f32 v208, |v205|, v208, |v205|
	v_mul_f32_e32 v209, 0xbfb8aa3b, v208
	v_fma_f32 v210, v208, s15, -v209
	v_rndne_f32_e32 v211, v209
	v_fmac_f32_e32 v210, 0xb2a5705f, v208
	v_sub_f32_e32 v209, v209, v211
	v_add_f32_e32 v209, v209, v210
	v_cvt_i32_f32_e32 v210, v211
	v_exp_f32_e32 v209, v209
	v_cmp_nlt_f32_e32 vcc, s16, v208
	v_ldexp_f32 v209, v209, v210
	s_nop 0
	v_cndmask_b32_e32 v209, 0, v209, vcc
	v_cmp_ngt_f32_e32 vcc, s17, v208
	s_nop 1
	v_cndmask_b32_e32 v208, v215, v209, vcc
	v_sub_f32_e32 v210, 1.0, v208
	s_branch .Ljn_23

; DEV float gelu_exact(float v) { return 0.5f * v * (1.f + erff(v * 0.7071067811865476f)); }
; DEV void peer_gather_token(const Params& p, int tok) {
;     ...
;       const v6u dq = v6u{dn[s][0][0], dn[s][0][1], dn[s][1][0], dn[s][1][1], dn[s][2][0], dn[s][2][1]};
;       const v32f dv = __builtin_amdgcn_cvt_scalef32_pk32_f32_fp6(dq, 1.0f);
;       float d0 = 0.f, d1 = 0.f, d2 = 0.f, d3 = 0.f;
; #pragma unroll
;       for (int i = 0; i < 8; ++i) { d0 += dv[4 * i] * hx[4 * i]; d1 += dv[4 * i + 1] * hx[4 * i + 1]; d2 += dv[4 * i + 2] * hx[4 * i + 2]; d3 += dv[4 * i + 3] * hx[4 * i + 3]; }
;       const float d = wave_sum_fast((d0 + d1) + (d2 + d3)) * (1.f / DOWN_SCALE);
;       const float gk = __builtin_bit_cast(float, (k < 64) ? __builtin_amdgcn_readlane(g0, k) : __builtin_amdgcn_readlane(g1, k - 64));
;       const float act = gelu_exact(d) * gk * (1.f / UP_SCALE);
;       const v6u uq = v6u{up[s][0][0], up[s][0][1], up[s][1][0], up[s][1][1], up[s][2][0], up[s][2][1]};
;       const v32f uv = __builtin_amdgcn_cvt_scalef32_pk32_f32_fp6(uq, 1.0f);
; #pragma unroll
;       for (int i = 0; i < 32; ++i) acc[i] += act * uv[i];
.Ljn_23:
	v_bfi_b32 v209, s18, v210, v205
	v_mul_f32_e32 v208, 0.5, v204
	v_add_f32_e32 v209, 1.0, v209
	v_mul_f32_e32 v208, v208, v209
	v_mul_f32_e32 v208, s26, v208
	v_mul_f32_e32 v206, 0x3e800000, v208
	v_pk_fma_f32 v[66:67], v[2:3], v[206:207], v[66:67] op_sel_hi:[1,0,1]
	v_pk_fma_f32 v[68:69], v[4:5], v[206:207], v[68:69] op_sel_hi:[1,0,1]
	v_pk_fma_f32 v[70:71], v[6:7], v[206:207], v[70:71] op_sel_hi:[1,0,1]
	v_pk_fma_f32 v[72:73], v[8:9], v[206:207], v[72:73] op_sel_hi:[1,0,1]
	v_pk_fma_f32 v[74:75], v[10:11], v[206:207], v[74:75] op_sel_hi:[1,0,1]
	v_pk_fma_f32 v[76:77], v[12:13], v[206:207], v[76:77] op_sel_hi:[1,0,1]
	v_pk_fma_f32 v[78:79], v[14:15], v[206:207], v[78:79] op_sel_hi:[1,0,1]
	v_pk_fma_f32 v[80:81], v[16:17], v[206:207], v[80:81] op_sel_hi:[1,0,1]
	v_pk_fma_f32 v[82:83], v[18:19], v[206:207], v[82:83] op_sel_hi:[1,0,1]
	v_pk_fma_f32 v[84:85], v[20:21], v[206:207], v[84:85] op_sel_hi:[1,0,1]
	v_pk_fma_f32 v[86:87], v[22:23], v[206:207], v[86:87] op_sel_hi:[1,0,1]
	v_pk_fma_f32 v[88:89], v[24:25], v[206:207], v[88:89] op_sel_hi:[1,0,1]
	v_pk_fma_f32 v[90:91], v[26:27], v[206:207], v[90:91] op_sel_hi:[1,0,1]
	v_pk_fma_f32 v[92:93], v[28:29], v[206:207], v[92:93] op_sel_hi:[1,0,1]
	v_pk_fma_f32 v[94:95], v[30:31], v[206:207], v[94:95] op_sel_hi:[1,0,1]
	v_pk_fma_f32 v[96:97], v[32:33], v[206:207], v[96:97] op_sel_hi:[1,0,1]
	s_waitcnt vmcnt(33)
	v_cvt_scalef32_pk32_f32_fp6 v[2:33], v[146:151], 1.0
	v_mul_f32_e32 v200, v2, v34
	v_mul_f32_e32 v201, v3, v35
	v_mul_f32_e32 v202, v4, v36
	v_mul_f32_e32 v203, v5, v37
	v_fmac_f32_e32 v200, v6, v38
	v_fmac_f32_e32 v201, v7, v39
	v_fmac_f32_e32 v202, v8, v40
	v_fmac_f32_e32 v203, v9, v41
	v_fmac_f32_e32 v200, v10, v42
	v_fmac_f32_e32 v201, v11, v43
	v_fmac_f32_e32 v202, v12, v44
	v_fmac_f32_e32 v203, v13, v45
	v_fmac_f32_e32 v200, v14, v46
	v_fmac_f32_e32 v201, v15, v47
	v_fmac_f32_e32 v202, v16, v48
	v_fmac_f32_e32 v203, v17, v49
	v_fmac_f32_e32 v200, v18, v50
	v_fmac_f32_e32 v201, v19, v51
	v_fmac_f32_e32 v202, v20, v52
	v_fmac_f32_e32 v203, v21, v53
	v_fmac_f32_e32 v200, v22, v54
	v_fmac_f32_e32 v201, v23, v55
	v_fmac_f32_e32 v202, v24, v56
	v_fmac_f32_e32 v203, v25, v57
	v_fmac_f32_e32 v200, v26, v58
	v_fmac_f32_e32 v201, v27, v59
	v_fmac_f32_e32 v202, v28, v60
	v_fmac_f32_e32 v203, v29, v61
	v_fmac_f32_e32 v200, v30, v62
	v_fmac_f32_e32 v201, v31, v63
	v_fmac_f32_e32 v202, v32, v64
	v_fmac_f32_e32 v203, v33, v65
	v_add_f32_e32 v200, v201, v200
	v_add_f32_e32 v202, v203, v202
	v_cvt_scalef32_pk32_f32_fp6 v[2:33], v[152:157], 1.0
	v_add_f32_e32 v200, v202, v200
	s_add_i32 s38, s24, 4
	v_readlane_b32 s26, v199, s38
	s_add_i32 s39, s23, 4
	v_readlane_b32 s25, v198, s39
	v_add_f32_dpp v200, v200, v200 quad_perm:[1,0,3,2] row_mask:0xf bank_mask:0xf bound_ctrl:1
	s_nop 1
	v_add_f32_dpp v200, v200, v200 quad_perm:[2,3,0,1] row_mask:0xf bank_mask:0xf bound_ctrl:1
	s_nop 1
	v_add_f32_dpp v200, v200, v200 row_half_mirror row_mask:0xf bank_mask:0xf bound_ctrl:1
	s_nop 1
	v_add_f32_dpp v200, v200, v200 row_mirror row_mask:0xf bank_mask:0xf bound_ctrl:1
	s_nop 1
	v_add_f32_dpp v200, v200, v200 row_bcast:15 row_mask:0xa bank_mask:0xf
	s_nop 1
	v_add_f32_dpp v200, v200, v200 row_bcast:31 row_mask:0xc bank_mask:0xf
	s_nop 0
	v_readlane_b32 s27, v200, 63
	s_mul_i32 s40, s25, 0xc00
	s_add_u32 s28, s62, s40
	s_addc_u32 s29, s63, 0
	global_load_dwordx4 v[146:149], v1, s[28:29]
	global_load_dwordx4 v[150:153], v1, s[28:29] offset:2048
	global_load_dwordx4 v[154:157], v1, s[28:29] offset:1024
	v_mul_f32_e32 v204, s27, v212
	v_mul_f32_e32 v205, 0x3f3504f3, v204
	v_cmp_lt_f32_e64 s[32:33], |v205|, 1.0
	s_and_b64 vcc, exec, s[32:33]
	s_cbranch_vccnz .Lsm_25
	v_fma_f32 v208, |v205|, s9, v214
	v_fma_f32 v208, |v205|, v208, s10
	v_fma_f32 v208, |v205|, v208, s11
	v_fma_f32 v208, |v205|, v208, s12
	v_fma_f32 v208, |v205|, v208, s13
	v_fma_f32 v208, |v205|, v208, s14
	v_fma_f32 v208, |v205|, v208, |v205|
	v_mul_f32_e32 v209, 0xbfb8aa3b, v208
	v_fma_f32 v210, v208, s15, -v209
	v_rndne_f32_e32 v211, v209
	v_fmac_f32_e32 v210, 0xb2a5705f, v208
	v_sub_f32_e32 v209, v209, v211
	v_add_f32_e32 v209, v209, v210
	v_cvt_i32_f32_e32 v210, v211
	v_exp_f32_e32 v209, v209
	v_cmp_nlt_f32_e32 vcc, s16, v208
	v_ldexp_f32 v209, v209, v210
	s_nop 0
	v_cndmask_b32_e32 v209, 0, v209, vcc
	v_cmp_ngt_f32_e32 vcc, s17, v208
	s_nop 1
	v_cndmask_b32_e32 v208, v215, v209, vcc
	v_sub_f32_e32 v210, 1.0, v208
	s_branch .Ljn_25

; DEV float gelu_exact(float v) { return 0.5f * v * (1.f + erff(v * 0.7071067811865476f)); }
; DEV void peer_gather_token(const Params& p, int tok) {
;     ...
;       const v6u dq = v6u{dn[s][0][0], dn[s][0][1], dn[s][1][0], dn[s][1][1], dn[s][2][0], dn[s][2][1]};
;       const v32f dv = __builtin_amdgcn_cvt_scalef32_pk32_f32_fp6(dq, 1.0f);
;       float d0 = 0.f, d1 = 0.f, d2 = 0.f, d3 = 0.f;
; #pragma unroll
;       for (int i = 0; i < 8; ++i) { d0 += dv[4 * i] * hx[4 * i]; d1 += dv[4 * i + 1] * hx[4 * i + 1]; d2 += dv[4 * i + 2] * hx[4 * i + 2]; d3 += dv[4 * i + 3] * hx[4 * i + 3]; }
;       const float d = wave_sum_fast((d0 + d1) + (d2 + d3)) * (1.f / DOWN_SCALE);
;       const float gk = __builtin_bit_cast(float, (k < 64) ? __builtin_amdgcn_readlane(g0, k) : __builtin_amdgcn_readlane(g1, k - 64));
;       const float act = gelu_exact(d) * gk * (1.f / UP_SCALE);
;       const v6u uq = v6u{up[s][0][0], up[s][0][1], up[s][1][0], up[s][1][1], up[s][2][0], up[s][2][1]};
;       const v32f uv = __builtin_amdgcn_cvt_scalef32_pk32_f32_fp6(uq, 1.0f);
; #pragma unroll
;       for (int i = 0; i < 32; ++i) acc[i] += act * uv[i];
.Ljn_25:
	v_bfi_b32 v209, s18, v210, v205
	v_mul_f32_e32 v208, 0.5, v204
	v_add_f32_e32 v209, 1.0, v209
	v_mul_f32_e32 v208, v208, v209
	v_mul_f32_e32 v208, s26, v208
	v_mul_f32_e32 v206, 0x3e800000, v208
	v_pk_fma_f32 v[66:67], v[2:3], v[206:207], v[66:67] op_sel_hi:[1,0,1]
	v_pk_fma_f32 v[68:69], v[4:5], v[206:207], v[68:69] op_sel_hi:[1,0,1]
	v_pk_fma_f32 v[70:71], v[6:7], v[206:207], v[70:71] op_sel_hi:[1,0,1]
	v_pk_fma_f32 v[72:73], v[8:9], v[206:207], v[72:73] op_sel_hi:[1,0,1]
	v_pk_fma_f32 v[74:75], v[10:11], v[206:207], v[74:75] op_sel_hi:[1,0,1]
	v_pk_fma_f32 v[76:77], v[12:13], v[206:207], v[76:77] op_sel_hi:[1,0,1]
	v_pk_fma_f32 v[78:79], v[14:15], v[206:207], v[78:79] op_sel_hi:[1,0,1]
	v_pk_fma_f32 v[80:81], v[16:17], v[206:207], v[80:81] op_sel_hi:[1,0,1]
	v_pk_fma_f32 v[82:83], v[18:19], v[206:207], v[82:83] op_sel_hi:[1,0,1]
	v_pk_fma_f32 v[84:85], v[20:21], v[206:207], v[84:85] op_sel_hi:[1,0,1]
	v_pk_fma_f32 v[86:87], v[22:23], v[206:207], v[86:87] op_sel_hi:[1,0,1]
	v_pk_fma_f32 v[88:89], v[24:25], v[206:207], v[88:89] op_sel_hi:[1,0,1]
	v_pk_fma_f32 v[90:91], v[26:27], v[206:207], v[90:91] op_sel_hi:[1,0,1]
	v_pk_fma_f32 v[92:93], v[28:29], v[206:207], v[92:93] op_sel_hi:[1,0,1]
	v_pk_fma_f32 v[94:95], v[30:31], v[206:207], v[94:95] op_sel_hi:[1,0,1]
	v_pk_fma_f32 v[96:97], v[32:33], v[206:207], v[96:97] op_sel_hi:[1,0,1]
	s_waitcnt vmcnt(33)
	v_cvt_scalef32_pk32_f32_fp6 v[2:33], v[158:163], 1.0
	v_mul_f32_e32 v200, v2, v34
	v_mul_f32_e32 v201, v3, v35
	v_mul_f32_e32 v202, v4, v36
	v_mul_f32_e32 v203, v5, v37
	v_fmac_f32_e32 v200, v6, v38
	v_fmac_f32_e32 v201, v7, v39
	v_fmac_f32_e32 v202, v8, v40
	v_fmac_f32_e32 v203, v9, v41
	v_fmac_f32_e32 v200, v10, v42
	v_fmac_f32_e32 v201, v11, v43
	v_fmac_f32_e32 v202, v12, v44
	v_fmac_f32_e32 v203, v13, v45
	v_fmac_f32_e32 v200, v14, v46
	v_fmac_f32_e32 v201, v15, v47
	v_fmac_f32_e32 v202, v16, v48
	v_fmac_f32_e32 v203, v17, v49
	v_fmac_f32_e32 v200, v18, v50
	v_fmac_f32_e32 v201, v19, v51
	v_fmac_f32_e32 v202, v20, v52
	v_fmac_f32_e32 v203, v21, v53
	v_fmac_f32_e32 v200, v22, v54
	v_fmac_f32_e32 v201, v23, v55
	v_fmac_f32_e32 v202, v24, v56
	v_fmac_f32_e32 v203, v25, v57
	v_fmac_f32_e32 v200, v26, v58
	v_fmac_f32_e32 v201, v27, v59
	v_fmac_f32_e32 v202, v28, v60
	v_fmac_f32_e32 v203, v29, v61
	v_fmac_f32_e32 v200, v30, v62
	v_fmac_f32_e32 v201, v31, v63
	v_fmac_f32_e32 v202, v32, v64
	v_fmac_f32_e32 v203, v33, v65
	v_add_f32_e32 v200, v201, v200
	v_add_f32_e32 v202, v203, v202
	v_cvt_scalef32_pk32_f32_fp6 v[2:33], v[164:169], 1.0
	v_add_f32_e32 v200, v202, v200
	s_add_i32 s38, s24, 5
	v_readlane_b32 s26, v199, s38
	s_add_i32 s39, s23, 5
	v_readlane_b32 s25, v198, s39
	v_add_f32_dpp v200, v200, v200 quad_perm:[1,0,3,2] row_mask:0xf bank_mask:0xf bound_ctrl:1
	s_nop 1
	v_add_f32_dpp v200, v200, v200 quad_perm:[2,3,0,1] row_mask:0xf bank_mask:0xf bound_ctrl:1
	s_nop 1
	v_add_f32_dpp v200, v200, v200 row_half_mirror row_mask:0xf bank_mask:0xf bound_ctrl:1
	s_nop 1
	v_add_f32_dpp v200, v200, v200 row_mirror row_mask:0xf bank_mask:0xf bound_ctrl:1
	s_nop 1
	v_add_f32_dpp v200, v200, v200 row_bcast:15 row_mask:0xa bank_mask:0xf
	s_nop 1
	v_add_f32_dpp v200, v200, v200 row_bcast:31 row_mask:0xc bank_mask:0xf
	s_nop 0
	v_readlane_b32 s27, v200, 63
	s_mul_i32 s40, s25, 0xc00
	s_add_u32 s28, s62, s40
	s_addc_u32 s29, s63, 0
	global_load_dwordx4 v[158:161], v1, s[28:29]
	global_load_dwordx4 v[162:165], v1, s[28:29] offset:2048
	global_load_dwordx4 v[166:169], v1, s[28:29] offset:1024
	v_mul_f32_e32 v204, s27, v212
	v_mul_f32_e32 v205, 0x3f3504f3, v204
	v_cmp_lt_f32_e64 s[32:33], |v205|, 1.0
	s_and_b64 vcc, exec, s[32:33]
	s_cbranch_vccnz .Lsm_27
	v_fma_f32 v208, |v205|, s9, v214
	v_fma_f32 v208, |v205|, v208, s10
	v_fma_f32 v208, |v205|, v208, s11
	v_fma_f32 v208, |v205|, v208, s12
	v_fma_f32 v208, |v205|, v208, s13
	v_fma_f32 v208, |v205|, v208, s14
	v_fma_f32 v208, |v205|, v208, |v205|
	v_mul_f32_e32 v209, 0xbfb8aa3b, v208
	v_fma_f32 v210, v208, s15, -v209
	v_rndne_f32_e32 v211, v209
	v_fmac_f32_e32 v210, 0xb2a5705f, v208
	v_sub_f32_e32 v209, v209, v211
	v_add_f32_e32 v209, v209, v210
	v_cvt_i32_f32_e32 v210, v211
	v_exp_f32_e32 v209, v209
	v_cmp_nlt_f32_e32 vcc, s16, v208
	v_ldexp_f32 v209, v209, v210
	s_nop 0
	v_cndmask_b32_e32 v209, 0, v209, vcc
	v_cmp_ngt_f32_e32 vcc, s17, v208
	s_nop 1
	v_cndmask_b32_e32 v208, v215, v209, vcc
	v_sub_f32_e32 v210, 1.0, v208
	s_branch .Ljn_27

; DEV float gelu_exact(float v) { return 0.5f * v * (1.f + erff(v * 0.7071067811865476f)); }
; DEV void peer_gather_token(const Params& p, int tok) {
;     ...
;       const v6u dq = v6u{dn[s][0][0], dn[s][0][1], dn[s][1][0], dn[s][1][1], dn[s][2][0], dn[s][2][1]};
;       const v32f dv = __builtin_amdgcn_cvt_scalef32_pk32_f32_fp6(dq, 1.0f);
;       float d0 = 0.f, d1 = 0.f, d2 = 0.f, d3 = 0.f;
; #pragma unroll
;       for (int i = 0; i < 8; ++i) { d0 += dv[4 * i] * hx[4 * i]; d1 += dv[4 * i + 1] * hx[4 * i + 1]; d2 += dv[4 * i + 2] * hx[4 * i + 2]; d3 += dv[4 * i + 3] * hx[4 * i + 3]; }
;       const float d = wave_sum_fast((d0 + d1) + (d2 + d3)) * (1.f / DOWN_SCALE);
;       const float gk = __builtin_bit_cast(float, (k < 64) ? __builtin_amdgcn_readlane(g0, k) : __builtin_amdgcn_readlane(g1, k - 64));
;       const float act = gelu_exact(d) * gk * (1.f / UP_SCALE);
;       const v6u uq = v6u{up[s][0][0], up[s][0][1], up[s][1][0], up[s][1][1], up[s][2][0], up[s][2][1]};
;       const v32f uv = __builtin_amdgcn_cvt_scalef32_pk32_f32_fp6(uq, 1.0f);
; #pragma unroll
;       for (int i = 0; i < 32; ++i) acc[i] += act * uv[i];
.Ljn_27:
	v_bfi_b32 v209, s18, v210, v205
	v_mul_f32_e32 v208, 0.5, v204
	v_add_f32_e32 v209, 1.0, v209
	v_mul_f32_e32 v208, v208, v209
	v_mul_f32_e32 v208, s26, v208
	v_mul_f32_e32 v206, 0x3e800000, v208
	v_pk_fma_f32 v[66:67], v[2:3], v[206:207], v[66:67] op_sel_hi:[1,0,1]
	v_pk_fma_f32 v[68:69], v[4:5], v[206:207], v[68:69] op_sel_hi:[1,0,1]
	v_pk_fma_f32 v[70:71], v[6:7], v[206:207], v[70:71] op_sel_hi:[1,0,1]
	v_pk_fma_f32 v[72:73], v[8:9], v[206:207], v[72:73] op_sel_hi:[1,0,1]
	v_pk_fma_f32 v[74:75], v[10:11], v[206:207], v[74:75] op_sel_hi:[1,0,1]
	v_pk_fma_f32 v[76:77], v[12:13], v[206:207], v[76:77] op_sel_hi:[1,0,1]
	v_pk_fma_f32 v[78:79], v[14:15], v[206:207], v[78:79] op_sel_hi:[1,0,1]
	v_pk_fma_f32 v[80:81], v[16:17], v[206:207], v[80:81] op_sel_hi:[1,0,1]
	v_pk_fma_f32 v[82:83], v[18:19], v[206:207], v[82:83] op_sel_hi:[1,0,1]
	v_pk_fma_f32 v[84:85], v[20:21], v[206:207], v[84:85] op_sel_hi:[1,0,1]
	v_pk_fma_f32 v[86:87], v[22:23], v[206:207], v[86:87] op_sel_hi:[1,0,1]
	v_pk_fma_f32 v[88:89], v[24:25], v[206:207], v[88:89] op_sel_hi:[1,0,1]
	v_pk_fma_f32 v[90:91], v[26:27], v[206:207], v[90:91] op_sel_hi:[1,0,1]
	v_pk_fma_f32 v[92:93], v[28:29], v[206:207], v[92:93] op_sel_hi:[1,0,1]
	v_pk_fma_f32 v[94:95], v[30:31], v[206:207], v[94:95] op_sel_hi:[1,0,1]
	v_pk_fma_f32 v[96:97], v[32:33], v[206:207], v[96:97] op_sel_hi:[1,0,1]
	s_waitcnt vmcnt(33)
	v_cvt_scalef32_pk32_f32_fp6 v[2:33], v[170:175], 1.0
	v_mul_f32_e32 v200, v2, v34
	v_mul_f32_e32 v201, v3, v35
	v_mul_f32_e32 v202, v4, v36
	v_mul_f32_e32 v203, v5, v37
	v_fmac_f32_e32 v200, v6, v38
	v_fmac_f32_e32 v201, v7, v39
	v_fmac_f32_e32 v202, v8, v40
	v_fmac_f32_e32 v203, v9, v41
	v_fmac_f32_e32 v200, v10, v42
	v_fmac_f32_e32 v201, v11, v43
	v_fmac_f32_e32 v202, v12, v44
	v_fmac_f32_e32 v203, v13, v45
	v_fmac_f32_e32 v200, v14, v46
	v_fmac_f32_e32 v201, v15, v47
	v_fmac_f32_e32 v202, v16, v48
	v_fmac_f32_e32 v203, v17, v49
	v_fmac_f32_e32 v200, v18, v50
	v_fmac_f32_e32 v201, v19, v51
	v_fmac_f32_e32 v202, v20, v52
	v_fmac_f32_e32 v203, v21, v53
	v_fmac_f32_e32 v200, v22, v54
	v_fmac_f32_e32 v201, v23, v55
	v_fmac_f32_e32 v202, v24, v56
	v_fmac_f32_e32 v203, v25, v57
	v_fmac_f32_e32 v200, v26, v58
	v_fmac_f32_e32 v201, v27, v59
	v_fmac_f32_e32 v202, v28, v60
	v_fmac_f32_e32 v203, v29, v61
	v_fmac_f32_e32 v200, v30, v62
	v_fmac_f32_e32 v201, v31, v63
	v_fmac_f32_e32 v202, v32, v64
	v_fmac_f32_e32 v203, v33, v65
	v_add_f32_e32 v200, v201, v200
	v_add_f32_e32 v202, v203, v202
	v_cvt_scalef32_pk32_f32_fp6 v[2:33], v[176:181], 1.0
	v_add_f32_e32 v200, v202, v200
	s_add_i32 s38, s24, 6
	v_readlane_b32 s26, v199, s38
	s_add_i32 s39, s23, 6
	v_readlane_b32 s25, v198, s39
	v_add_f32_dpp v200, v200, v200 quad_perm:[1,0,3,2] row_mask:0xf bank_mask:0xf bound_ctrl:1
	s_nop 1
	v_add_f32_dpp v200, v200, v200 quad_perm:[2,3,0,1] row_mask:0xf bank_mask:0xf bound_ctrl:1
	s_nop 1
	v_add_f32_dpp v200, v200, v200 row_half_mirror row_mask:0xf bank_mask:0xf bound_ctrl:1
	s_nop 1
	v_add_f32_dpp v200, v200, v200 row_mirror row_mask:0xf bank_mask:0xf bound_ctrl:1
	s_nop 1
	v_add_f32_dpp v200, v200, v200 row_bcast:15 row_mask:0xa bank_mask:0xf
	s_nop 1
	v_add_f32_dpp v200, v200, v200 row_bcast:31 row_mask:0xc bank_mask:0xf
	s_nop 0
	v_readlane_b32 s27, v200, 63
	s_mul_i32 s40, s25, 0xc00
	s_add_u32 s28, s62, s40
	s_addc_u32 s29, s63, 0
	global_load_dwordx4 v[170:173], v1, s[28:29]
	global_load_dwordx4 v[174:177], v1, s[28:29] offset:2048
	global_load_dwordx4 v[178:181], v1, s[28:29] offset:1024
	v_mul_f32_e32 v204, s27, v212
	v_mul_f32_e32 v205, 0x3f3504f3, v204
	v_cmp_lt_f32_e64 s[32:33], |v205|, 1.0
	s_and_b64 vcc, exec, s[32:33]
	s_cbranch_vccnz .Lsm_29
	v_fma_f32 v208, |v205|, s9, v214
	v_fma_f32 v208, |v205|, v208, s10
	v_fma_f32 v208, |v205|, v208, s11
	v_fma_f32 v208, |v205|, v208, s12
	v_fma_f32 v208, |v205|, v208, s13
	v_fma_f32 v208, |v205|, v208, s14
	v_fma_f32 v208, |v205|, v208, |v205|
	v_mul_f32_e32 v209, 0xbfb8aa3b, v208
	v_fma_f32 v210, v208, s15, -v209
	v_rndne_f32_e32 v211, v209
	v_fmac_f32_e32 v210, 0xb2a5705f, v208
	v_sub_f32_e32 v209, v209, v211
	v_add_f32_e32 v209, v209, v210
	v_cvt_i32_f32_e32 v210, v211
	v_exp_f32_e32 v209, v209
	v_cmp_nlt_f32_e32 vcc, s16, v208
	v_ldexp_f32 v209, v209, v210
	s_nop 0
	v_cndmask_b32_e32 v209, 0, v209, vcc
	v_cmp_ngt_f32_e32 vcc, s17, v208
	s_nop 1
	v_cndmask_b32_e32 v208, v215, v209, vcc
	v_sub_f32_e32 v210, 1.0, v208
	s_branch .Ljn_29

; DEV float gelu_exact(float v) { return 0.5f * v * (1.f + erff(v * 0.7071067811865476f)); }
; DEV void peer_gather_token(const Params& p, int tok) {
;     ...
;       const v6u dq = v6u{dn[s][0][0], dn[s][0][1], dn[s][1][0], dn[s][1][1], dn[s][2][0], dn[s][2][1]};
;       const v32f dv = __builtin_amdgcn_cvt_scalef32_pk32_f32_fp6(dq, 1.0f);
;       float d0 = 0.f, d1 = 0.f, d2 = 0.f, d3 = 0.f;
; #pragma unroll
;       for (int i = 0; i < 8; ++i) { d0 += dv[4 * i] * hx[4 * i]; d1 += dv[4 * i + 1] * hx[4 * i + 1]; d2 += dv[4 * i + 2] * hx[4 * i + 2]; d3 += dv[4 * i + 3] * hx[4 * i + 3]; }
;       const float d = wave_sum_fast((d0 + d1) + (d2 + d3)) * (1.f / DOWN_SCALE);
;       const float gk = __builtin_bit_cast(float, (k < 64) ? __builtin_amdgcn_readlane(g0, k) : __builtin_amdgcn_readlane(g1, k - 64));
;       const float act = gelu_exact(d) * gk * (1.f / UP_SCALE);
;       const v6u uq = v6u{up[s][0][0], up[s][0][1], up[s][1][0], up[s][1][1], up[s][2][0], up[s][2][1]};
;       const v32f uv = __builtin_amdgcn_cvt_scalef32_pk32_f32_fp6(uq, 1.0f);
; #pragma unroll
;       for (int i = 0; i < 32; ++i) acc[i] += act * uv[i];
.Ljn_29:
	v_bfi_b32 v209, s18, v210, v205
	v_mul_f32_e32 v208, 0.5, v204
	v_add_f32_e32 v209, 1.0, v209
	v_mul_f32_e32 v208, v208, v209
	v_mul_f32_e32 v208, s26, v208
	v_mul_f32_e32 v206, 0x3e800000, v208
	v_pk_fma_f32 v[66:67], v[2:3], v[206:207], v[66:67] op_sel_hi:[1,0,1]
	v_pk_fma_f32 v[68:69], v[4:5], v[206:207], v[68:69] op_sel_hi:[1,0,1]
	v_pk_fma_f32 v[70:71], v[6:7], v[206:207], v[70:71] op_sel_hi:[1,0,1]
	v_pk_fma_f32 v[72:73], v[8:9], v[206:207], v[72:73] op_sel_hi:[1,0,1]
	v_pk_fma_f32 v[74:75], v[10:11], v[206:207], v[74:75] op_sel_hi:[1,0,1]
	v_pk_fma_f32 v[76:77], v[12:13], v[206:207], v[76:77] op_sel_hi:[1,0,1]
	v_pk_fma_f32 v[78:79], v[14:15], v[206:207], v[78:79] op_sel_hi:[1,0,1]
	v_pk_fma_f32 v[80:81], v[16:17], v[206:207], v[80:81] op_sel_hi:[1,0,1]
	v_pk_fma_f32 v[82:83], v[18:19], v[206:207], v[82:83] op_sel_hi:[1,0,1]
	v_pk_fma_f32 v[84:85], v[20:21], v[206:207], v[84:85] op_sel_hi:[1,0,1]
	v_pk_fma_f32 v[86:87], v[22:23], v[206:207], v[86:87] op_sel_hi:[1,0,1]
	v_pk_fma_f32 v[88:89], v[24:25], v[206:207], v[88:89] op_sel_hi:[1,0,1]
	v_pk_fma_f32 v[90:91], v[26:27], v[206:207], v[90:91] op_sel_hi:[1,0,1]
	v_pk_fma_f32 v[92:93], v[28:29], v[206:207], v[92:93] op_sel_hi:[1,0,1]
	v_pk_fma_f32 v[94:95], v[30:31], v[206:207], v[94:95] op_sel_hi:[1,0,1]
	v_pk_fma_f32 v[96:97], v[32:33], v[206:207], v[96:97] op_sel_hi:[1,0,1]
	s_waitcnt vmcnt(33)
	v_cvt_scalef32_pk32_f32_fp6 v[2:33], v[182:187], 1.0
	v_mul_f32_e32 v200, v2, v34
	v_mul_f32_e32 v201, v3, v35
	v_mul_f32_e32 v202, v4, v36
	v_mul_f32_e32 v203, v5, v37
	v_fmac_f32_e32 v200, v6, v38
	v_fmac_f32_e32 v201, v7, v39
	v_fmac_f32_e32 v202, v8, v40
	v_fmac_f32_e32 v203, v9, v41
	v_fmac_f32_e32 v200, v10, v42
	v_fmac_f32_e32 v201, v11, v43
	v_fmac_f32_e32 v202, v12, v44
	v_fmac_f32_e32 v203, v13, v45
	v_fmac_f32_e32 v200, v14, v46
	v_fmac_f32_e32 v201, v15, v47
	v_fmac_f32_e32 v202, v16, v48
	v_fmac_f32_e32 v203, v17, v49
	v_fmac_f32_e32 v200, v18, v50
	v_fmac_f32_e32 v201, v19, v51
	v_fmac_f32_e32 v202, v20, v52
	v_fmac_f32_e32 v203, v21, v53
	v_fmac_f32_e32 v200, v22, v54
	v_fmac_f32_e32 v201, v23, v55
	v_fmac_f32_e32 v202, v24, v56
	v_fmac_f32_e32 v203, v25, v57
	v_fmac_f32_e32 v200, v26, v58
	v_fmac_f32_e32 v201, v27, v59
	v_fmac_f32_e32 v202, v28, v60
	v_fmac_f32_e32 v203, v29, v61
	v_fmac_f32_e32 v200, v30, v62
	v_fmac_f32_e32 v201, v31, v63
	v_fmac_f32_e32 v202, v32, v64
	v_fmac_f32_e32 v203, v33, v65
	v_add_f32_e32 v200, v201, v200
	v_add_f32_e32 v202, v203, v202
	v_cvt_scalef32_pk32_f32_fp6 v[2:33], v[188:193], 1.0
	v_add_f32_e32 v200, v202, v200
	s_add_i32 s38, s24, 7
	v_readlane_b32 s26, v199, s38
	s_add_i32 s39, s23, 7
	v_readlane_b32 s25, v198, s39
	v_add_f32_dpp v200, v200, v200 quad_perm:[1,0,3,2] row_mask:0xf bank_mask:0xf bound_ctrl:1
	s_nop 1
	v_add_f32_dpp v200, v200, v200 quad_perm:[2,3,0,1] row_mask:0xf bank_mask:0xf bound_ctrl:1
	s_nop 1
	v_add_f32_dpp v200, v200, v200 row_half_mirror row_mask:0xf bank_mask:0xf bound_ctrl:1
	s_nop 1
	v_add_f32_dpp v200, v200, v200 row_mirror row_mask:0xf bank_mask:0xf bound_ctrl:1
	s_nop 1
	v_add_f32_dpp v200, v200, v200 row_bcast:15 row_mask:0xa bank_mask:0xf
	s_nop 1
	v_add_f32_dpp v200, v200, v200 row_bcast:31 row_mask:0xc bank_mask:0xf
	s_nop 0
	v_readlane_b32 s27, v200, 63
	s_mul_i32 s40, s25, 0xc00
	s_add_u32 s28, s62, s40
	s_addc_u32 s29, s63, 0
	global_load_dwordx4 v[182:185], v1, s[28:29]
	global_load_dwordx4 v[186:189], v1, s[28:29] offset:2048
	global_load_dwordx4 v[190:193], v1, s[28:29] offset:1024
	v_mul_f32_e32 v204, s27, v212
	v_mul_f32_e32 v205, 0x3f3504f3, v204
	v_cmp_lt_f32_e64 s[32:33], |v205|, 1.0
	s_and_b64 vcc, exec, s[32:33]
	s_cbranch_vccnz .Lsm_31
	v_fma_f32 v208, |v205|, s9, v214
	v_fma_f32 v208, |v205|, v208, s10
	v_fma_f32 v208, |v205|, v208, s11
	v_fma_f32 v208, |v205|, v208, s12
	v_fma_f32 v208, |v205|, v208, s13
	v_fma_f32 v208, |v205|, v208, s14
	v_fma_f32 v208, |v205|, v208, |v205|
	v_mul_f32_e32 v209, 0xbfb8aa3b, v208
	v_fma_f32 v210, v208, s15, -v209
	v_rndne_f32_e32 v211, v209
	v_fmac_f32_e32 v210, 0xb2a5705f, v208
	v_sub_f32_e32 v209, v209, v211
	v_add_f32_e32 v209, v209, v210
	v_cvt_i32_f32_e32 v210, v211
	v_exp_f32_e32 v209, v209
	v_cmp_nlt_f32_e32 vcc, s16, v208
	v_ldexp_f32 v209, v209, v210
	s_nop 0
	v_cndmask_b32_e32 v209, 0, v209, vcc
	v_cmp_ngt_f32_e32 vcc, s17, v208
	s_nop 1
	v_cndmask_b32_e32 v208, v215, v209, vcc
	v_sub_f32_e32 v210, 1.0, v208
	s_branch .Ljn_31
